# main-loop fragment wait as a four-rung counted ladder (waits before MFMA 0, 4, 8, 12 of each cluster)
# speedup vs baseline: 1.0077x; 1.0000x over previous
.LBB0_403:
	s_add_u32 s14, s4, 0x100
	s_addc_u32 s15, s5, 0
	s_add_i32 s38, 0, 0x10000
	v_add_u32_e32 v12, s38, v193
	ds_read_b128 v[0:3], v12
	ds_read_b128 v[8:11], v12 offset:2048
	ds_read_b128 v[4:7], v12 offset:1024
	ds_read_b128 v[12:15], v12 offset:3072
	s_cmp_eq_u32 s37, 12
	s_cselect_b32 s19, s9, s15
	s_cselect_b32 s18, s8, s14
	s_cselect_b32 s17, s11, s36
	s_cselect_b32 s16, s10, s7
	v_lshl_add_u64 v[190:191], s[4:5], 0, v[186:187]
	s_add_i32 m0, s23, 0xc000
	ds_read_b128 v[16:19], v206
	ds_read_b128 v[24:27], v206 offset:2048
	ds_read_b128 v[162:165], v206 offset:4096
	ds_read_b128 v[170:173], v206 offset:6144
	ds_read_b128 v[20:23], v206 offset:1024
	ds_read_b128 v[28:31], v206 offset:3072
	ds_read_b128 v[166:169], v206 offset:5120
	ds_read_b128 v[174:177], v206 offset:7168
	global_load_lds_dwordx4 v[190:191], off
	v_lshl_add_u64 v[190:191], s[4:5], 0, v[188:189]
	s_add_i32 m0, s23, 0xe000
	s_nop 0
	global_load_lds_dwordx4 v[190:191], off
	s_waitcnt lgkmcnt(8)
	s_barrier
	s_waitcnt lgkmcnt(6)
	s_setprio 1
	v_mfma_f32_16x16x32_f16 v[158:161], v[0:3], v[16:19], v[158:161]
	v_mfma_f32_16x16x32_f16 v[142:145], v[8:11], v[16:19], v[142:145]
	v_mfma_f32_16x16x32_f16 v[150:153], v[0:3], v[24:27], v[150:153]
	v_mfma_f32_16x16x32_f16 v[134:137], v[8:11], v[24:27], v[134:137]
	s_waitcnt lgkmcnt(4)
	v_mfma_f32_16x16x32_f16 v[154:157], v[0:3], v[162:165], v[154:157]
	v_mfma_f32_16x16x32_f16 v[138:141], v[8:11], v[162:165], v[138:141]
	v_mfma_f32_16x16x32_f16 v[146:149], v[0:3], v[170:173], v[146:149]
	v_mfma_f32_16x16x32_f16 v[130:133], v[8:11], v[170:173], v[130:133]
	s_waitcnt lgkmcnt(2)
	v_mfma_f32_16x16x32_f16 v[158:161], v[4:7], v[20:23], v[158:161]
	v_mfma_f32_16x16x32_f16 v[142:145], v[12:15], v[20:23], v[142:145]
	v_mfma_f32_16x16x32_f16 v[150:153], v[4:7], v[28:31], v[150:153]
	v_mfma_f32_16x16x32_f16 v[134:137], v[12:15], v[28:31], v[134:137]
	s_waitcnt lgkmcnt(0)
	v_mfma_f32_16x16x32_f16 v[154:157], v[4:7], v[166:169], v[154:157]
	v_mfma_f32_16x16x32_f16 v[138:141], v[12:15], v[166:169], v[138:141]
	v_mfma_f32_16x16x32_f16 v[146:149], v[4:7], v[174:177], v[146:149]
	v_mfma_f32_16x16x32_f16 v[130:133], v[12:15], v[174:177], v[130:133]
	s_setprio 0
	s_barrier
	s_add_i32 s39, 0, 0x14000
	s_add_i32 s4, s38, s22
	v_add_u32_e32 v32, s39, v193
	v_lshl_add_u64 v[190:191], s[16:17], 0, v[178:179]
	s_mov_b32 m0, s4
	ds_read_b128 v[208:211], v32
	ds_read_b128 v[216:219], v32 offset:2048
	ds_read_b128 v[212:215], v32 offset:1024
	ds_read_b128 v[230:233], v32 offset:3072
	global_load_lds_dwordx4 v[190:191], off
	v_lshl_add_u64 v[238:239], s[16:17], 0, v[180:181]
	s_add_i32 m0, s4, 0x2000
	s_nop 0
	global_load_lds_dwordx4 v[238:239], off
	s_barrier
	s_waitcnt lgkmcnt(0)
	s_setprio 1
	s_waitcnt lgkmcnt(0)
	v_mfma_f32_16x16x32_f16 v[94:97], v[208:211], v[16:19], v[94:97]
	v_mfma_f32_16x16x32_f16 v[16:19], v[216:219], v[16:19], v[78:81]
	v_mfma_f32_16x16x32_f16 v[94:97], v[212:215], v[20:23], v[94:97]
	v_mfma_f32_16x16x32_f16 v[16:19], v[230:233], v[20:23], v[16:19]
	v_mfma_f32_16x16x32_f16 v[20:23], v[208:211], v[24:27], v[86:89]
	v_mfma_f32_16x16x32_f16 v[24:27], v[216:219], v[24:27], v[70:73]
	v_mfma_f32_16x16x32_f16 v[70:73], v[216:219], v[162:165], v[74:77]
	v_mfma_f32_16x16x32_f16 v[74:77], v[230:233], v[166:169], v[70:73]
	v_mfma_f32_16x16x32_f16 v[70:73], v[208:211], v[170:173], v[82:85]
	v_mfma_f32_16x16x32_f16 v[66:69], v[216:219], v[170:173], v[66:69]
	v_mfma_f32_16x16x32_f16 v[20:23], v[212:215], v[28:31], v[20:23]
	v_mfma_f32_16x16x32_f16 v[24:27], v[230:233], v[28:31], v[24:27]
	v_mfma_f32_16x16x32_f16 v[28:31], v[208:211], v[162:165], v[90:93]
	v_mfma_f32_16x16x32_f16 v[82:85], v[212:215], v[174:177], v[70:73]
	v_mfma_f32_16x16x32_f16 v[66:69], v[230:233], v[174:177], v[66:69]
	v_mfma_f32_16x16x32_f16 v[28:31], v[212:215], v[166:169], v[28:31]
	s_setprio 0
	s_mov_b32 m0, s23
	v_lshl_add_u64 v[240:241], s[18:19], 0, v[178:179]
	s_barrier
	ds_read_b128 v[70:73], v206 offset:16384
	ds_read_b128 v[86:89], v206 offset:18432
	ds_read_b128 v[162:165], v206 offset:20480
	ds_read_b128 v[170:173], v206 offset:22528
	ds_read_b128 v[78:81], v206 offset:17408
	ds_read_b128 v[90:93], v206 offset:19456
	ds_read_b128 v[166:169], v206 offset:21504
	ds_read_b128 v[174:177], v206 offset:23552
	global_load_lds_dwordx4 v[240:241], off
	v_lshl_add_u64 v[242:243], s[18:19], 0, v[180:181]
	s_mov_b32 m0, s24
	s_nop 0
	global_load_lds_dwordx4 v[242:243], off
	s_barrier
	s_waitcnt lgkmcnt(6)
	s_setprio 1
	v_mfma_f32_16x16x32_f16 v[126:129], v[0:3], v[70:73], v[126:129]
	v_mfma_f32_16x16x32_f16 v[110:113], v[8:11], v[70:73], v[110:113]
	v_mfma_f32_16x16x32_f16 v[118:121], v[0:3], v[86:89], v[118:121]
	v_mfma_f32_16x16x32_f16 v[102:105], v[8:11], v[86:89], v[102:105]
	s_waitcnt lgkmcnt(3)
	v_mfma_f32_16x16x32_f16 v[122:125], v[0:3], v[162:165], v[122:125]
	v_mfma_f32_16x16x32_f16 v[106:109], v[8:11], v[162:165], v[106:109]
	v_mfma_f32_16x16x32_f16 v[0:3], v[0:3], v[170:173], v[114:117]
	v_mfma_f32_16x16x32_f16 v[126:129], v[4:7], v[78:81], v[126:129]
	s_waitcnt lgkmcnt(1)
	v_mfma_f32_16x16x32_f16 v[110:113], v[12:15], v[78:81], v[110:113]
	v_mfma_f32_16x16x32_f16 v[118:121], v[4:7], v[90:93], v[118:121]
	v_mfma_f32_16x16x32_f16 v[102:105], v[12:15], v[90:93], v[102:105]
	v_mfma_f32_16x16x32_f16 v[122:125], v[4:7], v[166:169], v[122:125]
	s_waitcnt lgkmcnt(0)
	v_mfma_f32_16x16x32_f16 v[106:109], v[12:15], v[166:169], v[106:109]
	v_mfma_f32_16x16x32_f16 v[0:3], v[4:7], v[174:177], v[0:3]
	v_mfma_f32_16x16x32_f16 v[4:7], v[8:11], v[170:173], v[98:101]
	v_mfma_f32_16x16x32_f16 v[4:7], v[12:15], v[174:177], v[4:7]
	s_setprio 0
	s_barrier
	s_add_u32 s4, s16, 0x40000
	s_addc_u32 s5, s17, 0
	s_add_i32 s38, s39, s22
	v_lshl_add_u64 v[8:9], s[4:5], 0, v[178:179]
	s_mov_b32 m0, s38
	s_nop 0
	global_load_lds_dwordx4 v[8:9], off
	v_lshl_add_u64 v[8:9], s[4:5], 0, v[180:181]
	s_add_i32 m0, s38, 0x2000
	s_nop 0
	global_load_lds_dwordx4 v[8:9], off
	s_waitcnt vmcnt(6)
	s_barrier
	s_setprio 1
	v_mfma_f32_16x16x32_f16 v[12:15], v[216:219], v[70:73], v[46:49]
	v_mfma_f32_16x16x32_f16 v[46:49], v[208:211], v[86:89], v[54:57]
	v_mfma_f32_16x16x32_f16 v[54:57], v[212:215], v[90:93], v[46:49]
	v_mfma_f32_16x16x32_f16 v[46:49], v[208:211], v[162:165], v[58:61]
	v_mfma_f32_16x16x32_f16 v[38:41], v[216:219], v[86:89], v[38:41]
	v_mfma_f32_16x16x32_f16 v[58:61], v[212:215], v[166:169], v[46:49]
	v_mfma_f32_16x16x32_f16 v[42:45], v[216:219], v[162:165], v[42:45]
	v_mfma_f32_16x16x32_f16 v[46:49], v[208:211], v[170:173], v[50:53]
	v_mfma_f32_16x16x32_f16 v[34:37], v[216:219], v[170:173], v[34:37]
	v_mfma_f32_16x16x32_f16 v[8:11], v[208:211], v[70:73], v[62:65]
	v_mfma_f32_16x16x32_f16 v[38:41], v[230:233], v[90:93], v[38:41]
	v_mfma_f32_16x16x32_f16 v[42:45], v[230:233], v[166:169], v[42:45]
	v_mfma_f32_16x16x32_f16 v[50:53], v[212:215], v[174:177], v[46:49]
	v_mfma_f32_16x16x32_f16 v[34:37], v[230:233], v[174:177], v[34:37]
	v_mfma_f32_16x16x32_f16 v[8:11], v[212:215], v[78:81], v[8:11]
	v_mfma_f32_16x16x32_f16 v[12:15], v[230:233], v[78:81], v[12:15]
	s_setprio 0
	s_add_i32 s38, 0, 0x18000
	v_add_u32_e32 v32, s38, v193
	s_barrier
	ds_read_b128 v[46:49], v32
	ds_read_b128 v[62:65], v32 offset:1024
	ds_read_b128 v[98:101], v32 offset:2048
	ds_read_b128 v[162:165], v32 offset:3072
	s_add_u32 s4, s18, 0x40000
	s_addc_u32 s5, s19, 0
	s_mov_b32 m0, s25
	v_lshl_add_u64 v[86:87], s[4:5], 0, v[178:179]
	ds_read_b128 v[70:73], v206 offset:32768
	ds_read_b128 v[78:81], v206 offset:33792
	ds_read_b128 v[90:93], v206 offset:34816
	ds_read_b128 v[114:117], v206 offset:35840
	ds_read_b128 v[166:169], v206 offset:36864
	ds_read_b128 v[170:173], v206 offset:37888
	ds_read_b128 v[174:177], v206 offset:38912
	ds_read_b128 v[208:211], v206 offset:39936
	global_load_lds_dwordx4 v[86:87], off
	v_lshl_add_u64 v[86:87], s[4:5], 0, v[180:181]
	s_mov_b32 m0, s26
	s_nop 0
	global_load_lds_dwordx4 v[86:87], off
	s_waitcnt lgkmcnt(8)
	s_barrier
	s_waitcnt lgkmcnt(6)
	s_setprio 1
	v_mfma_f32_16x16x32_f16 v[86:89], v[46:49], v[70:73], v[158:161]
	v_mfma_f32_16x16x32_f16 v[158:161], v[62:65], v[78:81], v[86:89]
	v_mfma_f32_16x16x32_f16 v[86:89], v[98:101], v[70:73], v[142:145]
	v_mfma_f32_16x16x32_f16 v[142:145], v[162:165], v[78:81], v[86:89]
	s_waitcnt lgkmcnt(4)
	v_mfma_f32_16x16x32_f16 v[86:89], v[46:49], v[90:93], v[150:153]
	v_mfma_f32_16x16x32_f16 v[150:153], v[62:65], v[114:117], v[86:89]
	v_mfma_f32_16x16x32_f16 v[86:89], v[98:101], v[90:93], v[134:137]
	v_mfma_f32_16x16x32_f16 v[134:137], v[162:165], v[114:117], v[86:89]
	s_waitcnt lgkmcnt(2)
	v_mfma_f32_16x16x32_f16 v[86:89], v[46:49], v[166:169], v[154:157]
	v_mfma_f32_16x16x32_f16 v[154:157], v[62:65], v[170:173], v[86:89]
	v_mfma_f32_16x16x32_f16 v[86:89], v[98:101], v[166:169], v[138:141]
	v_mfma_f32_16x16x32_f16 v[138:141], v[162:165], v[170:173], v[86:89]
	s_waitcnt lgkmcnt(0)
	v_mfma_f32_16x16x32_f16 v[86:89], v[46:49], v[174:177], v[146:149]
	v_mfma_f32_16x16x32_f16 v[146:149], v[62:65], v[208:211], v[86:89]
	v_mfma_f32_16x16x32_f16 v[86:89], v[98:101], v[174:177], v[130:133]
	v_mfma_f32_16x16x32_f16 v[130:133], v[162:165], v[208:211], v[86:89]
	s_setprio 0
	s_barrier
	s_add_i32 s18, 0, 0x1c000
	s_add_i32 s4, s38, s22
	v_add_u32_e32 v32, s18, v193
	s_nop 1
	v_lshl_add_u64 v[86:87], v[190:191], 0, s[84:85]
	s_mov_b32 m0, s4
	ds_read_b128 v[212:215], v32
	ds_read_b128 v[230:233], v32 offset:2048
	ds_read_b128 v[216:219], v32 offset:1024
	ds_read_b128 v[234:237], v32 offset:3072
	global_load_lds_dwordx4 v[86:87], off
	v_lshl_add_u64 v[86:87], v[238:239], 0, s[84:85]
	s_add_i32 m0, s4, 0x2000
	s_nop 0
	global_load_lds_dwordx4 v[86:87], off
	s_barrier
	s_waitcnt lgkmcnt(0)
	s_setprio 1
	s_waitcnt lgkmcnt(0)
	v_mfma_f32_16x16x32_f16 v[86:89], v[212:215], v[70:73], v[94:97]
	v_mfma_f32_16x16x32_f16 v[16:19], v[230:233], v[70:73], v[16:19]
	v_mfma_f32_16x16x32_f16 v[94:97], v[216:219], v[78:81], v[86:89]
	v_mfma_f32_16x16x32_f16 v[78:81], v[234:237], v[78:81], v[16:19]
	v_mfma_f32_16x16x32_f16 v[16:19], v[212:215], v[90:93], v[20:23]
	v_mfma_f32_16x16x32_f16 v[86:89], v[216:219], v[114:117], v[16:19]
	v_mfma_f32_16x16x32_f16 v[16:19], v[230:233], v[90:93], v[24:27]
	v_mfma_f32_16x16x32_f16 v[70:73], v[234:237], v[114:117], v[16:19]
	v_mfma_f32_16x16x32_f16 v[16:19], v[212:215], v[166:169], v[28:31]
	v_mfma_f32_16x16x32_f16 v[90:93], v[216:219], v[170:173], v[16:19]
	v_mfma_f32_16x16x32_f16 v[16:19], v[230:233], v[166:169], v[74:77]
	v_mfma_f32_16x16x32_f16 v[74:77], v[234:237], v[170:173], v[16:19]
	v_mfma_f32_16x16x32_f16 v[16:19], v[212:215], v[174:177], v[82:85]
	v_mfma_f32_16x16x32_f16 v[82:85], v[216:219], v[208:211], v[16:19]
	v_mfma_f32_16x16x32_f16 v[16:19], v[230:233], v[174:177], v[66:69]
	v_mfma_f32_16x16x32_f16 v[66:69], v[234:237], v[208:211], v[16:19]
	s_setprio 0
	s_mov_b32 m0, s28
	v_lshl_add_u64 v[114:115], v[240:241], 0, s[84:85]
	s_barrier
	s_nop 2
	ds_read_b128 v[16:19], v206 offset:49152
	ds_read_b128 v[20:23], v206 offset:50176
	ds_read_b128 v[24:27], v206 offset:51200
	ds_read_b128 v[28:31], v206 offset:52224
	ds_read_b128 v[166:169], v206 offset:53248
	ds_read_b128 v[174:177], v206 offset:55296
	ds_read_b128 v[170:173], v206 offset:54272
	ds_read_b128 v[208:211], v206 offset:56320
	global_load_lds_dwordx4 v[114:115], off
	v_lshl_add_u64 v[114:115], v[242:243], 0, s[84:85]
	s_mov_b32 m0, s29
	s_nop 0
	global_load_lds_dwordx4 v[114:115], off
	s_barrier
	s_waitcnt lgkmcnt(4)
	s_setprio 1
	v_mfma_f32_16x16x32_f16 v[114:117], v[46:49], v[16:19], v[126:129]
	v_mfma_f32_16x16x32_f16 v[126:129], v[62:65], v[20:23], v[114:117]
	v_mfma_f32_16x16x32_f16 v[114:117], v[46:49], v[24:27], v[118:121]
	v_mfma_f32_16x16x32_f16 v[118:121], v[62:65], v[28:31], v[114:117]
	s_waitcnt lgkmcnt(2)
	v_mfma_f32_16x16x32_f16 v[114:117], v[46:49], v[166:169], v[122:125]
	v_mfma_f32_16x16x32_f16 v[0:3], v[46:49], v[174:177], v[0:3]
	v_mfma_f32_16x16x32_f16 v[110:113], v[98:101], v[16:19], v[110:113]
	v_mfma_f32_16x16x32_f16 v[102:105], v[98:101], v[24:27], v[102:105]
	s_waitcnt lgkmcnt(0)
	v_mfma_f32_16x16x32_f16 v[122:125], v[62:65], v[170:173], v[114:117]
	v_mfma_f32_16x16x32_f16 v[106:109], v[98:101], v[166:169], v[106:109]
	v_mfma_f32_16x16x32_f16 v[114:117], v[62:65], v[208:211], v[0:3]
	v_mfma_f32_16x16x32_f16 v[0:3], v[98:101], v[174:177], v[4:7]
	v_mfma_f32_16x16x32_f16 v[110:113], v[162:165], v[20:23], v[110:113]
	v_mfma_f32_16x16x32_f16 v[102:105], v[162:165], v[28:31], v[102:105]
	v_mfma_f32_16x16x32_f16 v[106:109], v[162:165], v[170:173], v[106:109]
	v_mfma_f32_16x16x32_f16 v[98:101], v[162:165], v[208:211], v[0:3]
	s_setprio 0
	s_barrier
	s_add_u32 s4, s16, 0x40080
	s_addc_u32 s5, s17, 0
	s_add_i32 s16, s18, s22
	v_lshl_add_u64 v[0:1], s[4:5], 0, v[178:179]
	s_mov_b32 m0, s16
	s_nop 0
	global_load_lds_dwordx4 v[0:1], off
	v_lshl_add_u64 v[0:1], s[4:5], 0, v[180:181]
	s_add_i32 m0, s16, 0x2000
	s_nop 0
	global_load_lds_dwordx4 v[0:1], off
	s_waitcnt vmcnt(6)
	s_barrier
	s_setprio 1
	v_mfma_f32_16x16x32_f16 v[0:3], v[212:215], v[16:19], v[8:11]
	v_mfma_f32_16x16x32_f16 v[62:65], v[216:219], v[20:23], v[0:3]
	v_mfma_f32_16x16x32_f16 v[0:3], v[230:233], v[16:19], v[12:15]
	v_mfma_f32_16x16x32_f16 v[46:49], v[234:237], v[20:23], v[0:3]
	v_mfma_f32_16x16x32_f16 v[0:3], v[212:215], v[24:27], v[54:57]
	v_mfma_f32_16x16x32_f16 v[54:57], v[216:219], v[28:31], v[0:3]
	v_mfma_f32_16x16x32_f16 v[0:3], v[230:233], v[24:27], v[38:41]
	v_mfma_f32_16x16x32_f16 v[38:41], v[234:237], v[28:31], v[0:3]
	v_mfma_f32_16x16x32_f16 v[0:3], v[212:215], v[166:169], v[58:61]
	v_mfma_f32_16x16x32_f16 v[58:61], v[216:219], v[170:173], v[0:3]
	v_mfma_f32_16x16x32_f16 v[0:3], v[230:233], v[166:169], v[42:45]
	v_mfma_f32_16x16x32_f16 v[42:45], v[234:237], v[170:173], v[0:3]
	v_mfma_f32_16x16x32_f16 v[0:3], v[212:215], v[174:177], v[50:53]
	v_mfma_f32_16x16x32_f16 v[50:53], v[216:219], v[208:211], v[0:3]
	v_mfma_f32_16x16x32_f16 v[0:3], v[230:233], v[174:177], v[34:37]
	v_mfma_f32_16x16x32_f16 v[34:37], v[234:237], v[208:211], v[0:3]
	s_setprio 0
	s_add_i32 s37, s37, 2
	s_add_u32 s7, s7, 0x100
	s_addc_u32 s36, s36, 0
	s_cmp_gt_u32 s37, 13
	s_mov_b64 s[4:5], s[14:15]
	s_barrier
	s_cbranch_scc0 .LBB0_403
	s_lshl_b32 s7, s34, 8
	s_cmp_lt_i32 s35, 28
	s_mov_b64 s[4:5], -1
	s_cbranch_scc0 .LBB0_431
	s_add_i32 s16, s7, s27
	v_or_b32_e32 v207, s16, v192
	s_cmp_gt_i32 s35, 3
	s_cbranch_scc0 .LBB0_411
	s_add_i32 s4, s35, -12
	s_cmp_gt_u32 s4, 7
	s_mov_b64 s[4:5], -1
	s_cbranch_scc0 .LBB0_408
	s_lshl_b32 s4, s35, 8
	s_add_i32 s5, s4, 0xfffffc00
	s_cmp_lt_u32 s35, 12
	s_cselect_b32 s4, s4, s5
	v_and_b32_e32 v10, 7, v220
	v_and_b32_e32 v11, 8, v220
	v_cmp_ne_u32_e32 vcc, 0, v11
	v_and_b32_e32 v12, 0x60, v194
	v_lshlrev_b32_e32 v12, 1, v12
	v_lshl_or_b32 v12, v11, 2, v12
	v_and_b32_e32 v13, 0x18, v194
	v_or_b32_e32 v12, v12, v13
	v_or_b32_e32 v32, s4, v12
	v_or_b32_e32 v14, s16, v10
	v_mov_b64_e32 v[4:5], s[70:71]
	v_mad_i64_i32 v[0:1], s[4:5], v14, s33, v[4:5]
	v_lshlrev_b64 v[6:7], 1, v[32:33]
	v_lshl_add_u64 v[16:17], v[0:1], 0, v[6:7]
	v_mov_b32_e32 v32, 0x30000
	v_lshl_add_u64 v[18:19], v[16:17], 0, v[32:33]
	v_lshl_add_u64 v[20:21], v[18:19], 0, v[32:33]
	v_lshl_add_u64 v[22:23], v[20:21], 0, v[32:33]
	v_mov_b32_e32 v8, 0x180000
	v_mov_b32_e32 v9, 0
	v_lshl_add_u64 v[24:25], v[16:17], 0, v[8:9]
	v_lshl_add_u64 v[26:27], v[24:25], 0, v[32:33]
	v_lshl_add_u64 v[28:29], v[26:27], 0, v[32:33]
	v_lshl_add_u64 v[30:31], v[28:29], 0, v[32:33]
	v_mov_b32_e32 v8, 0x18000
	v_cvt_pk_f16_f32 v158, v158, v159
	v_cvt_pk_f16_f32 v159, v160, v161
	v_cvt_pk_f16_f32 v160, v142, v143
	v_cvt_pk_f16_f32 v161, v144, v145
	v_cvt_pk_f16_f32 v94, v94, v95
	v_cvt_pk_f16_f32 v95, v96, v97
	v_cvt_pk_f16_f32 v96, v78, v79
	v_cvt_pk_f16_f32 v97, v80, v81
	v_mov_b32_dpp v0, v158 row_ror:8 row_mask:0xf bank_mask:0xf
	v_mov_b32_dpp v1, v159 row_ror:8 row_mask:0xf bank_mask:0xf
	v_mov_b32_dpp v2, v160 row_ror:8 row_mask:0xf bank_mask:0xf
	v_mov_b32_dpp v3, v161 row_ror:8 row_mask:0xf bank_mask:0xf
	v_mov_b32_dpp v4, v94 row_ror:8 row_mask:0xf bank_mask:0xf
	v_mov_b32_dpp v5, v95 row_ror:8 row_mask:0xf bank_mask:0xf
	v_mov_b32_dpp v6, v96 row_ror:8 row_mask:0xf bank_mask:0xf
	v_mov_b32_dpp v7, v97 row_ror:8 row_mask:0xf bank_mask:0xf
	v_cndmask_b32_e32 v158, v158, v4, vcc
	v_cndmask_b32_e32 v159, v159, v5, vcc
	v_cndmask_b32_e32 v160, v160, v6, vcc
	v_cndmask_b32_e32 v161, v161, v7, vcc
	v_cndmask_b32_e32 v94, v0, v94, vcc
	v_cndmask_b32_e32 v95, v1, v95, vcc
	v_cndmask_b32_e32 v96, v2, v96, vcc
	v_cndmask_b32_e32 v97, v3, v97, vcc
	v_lshl_add_u64 v[10:11], v[16:17], 0, v[8:9]
	global_store_dwordx4 v[16:17], v[158:161], off
	global_store_dwordx4 v[10:11], v[94:97], off
	v_cvt_pk_f16_f32 v150, v150, v151
	v_cvt_pk_f16_f32 v151, v152, v153
	v_cvt_pk_f16_f32 v152, v134, v135
	v_cvt_pk_f16_f32 v153, v136, v137
	v_cvt_pk_f16_f32 v86, v86, v87
	v_cvt_pk_f16_f32 v87, v88, v89
	v_cvt_pk_f16_f32 v88, v70, v71
	v_cvt_pk_f16_f32 v89, v72, v73
	v_mov_b32_dpp v0, v150 row_ror:8 row_mask:0xf bank_mask:0xf
	v_mov_b32_dpp v1, v151 row_ror:8 row_mask:0xf bank_mask:0xf
	v_mov_b32_dpp v2, v152 row_ror:8 row_mask:0xf bank_mask:0xf
	v_mov_b32_dpp v3, v153 row_ror:8 row_mask:0xf bank_mask:0xf
	v_mov_b32_dpp v4, v86 row_ror:8 row_mask:0xf bank_mask:0xf
	v_mov_b32_dpp v5, v87 row_ror:8 row_mask:0xf bank_mask:0xf
	v_mov_b32_dpp v6, v88 row_ror:8 row_mask:0xf bank_mask:0xf
	v_mov_b32_dpp v7, v89 row_ror:8 row_mask:0xf bank_mask:0xf
	v_cndmask_b32_e32 v150, v150, v4, vcc
	v_cndmask_b32_e32 v151, v151, v5, vcc
	v_cndmask_b32_e32 v152, v152, v6, vcc
	v_cndmask_b32_e32 v153, v153, v7, vcc
	v_cndmask_b32_e32 v86, v0, v86, vcc
	v_cndmask_b32_e32 v87, v1, v87, vcc
	v_cndmask_b32_e32 v88, v2, v88, vcc
	v_cndmask_b32_e32 v89, v3, v89, vcc
	v_lshl_add_u64 v[10:11], v[18:19], 0, v[8:9]
	global_store_dwordx4 v[18:19], v[150:153], off
	global_store_dwordx4 v[10:11], v[86:89], off
	v_cvt_pk_f16_f32 v154, v154, v155
	v_cvt_pk_f16_f32 v155, v156, v157
	v_cvt_pk_f16_f32 v156, v138, v139
	v_cvt_pk_f16_f32 v157, v140, v141
	v_cvt_pk_f16_f32 v90, v90, v91
	v_cvt_pk_f16_f32 v91, v92, v93
	v_cvt_pk_f16_f32 v92, v74, v75
	v_cvt_pk_f16_f32 v93, v76, v77
	v_mov_b32_dpp v0, v154 row_ror:8 row_mask:0xf bank_mask:0xf
	v_mov_b32_dpp v1, v155 row_ror:8 row_mask:0xf bank_mask:0xf
	v_mov_b32_dpp v2, v156 row_ror:8 row_mask:0xf bank_mask:0xf
	v_mov_b32_dpp v3, v157 row_ror:8 row_mask:0xf bank_mask:0xf
	v_mov_b32_dpp v4, v90 row_ror:8 row_mask:0xf bank_mask:0xf
	v_mov_b32_dpp v5, v91 row_ror:8 row_mask:0xf bank_mask:0xf
	v_mov_b32_dpp v6, v92 row_ror:8 row_mask:0xf bank_mask:0xf
	v_mov_b32_dpp v7, v93 row_ror:8 row_mask:0xf bank_mask:0xf
	v_cndmask_b32_e32 v154, v154, v4, vcc
	v_cndmask_b32_e32 v155, v155, v5, vcc
	v_cndmask_b32_e32 v156, v156, v6, vcc
	v_cndmask_b32_e32 v157, v157, v7, vcc
	v_cndmask_b32_e32 v90, v0, v90, vcc
	v_cndmask_b32_e32 v91, v1, v91, vcc
	v_cndmask_b32_e32 v92, v2, v92, vcc
	v_cndmask_b32_e32 v93, v3, v93, vcc
	v_lshl_add_u64 v[10:11], v[20:21], 0, v[8:9]
	global_store_dwordx4 v[20:21], v[154:157], off
	global_store_dwordx4 v[10:11], v[90:93], off
	v_cvt_pk_f16_f32 v146, v146, v147
	v_cvt_pk_f16_f32 v147, v148, v149
	v_cvt_pk_f16_f32 v148, v130, v131
	v_cvt_pk_f16_f32 v149, v132, v133
	v_cvt_pk_f16_f32 v82, v82, v83
	v_cvt_pk_f16_f32 v83, v84, v85
	v_cvt_pk_f16_f32 v84, v66, v67
	v_cvt_pk_f16_f32 v85, v68, v69
	v_mov_b32_dpp v0, v146 row_ror:8 row_mask:0xf bank_mask:0xf
	v_mov_b32_dpp v1, v147 row_ror:8 row_mask:0xf bank_mask:0xf
	v_mov_b32_dpp v2, v148 row_ror:8 row_mask:0xf bank_mask:0xf
	v_mov_b32_dpp v3, v149 row_ror:8 row_mask:0xf bank_mask:0xf
	v_mov_b32_dpp v4, v82 row_ror:8 row_mask:0xf bank_mask:0xf
	v_mov_b32_dpp v5, v83 row_ror:8 row_mask:0xf bank_mask:0xf
	v_mov_b32_dpp v6, v84 row_ror:8 row_mask:0xf bank_mask:0xf
	v_mov_b32_dpp v7, v85 row_ror:8 row_mask:0xf bank_mask:0xf
	v_cndmask_b32_e32 v146, v146, v4, vcc
	v_cndmask_b32_e32 v147, v147, v5, vcc
	v_cndmask_b32_e32 v148, v148, v6, vcc
	v_cndmask_b32_e32 v149, v149, v7, vcc
	v_cndmask_b32_e32 v82, v0, v82, vcc
	v_cndmask_b32_e32 v83, v1, v83, vcc
	v_cndmask_b32_e32 v84, v2, v84, vcc
	v_cndmask_b32_e32 v85, v3, v85, vcc
	v_lshl_add_u64 v[10:11], v[22:23], 0, v[8:9]
	global_store_dwordx4 v[22:23], v[146:149], off
	global_store_dwordx4 v[10:11], v[82:85], off
	v_cvt_pk_f16_f32 v126, v126, v127
	v_cvt_pk_f16_f32 v127, v128, v129
	v_cvt_pk_f16_f32 v128, v110, v111
	v_cvt_pk_f16_f32 v129, v112, v113
	v_cvt_pk_f16_f32 v62, v62, v63
	v_cvt_pk_f16_f32 v63, v64, v65
	v_cvt_pk_f16_f32 v64, v46, v47
	v_cvt_pk_f16_f32 v65, v48, v49
	v_mov_b32_dpp v0, v126 row_ror:8 row_mask:0xf bank_mask:0xf
	v_mov_b32_dpp v1, v127 row_ror:8 row_mask:0xf bank_mask:0xf
	v_mov_b32_dpp v2, v128 row_ror:8 row_mask:0xf bank_mask:0xf
	v_mov_b32_dpp v3, v129 row_ror:8 row_mask:0xf bank_mask:0xf
	v_mov_b32_dpp v4, v62 row_ror:8 row_mask:0xf bank_mask:0xf
	v_mov_b32_dpp v5, v63 row_ror:8 row_mask:0xf bank_mask:0xf
	v_mov_b32_dpp v6, v64 row_ror:8 row_mask:0xf bank_mask:0xf
	v_mov_b32_dpp v7, v65 row_ror:8 row_mask:0xf bank_mask:0xf
	v_cndmask_b32_e32 v126, v126, v4, vcc
	v_cndmask_b32_e32 v127, v127, v5, vcc
	v_cndmask_b32_e32 v128, v128, v6, vcc
	v_cndmask_b32_e32 v129, v129, v7, vcc
	v_cndmask_b32_e32 v62, v0, v62, vcc
	v_cndmask_b32_e32 v63, v1, v63, vcc
	v_cndmask_b32_e32 v64, v2, v64, vcc
	v_cndmask_b32_e32 v65, v3, v65, vcc
	v_lshl_add_u64 v[10:11], v[24:25], 0, v[8:9]
	global_store_dwordx4 v[24:25], v[126:129], off
	global_store_dwordx4 v[10:11], v[62:65], off
	v_cvt_pk_f16_f32 v118, v118, v119
	v_cvt_pk_f16_f32 v119, v120, v121
	v_cvt_pk_f16_f32 v120, v102, v103
	v_cvt_pk_f16_f32 v121, v104, v105
	v_cvt_pk_f16_f32 v54, v54, v55
	v_cvt_pk_f16_f32 v55, v56, v57
	v_cvt_pk_f16_f32 v56, v38, v39
	v_cvt_pk_f16_f32 v57, v40, v41
	v_mov_b32_dpp v0, v118 row_ror:8 row_mask:0xf bank_mask:0xf
	v_mov_b32_dpp v1, v119 row_ror:8 row_mask:0xf bank_mask:0xf
	v_mov_b32_dpp v2, v120 row_ror:8 row_mask:0xf bank_mask:0xf
	v_mov_b32_dpp v3, v121 row_ror:8 row_mask:0xf bank_mask:0xf
	v_mov_b32_dpp v4, v54 row_ror:8 row_mask:0xf bank_mask:0xf
	v_mov_b32_dpp v5, v55 row_ror:8 row_mask:0xf bank_mask:0xf
	v_mov_b32_dpp v6, v56 row_ror:8 row_mask:0xf bank_mask:0xf
	v_mov_b32_dpp v7, v57 row_ror:8 row_mask:0xf bank_mask:0xf
	v_cndmask_b32_e32 v118, v118, v4, vcc
	v_cndmask_b32_e32 v119, v119, v5, vcc
	v_cndmask_b32_e32 v120, v120, v6, vcc
	v_cndmask_b32_e32 v121, v121, v7, vcc
	v_cndmask_b32_e32 v54, v0, v54, vcc
	v_cndmask_b32_e32 v55, v1, v55, vcc
	v_cndmask_b32_e32 v56, v2, v56, vcc
	v_cndmask_b32_e32 v57, v3, v57, vcc
	v_lshl_add_u64 v[10:11], v[26:27], 0, v[8:9]
	global_store_dwordx4 v[26:27], v[118:121], off
	global_store_dwordx4 v[10:11], v[54:57], off
	v_cvt_pk_f16_f32 v122, v122, v123
	v_cvt_pk_f16_f32 v123, v124, v125
	v_cvt_pk_f16_f32 v124, v106, v107
	v_cvt_pk_f16_f32 v125, v108, v109
	v_cvt_pk_f16_f32 v58, v58, v59
	v_cvt_pk_f16_f32 v59, v60, v61
	v_cvt_pk_f16_f32 v60, v42, v43
	v_cvt_pk_f16_f32 v61, v44, v45
	v_mov_b32_dpp v0, v122 row_ror:8 row_mask:0xf bank_mask:0xf
	v_mov_b32_dpp v1, v123 row_ror:8 row_mask:0xf bank_mask:0xf
	v_mov_b32_dpp v2, v124 row_ror:8 row_mask:0xf bank_mask:0xf
	v_mov_b32_dpp v3, v125 row_ror:8 row_mask:0xf bank_mask:0xf
	v_mov_b32_dpp v4, v58 row_ror:8 row_mask:0xf bank_mask:0xf
	v_mov_b32_dpp v5, v59 row_ror:8 row_mask:0xf bank_mask:0xf
	v_mov_b32_dpp v6, v60 row_ror:8 row_mask:0xf bank_mask:0xf
	v_mov_b32_dpp v7, v61 row_ror:8 row_mask:0xf bank_mask:0xf
	v_cndmask_b32_e32 v122, v122, v4, vcc
	v_cndmask_b32_e32 v123, v123, v5, vcc
	v_cndmask_b32_e32 v124, v124, v6, vcc
	v_cndmask_b32_e32 v125, v125, v7, vcc
	v_cndmask_b32_e32 v58, v0, v58, vcc
	v_cndmask_b32_e32 v59, v1, v59, vcc
	v_cndmask_b32_e32 v60, v2, v60, vcc
	v_cndmask_b32_e32 v61, v3, v61, vcc
	v_lshl_add_u64 v[10:11], v[28:29], 0, v[8:9]
	global_store_dwordx4 v[28:29], v[122:125], off
	global_store_dwordx4 v[10:11], v[58:61], off
	v_cvt_pk_f16_f32 v114, v114, v115
	v_cvt_pk_f16_f32 v115, v116, v117
	v_cvt_pk_f16_f32 v116, v98, v99
	v_cvt_pk_f16_f32 v117, v100, v101
	v_cvt_pk_f16_f32 v50, v50, v51
	v_cvt_pk_f16_f32 v51, v52, v53
	v_cvt_pk_f16_f32 v52, v34, v35
	v_cvt_pk_f16_f32 v53, v36, v37
	v_mov_b32_dpp v0, v114 row_ror:8 row_mask:0xf bank_mask:0xf
	v_mov_b32_dpp v1, v115 row_ror:8 row_mask:0xf bank_mask:0xf
	v_mov_b32_dpp v2, v116 row_ror:8 row_mask:0xf bank_mask:0xf
	v_mov_b32_dpp v3, v117 row_ror:8 row_mask:0xf bank_mask:0xf
	v_mov_b32_dpp v4, v50 row_ror:8 row_mask:0xf bank_mask:0xf
	v_mov_b32_dpp v5, v51 row_ror:8 row_mask:0xf bank_mask:0xf
	v_mov_b32_dpp v6, v52 row_ror:8 row_mask:0xf bank_mask:0xf
	v_mov_b32_dpp v7, v53 row_ror:8 row_mask:0xf bank_mask:0xf
	v_cndmask_b32_e32 v114, v114, v4, vcc
	v_cndmask_b32_e32 v115, v115, v5, vcc
	v_cndmask_b32_e32 v116, v116, v6, vcc
	v_cndmask_b32_e32 v117, v117, v7, vcc
	v_cndmask_b32_e32 v50, v0, v50, vcc
	v_cndmask_b32_e32 v51, v1, v51, vcc
	v_cndmask_b32_e32 v52, v2, v52, vcc
	v_cndmask_b32_e32 v53, v3, v53, vcc
	v_lshl_add_u64 v[10:11], v[30:31], 0, v[8:9]
	global_store_dwordx4 v[30:31], v[114:117], off
	global_store_dwordx4 v[10:11], v[50:53], off
	s_mov_b64 s[4:5], 0

.LBB0_940:
	s_add_u32 s20, s14, 0x100
	s_addc_u32 s21, s15, 0
	s_add_i32 s40, 0, 0x10000
	v_add_u32_e32 v32, s40, v209
	ds_read_b128 v[132:135], v32
	ds_read_b128 v[140:143], v32 offset:2048
	ds_read_b128 v[136:139], v32 offset:1024
	ds_read_b128 v[144:147], v32 offset:3072
	s_cmp_eq_u32 s11, 12
	s_cselect_b32 s25, s17, s21
	s_cselect_b32 s24, s16, s20
	s_cselect_b32 s23, s19, s3
	s_cselect_b32 s22, s18, s1
	v_lshl_add_u64 v[34:35], s[14:15], 0, v[200:201]
	s_add_i32 m0, s30, 0xc000
	ds_read_b128 v[148:151], v211
	ds_read_b128 v[156:159], v211 offset:2048
	ds_read_b128 v[164:167], v211 offset:4096
	ds_read_b128 v[172:175], v211 offset:6144
	ds_read_b128 v[152:155], v211 offset:1024
	ds_read_b128 v[160:163], v211 offset:3072
	ds_read_b128 v[168:171], v211 offset:5120
	ds_read_b128 v[176:179], v211 offset:7168
	global_load_lds_dwordx4 v[34:35], off
	v_lshl_add_u64 v[34:35], s[14:15], 0, v[202:203]
	s_add_i32 m0, s30, 0xe000
	s_nop 0
	global_load_lds_dwordx4 v[34:35], off
	s_waitcnt lgkmcnt(8)
	s_barrier
	s_waitcnt lgkmcnt(6)
	s_setprio 1
	v_mfma_f32_16x16x32_f16 v[128:131], v[132:135], v[148:151], v[128:131]
	v_mfma_f32_16x16x32_f16 v[124:127], v[140:143], v[148:151], v[124:127]
	v_mfma_f32_16x16x32_f16 v[120:123], v[132:135], v[156:159], v[120:123]
	v_mfma_f32_16x16x32_f16 v[116:119], v[140:143], v[156:159], v[116:119]
	s_waitcnt lgkmcnt(4)
	v_mfma_f32_16x16x32_f16 v[112:115], v[132:135], v[164:167], v[112:115]
	v_mfma_f32_16x16x32_f16 v[108:111], v[140:143], v[164:167], v[108:111]
	v_mfma_f32_16x16x32_f16 v[104:107], v[132:135], v[172:175], v[104:107]
	v_mfma_f32_16x16x32_f16 v[100:103], v[140:143], v[172:175], v[100:103]
	s_waitcnt lgkmcnt(2)
	v_mfma_f32_16x16x32_f16 v[128:131], v[136:139], v[152:155], v[128:131]
	v_mfma_f32_16x16x32_f16 v[124:127], v[144:147], v[152:155], v[124:127]
	v_mfma_f32_16x16x32_f16 v[120:123], v[136:139], v[160:163], v[120:123]
	v_mfma_f32_16x16x32_f16 v[116:119], v[144:147], v[160:163], v[116:119]
	s_waitcnt lgkmcnt(0)
	v_mfma_f32_16x16x32_f16 v[112:115], v[136:139], v[168:171], v[112:115]
	v_mfma_f32_16x16x32_f16 v[108:111], v[144:147], v[168:171], v[108:111]
	v_mfma_f32_16x16x32_f16 v[104:107], v[136:139], v[176:179], v[104:107]
	v_mfma_f32_16x16x32_f16 v[100:103], v[144:147], v[176:179], v[100:103]
	s_setprio 0
	s_barrier
	s_add_i32 s41, 0, 0x14000
	s_add_i32 s14, s40, s29
	v_add_u32_e32 v32, s41, v209
	v_lshl_add_u64 v[204:205], s[22:23], 0, v[196:197]
	s_mov_b32 m0, s14
	ds_read_b128 v[180:183], v32
	ds_read_b128 v[188:191], v32 offset:2048
	ds_read_b128 v[184:187], v32 offset:1024
	ds_read_b128 v[192:195], v32 offset:3072
	global_load_lds_dwordx4 v[204:205], off
	v_lshl_add_u64 v[206:207], s[22:23], 0, v[198:199]
	s_add_i32 m0, s14, 0x2000
	s_nop 0
	global_load_lds_dwordx4 v[206:207], off
	s_barrier
	s_waitcnt lgkmcnt(2)
	s_setprio 1
	v_mfma_f32_16x16x32_f16 v[96:99], v[180:183], v[148:151], v[96:99]
	v_mfma_f32_16x16x32_f16 v[92:95], v[188:191], v[148:151], v[92:95]
	v_mfma_f32_16x16x32_f16 v[88:91], v[180:183], v[156:159], v[88:91]
	v_mfma_f32_16x16x32_f16 v[84:87], v[188:191], v[156:159], v[84:87]
	v_mfma_f32_16x16x32_f16 v[80:83], v[180:183], v[164:167], v[80:83]
	v_mfma_f32_16x16x32_f16 v[76:79], v[188:191], v[164:167], v[76:79]
	v_mfma_f32_16x16x32_f16 v[72:75], v[180:183], v[172:175], v[72:75]
	v_mfma_f32_16x16x32_f16 v[68:71], v[188:191], v[172:175], v[68:71]
	s_waitcnt lgkmcnt(0)
	v_mfma_f32_16x16x32_f16 v[96:99], v[184:187], v[152:155], v[96:99]
	v_mfma_f32_16x16x32_f16 v[92:95], v[192:195], v[152:155], v[92:95]
	v_mfma_f32_16x16x32_f16 v[88:91], v[184:187], v[160:163], v[88:91]
	v_mfma_f32_16x16x32_f16 v[84:87], v[192:195], v[160:163], v[84:87]
	v_mfma_f32_16x16x32_f16 v[80:83], v[184:187], v[168:171], v[80:83]
	v_mfma_f32_16x16x32_f16 v[76:79], v[192:195], v[168:171], v[76:79]
	v_mfma_f32_16x16x32_f16 v[72:75], v[184:187], v[176:179], v[72:75]
	v_mfma_f32_16x16x32_f16 v[68:71], v[192:195], v[176:179], v[68:71]
	s_setprio 0
	s_mov_b32 m0, s30
	v_lshl_add_u64 v[212:213], s[24:25], 0, v[196:197]
	s_barrier
	ds_read_b128 v[148:151], v211 offset:16384
	ds_read_b128 v[156:159], v211 offset:18432
	ds_read_b128 v[164:167], v211 offset:20480
	ds_read_b128 v[172:175], v211 offset:22528
	ds_read_b128 v[152:155], v211 offset:17408
	ds_read_b128 v[160:163], v211 offset:19456
	ds_read_b128 v[168:171], v211 offset:21504
	ds_read_b128 v[176:179], v211 offset:23552
	global_load_lds_dwordx4 v[212:213], off
	v_lshl_add_u64 v[214:215], s[24:25], 0, v[198:199]
	s_mov_b32 m0, s31
	s_nop 0
	global_load_lds_dwordx4 v[214:215], off
	s_barrier
	s_waitcnt lgkmcnt(6)
	s_setprio 1
	v_mfma_f32_16x16x32_f16 v[64:67], v[132:135], v[148:151], v[64:67]
	v_mfma_f32_16x16x32_f16 v[60:63], v[140:143], v[148:151], v[60:63]
	v_mfma_f32_16x16x32_f16 v[56:59], v[132:135], v[156:159], v[56:59]
	v_mfma_f32_16x16x32_f16 v[52:55], v[140:143], v[156:159], v[52:55]
	s_waitcnt lgkmcnt(4)
	v_mfma_f32_16x16x32_f16 v[48:51], v[132:135], v[164:167], v[48:51]
	v_mfma_f32_16x16x32_f16 v[44:47], v[140:143], v[164:167], v[44:47]
	v_mfma_f32_16x16x32_f16 v[40:43], v[132:135], v[172:175], v[40:43]
	v_mfma_f32_16x16x32_f16 v[34:37], v[140:143], v[172:175], v[36:39]
	s_waitcnt lgkmcnt(2)
	v_mfma_f32_16x16x32_f16 v[64:67], v[136:139], v[152:155], v[64:67]
	v_mfma_f32_16x16x32_f16 v[60:63], v[144:147], v[152:155], v[60:63]
	v_mfma_f32_16x16x32_f16 v[56:59], v[136:139], v[160:163], v[56:59]
	v_mfma_f32_16x16x32_f16 v[52:55], v[144:147], v[160:163], v[52:55]
	s_waitcnt lgkmcnt(0)
	v_mfma_f32_16x16x32_f16 v[48:51], v[136:139], v[168:171], v[48:51]
	v_mfma_f32_16x16x32_f16 v[44:47], v[144:147], v[168:171], v[44:47]
	v_mfma_f32_16x16x32_f16 v[40:43], v[136:139], v[176:179], v[40:43]
	v_mfma_f32_16x16x32_f16 v[34:37], v[144:147], v[176:179], v[34:37]
	s_setprio 0
	s_barrier
	s_add_u32 s14, s22, 0x40000
	s_addc_u32 s15, s23, 0
	s_add_i32 s40, s41, s29
	v_lshl_add_u64 v[38:39], s[14:15], 0, v[196:197]
	s_mov_b32 m0, s40
	s_nop 0
	global_load_lds_dwordx4 v[38:39], off
	v_lshl_add_u64 v[38:39], s[14:15], 0, v[198:199]
	s_add_i32 m0, s40, 0x2000
	s_nop 0
	global_load_lds_dwordx4 v[38:39], off
	s_waitcnt vmcnt(6)
	s_barrier
	s_setprio 1
	v_mfma_f32_16x16x32_f16 v[28:31], v[180:183], v[148:151], v[28:31]
	v_mfma_f32_16x16x32_f16 v[24:27], v[188:191], v[148:151], v[24:27]
	v_mfma_f32_16x16x32_f16 v[20:23], v[180:183], v[156:159], v[20:23]
	v_mfma_f32_16x16x32_f16 v[16:19], v[188:191], v[156:159], v[16:19]
	v_mfma_f32_16x16x32_f16 v[12:15], v[180:183], v[164:167], v[12:15]
	v_mfma_f32_16x16x32_f16 v[8:11], v[188:191], v[164:167], v[8:11]
	v_mfma_f32_16x16x32_f16 v[4:7], v[180:183], v[172:175], v[4:7]
	v_mfma_f32_16x16x32_f16 v[0:3], v[188:191], v[172:175], v[0:3]
	v_mfma_f32_16x16x32_f16 v[28:31], v[184:187], v[152:155], v[28:31]
	v_mfma_f32_16x16x32_f16 v[24:27], v[192:195], v[152:155], v[24:27]
	v_mfma_f32_16x16x32_f16 v[20:23], v[184:187], v[160:163], v[20:23]
	v_mfma_f32_16x16x32_f16 v[16:19], v[192:195], v[160:163], v[16:19]
	v_mfma_f32_16x16x32_f16 v[12:15], v[184:187], v[168:171], v[12:15]
	v_mfma_f32_16x16x32_f16 v[8:11], v[192:195], v[168:171], v[8:11]
	v_mfma_f32_16x16x32_f16 v[4:7], v[184:187], v[176:179], v[4:7]
	v_mfma_f32_16x16x32_f16 v[0:3], v[192:195], v[176:179], v[0:3]
	s_setprio 0
	s_add_i32 s40, 0, 0x18000
	v_add_u32_e32 v32, s40, v209
	s_barrier
	ds_read_b128 v[132:135], v32
	ds_read_b128 v[140:143], v32 offset:2048
	ds_read_b128 v[136:139], v32 offset:1024
	ds_read_b128 v[144:147], v32 offset:3072
	s_add_u32 s14, s24, 0x40000
	s_addc_u32 s15, s25, 0
	s_mov_b32 m0, s34
	v_lshl_add_u64 v[38:39], s[14:15], 0, v[196:197]
	ds_read_b128 v[148:151], v211 offset:32768
	ds_read_b128 v[156:159], v211 offset:34816
	ds_read_b128 v[164:167], v211 offset:36864
	ds_read_b128 v[172:175], v211 offset:38912
	ds_read_b128 v[152:155], v211 offset:33792
	ds_read_b128 v[160:163], v211 offset:35840
	ds_read_b128 v[168:171], v211 offset:37888
	ds_read_b128 v[176:179], v211 offset:39936
	global_load_lds_dwordx4 v[38:39], off
	v_lshl_add_u64 v[38:39], s[14:15], 0, v[198:199]
	s_mov_b32 m0, s35
	s_nop 0
	global_load_lds_dwordx4 v[38:39], off
	s_waitcnt lgkmcnt(8)
	s_barrier
	s_waitcnt lgkmcnt(6)
	s_setprio 1
	v_mfma_f32_16x16x32_f16 v[128:131], v[132:135], v[148:151], v[128:131]
	v_mfma_f32_16x16x32_f16 v[124:127], v[140:143], v[148:151], v[124:127]
	v_mfma_f32_16x16x32_f16 v[120:123], v[132:135], v[156:159], v[120:123]
	v_mfma_f32_16x16x32_f16 v[116:119], v[140:143], v[156:159], v[116:119]
	s_waitcnt lgkmcnt(4)
	v_mfma_f32_16x16x32_f16 v[112:115], v[132:135], v[164:167], v[112:115]
	v_mfma_f32_16x16x32_f16 v[108:111], v[140:143], v[164:167], v[108:111]
	v_mfma_f32_16x16x32_f16 v[104:107], v[132:135], v[172:175], v[104:107]
	v_mfma_f32_16x16x32_f16 v[100:103], v[140:143], v[172:175], v[100:103]
	s_waitcnt lgkmcnt(2)
	v_mfma_f32_16x16x32_f16 v[128:131], v[136:139], v[152:155], v[128:131]
	v_mfma_f32_16x16x32_f16 v[124:127], v[144:147], v[152:155], v[124:127]
	v_mfma_f32_16x16x32_f16 v[120:123], v[136:139], v[160:163], v[120:123]
	v_mfma_f32_16x16x32_f16 v[116:119], v[144:147], v[160:163], v[116:119]
	s_waitcnt lgkmcnt(0)
	v_mfma_f32_16x16x32_f16 v[112:115], v[136:139], v[168:171], v[112:115]
	v_mfma_f32_16x16x32_f16 v[108:111], v[144:147], v[168:171], v[108:111]
	v_mfma_f32_16x16x32_f16 v[104:107], v[136:139], v[176:179], v[104:107]
	v_mfma_f32_16x16x32_f16 v[100:103], v[144:147], v[176:179], v[100:103]
	s_setprio 0
	s_barrier
	s_add_i32 s24, 0, 0x1c000
	s_add_i32 s14, s40, s29
	v_add_u32_e32 v32, s24, v209
	v_lshl_add_u64 v[38:39], v[204:205], 0, s[84:85]
	s_mov_b32 m0, s14
	ds_read_b128 v[180:183], v32
	ds_read_b128 v[188:191], v32 offset:2048
	ds_read_b128 v[184:187], v32 offset:1024
	ds_read_b128 v[192:195], v32 offset:3072
	global_load_lds_dwordx4 v[38:39], off
	v_lshl_add_u64 v[38:39], v[206:207], 0, s[84:85]
	s_add_i32 m0, s14, 0x2000
	s_nop 0
	global_load_lds_dwordx4 v[38:39], off
	s_barrier
	s_waitcnt lgkmcnt(2)
	s_setprio 1
	v_mfma_f32_16x16x32_f16 v[96:99], v[180:183], v[148:151], v[96:99]
	v_mfma_f32_16x16x32_f16 v[92:95], v[188:191], v[148:151], v[92:95]
	v_mfma_f32_16x16x32_f16 v[88:91], v[180:183], v[156:159], v[88:91]
	v_mfma_f32_16x16x32_f16 v[84:87], v[188:191], v[156:159], v[84:87]
	v_mfma_f32_16x16x32_f16 v[80:83], v[180:183], v[164:167], v[80:83]
	v_mfma_f32_16x16x32_f16 v[76:79], v[188:191], v[164:167], v[76:79]
	v_mfma_f32_16x16x32_f16 v[72:75], v[180:183], v[172:175], v[72:75]
	v_mfma_f32_16x16x32_f16 v[68:71], v[188:191], v[172:175], v[68:71]
	s_waitcnt lgkmcnt(0)
	v_mfma_f32_16x16x32_f16 v[96:99], v[184:187], v[152:155], v[96:99]
	v_mfma_f32_16x16x32_f16 v[92:95], v[192:195], v[152:155], v[92:95]
	v_mfma_f32_16x16x32_f16 v[88:91], v[184:187], v[160:163], v[88:91]
	v_mfma_f32_16x16x32_f16 v[84:87], v[192:195], v[160:163], v[84:87]
	v_mfma_f32_16x16x32_f16 v[80:83], v[184:187], v[168:171], v[80:83]
	v_mfma_f32_16x16x32_f16 v[76:79], v[192:195], v[168:171], v[76:79]
	v_mfma_f32_16x16x32_f16 v[72:75], v[184:187], v[176:179], v[72:75]
	v_mfma_f32_16x16x32_f16 v[68:71], v[192:195], v[176:179], v[68:71]
	s_setprio 0
	s_mov_b32 m0, s36
	v_lshl_add_u64 v[38:39], v[212:213], 0, s[84:85]
	s_barrier
	ds_read_b128 v[148:151], v211 offset:49152
	ds_read_b128 v[156:159], v211 offset:51200
	ds_read_b128 v[164:167], v211 offset:53248
	ds_read_b128 v[172:175], v211 offset:55296
	ds_read_b128 v[152:155], v211 offset:50176
	ds_read_b128 v[160:163], v211 offset:52224
	ds_read_b128 v[168:171], v211 offset:54272
	ds_read_b128 v[176:179], v211 offset:56320
	global_load_lds_dwordx4 v[38:39], off
	v_lshl_add_u64 v[38:39], v[214:215], 0, s[84:85]
	s_mov_b32 m0, s37
	s_nop 0
	global_load_lds_dwordx4 v[38:39], off
	s_barrier
	s_waitcnt lgkmcnt(6)
	s_setprio 1
	v_mfma_f32_16x16x32_f16 v[64:67], v[132:135], v[148:151], v[64:67]
	v_mfma_f32_16x16x32_f16 v[60:63], v[140:143], v[148:151], v[60:63]
	v_mfma_f32_16x16x32_f16 v[56:59], v[132:135], v[156:159], v[56:59]
	v_mfma_f32_16x16x32_f16 v[52:55], v[140:143], v[156:159], v[52:55]
	s_waitcnt lgkmcnt(4)
	v_mfma_f32_16x16x32_f16 v[48:51], v[132:135], v[164:167], v[48:51]
	v_mfma_f32_16x16x32_f16 v[44:47], v[140:143], v[164:167], v[44:47]
	v_mfma_f32_16x16x32_f16 v[38:41], v[132:135], v[172:175], v[40:43]
	v_mfma_f32_16x16x32_f16 v[34:37], v[140:143], v[172:175], v[34:37]
	s_waitcnt lgkmcnt(2)
	v_mfma_f32_16x16x32_f16 v[64:67], v[136:139], v[152:155], v[64:67]
	v_mfma_f32_16x16x32_f16 v[60:63], v[144:147], v[152:155], v[60:63]
	v_mfma_f32_16x16x32_f16 v[56:59], v[136:139], v[160:163], v[56:59]
	v_mfma_f32_16x16x32_f16 v[52:55], v[144:147], v[160:163], v[52:55]
	s_waitcnt lgkmcnt(0)
	v_mfma_f32_16x16x32_f16 v[48:51], v[136:139], v[168:171], v[48:51]
	v_mfma_f32_16x16x32_f16 v[44:47], v[144:147], v[168:171], v[44:47]
	v_mfma_f32_16x16x32_f16 v[40:43], v[136:139], v[176:179], v[38:41]
	v_mfma_f32_16x16x32_f16 v[36:39], v[144:147], v[176:179], v[34:37]
	s_setprio 0
	s_barrier
	s_add_u32 s14, s22, 0x40080
	s_addc_u32 s15, s23, 0
	s_add_i32 s22, s24, s29
	v_lshl_add_u64 v[34:35], s[14:15], 0, v[196:197]
	s_mov_b32 m0, s22
	s_nop 0
	global_load_lds_dwordx4 v[34:35], off
	v_lshl_add_u64 v[34:35], s[14:15], 0, v[198:199]
	s_add_i32 m0, s22, 0x2000
	s_nop 0
	global_load_lds_dwordx4 v[34:35], off
	s_waitcnt vmcnt(6)
	s_barrier
	s_setprio 1
	v_mfma_f32_16x16x32_f16 v[28:31], v[180:183], v[148:151], v[28:31]
	v_mfma_f32_16x16x32_f16 v[24:27], v[188:191], v[148:151], v[24:27]
	v_mfma_f32_16x16x32_f16 v[20:23], v[180:183], v[156:159], v[20:23]
	v_mfma_f32_16x16x32_f16 v[16:19], v[188:191], v[156:159], v[16:19]
	v_mfma_f32_16x16x32_f16 v[12:15], v[180:183], v[164:167], v[12:15]
	v_mfma_f32_16x16x32_f16 v[8:11], v[188:191], v[164:167], v[8:11]
	v_mfma_f32_16x16x32_f16 v[4:7], v[180:183], v[172:175], v[4:7]
	v_mfma_f32_16x16x32_f16 v[0:3], v[188:191], v[172:175], v[0:3]
	v_mfma_f32_16x16x32_f16 v[28:31], v[184:187], v[152:155], v[28:31]
	v_mfma_f32_16x16x32_f16 v[24:27], v[192:195], v[152:155], v[24:27]
	v_mfma_f32_16x16x32_f16 v[20:23], v[184:187], v[160:163], v[20:23]
	v_mfma_f32_16x16x32_f16 v[16:19], v[192:195], v[160:163], v[16:19]
	v_mfma_f32_16x16x32_f16 v[12:15], v[184:187], v[168:171], v[12:15]
	v_mfma_f32_16x16x32_f16 v[8:11], v[192:195], v[168:171], v[8:11]
	v_mfma_f32_16x16x32_f16 v[4:7], v[184:187], v[176:179], v[4:7]
	v_mfma_f32_16x16x32_f16 v[0:3], v[192:195], v[176:179], v[0:3]
	s_setprio 0
	s_add_i32 s11, s11, 2
	s_add_u32 s1, s1, 0x100
	s_addc_u32 s3, s3, 0
	s_cmp_gt_u32 s11, 13
	s_mov_b64 s[14:15], s[20:21]
	s_barrier
	s_cbranch_scc0 .LBB0_940
	v_lshl_add_u32 v34, s12, 8, v208
	v_lshl_or_b32 v156, s10, 8, v210
	s_cmp_lg_u32 s13, 0
	s_cselect_b64 s[10:11], -1, 0
	s_cmp_eq_u32 s13, 0
	v_ashrrev_i32_e32 v157, 31, v156
	v_ashrrev_i32_e32 v35, 31, v34
	v_mad_i64_i32 v[158:159], s[12:13], v34, s33, 0
	v_or_b32_e32 v160, 16, v34
	v_or_b32_e32 v162, 32, v34
	v_or_b32_e32 v164, 48, v34
	s_cbranch_scc1 .LBB0_946
	v_lshl_add_u64 v[132:133], s[70:71], 0, v[158:159]
	v_lshlrev_b64 v[166:167], 1, v[156:157]
	v_lshl_add_u64 v[132:133], v[132:133], 0, v[166:167]
	s_mov_b64 s[16:17], 0x2800
	v_mov_b64_e32 v[168:169], s[70:71]
	s_movk_i32 s1, 0x2000
	v_lshl_add_u64 v[134:135], v[132:133], 0, s[16:17]
	v_mad_i64_i32 v[136:137], s[12:13], v160, s33, v[168:169]
	v_add_co_u32_e32 v132, vcc, s1, v132
	v_lshl_add_u64 v[136:137], v[136:137], 0, v[166:167]
	s_nop 0
	v_addc_co_u32_e32 v133, vcc, 0, v133, vcc
	v_lshl_add_u64 v[138:139], v[136:137], 0, s[16:17]
	v_mad_i64_i32 v[140:141], s[12:13], v162, s33, v[168:169]
	v_add_co_u32_e32 v136, vcc, s1, v136
	v_lshl_add_u64 v[140:141], v[140:141], 0, v[166:167]
	s_nop 0
	v_addc_co_u32_e32 v137, vcc, 0, v137, vcc
	v_mad_i64_i32 v[144:145], s[12:13], v164, s33, v[168:169]
	global_load_dwordx4 v[170:173], v[132:133], off offset:2048
	global_load_dwordx4 v[152:155], v[136:137], off offset:2048
	global_load_dwordx4 v[174:177], v[134:135], off offset:256
	global_load_dwordx4 v[148:151], v[138:139], off offset:256
	v_add_co_u32_e32 v132, vcc, s1, v140
	v_lshl_add_u64 v[144:145], v[144:145], 0, v[166:167]
	s_nop 0
	v_addc_co_u32_e32 v133, vcc, 0, v141, vcc
	v_add_co_u32_e32 v134, vcc, s1, v144
	v_lshl_add_u64 v[142:143], v[140:141], 0, s[16:17]
	s_nop 0
	v_addc_co_u32_e32 v135, vcc, 0, v145, vcc
	v_lshl_add_u64 v[178:179], v[144:145], 0, s[16:17]
	global_load_dwordx4 v[144:147], v[132:133], off offset:2048
	global_load_dwordx4 v[136:139], v[134:135], off offset:2048
	s_nop 0
	global_load_dwordx4 v[140:143], v[142:143], off offset:256
	s_nop 0
	global_load_dwordx4 v[132:135], v[178:179], off offset:256
	v_ashrrev_i32_e32 v161, 31, v160
	v_ashrrev_i32_e32 v163, 31, v162
	v_ashrrev_i32_e32 v165, 31, v164
	s_waitcnt vmcnt(0)
	v_cvt_f32_f16_e32 v32, v170
	v_cvt_f32_f16_sdwa v170, v170 dst_sel:DWORD dst_unused:UNUSED_PAD src0_sel:WORD_1
	v_lshlrev_b64 v[178:179], 11, v[34:35]
	v_readlane_b32 s14, v252, 9
	v_max_f32_e32 v32, 0xc1f00000, v32
	v_max_f32_e32 v35, 0xc1f00000, v170
	v_cvt_f32_f16_e32 v170, v171
	v_cvt_f32_f16_sdwa v171, v171 dst_sel:DWORD dst_unused:UNUSED_PAD src0_sel:WORD_1
	v_mul_f32_e32 v35, 0xbfb8aa3b, v35
	v_exp_f32_e32 v35, v35
	v_max_f32_e32 v170, 0xc1f00000, v170
	v_mul_f32_e32 v170, 0xbfb8aa3b, v170
	v_exp_f32_e32 v180, v170
	v_max_f32_e32 v170, 0xc1f00000, v171
	v_mul_f32_e32 v170, 0xbfb8aa3b, v170
	v_cvt_f32_f16_e32 v171, v172
	v_exp_f32_e32 v181, v170
	v_cvt_f32_f16_sdwa v170, v172 dst_sel:DWORD dst_unused:UNUSED_PAD src0_sel:WORD_1
	v_mul_f32_e32 v32, 0xbfb8aa3b, v32
	v_max_f32_e32 v171, 0xc1f00000, v171
	v_mul_f32_e32 v171, 0xbfb8aa3b, v171
	v_max_f32_e32 v170, 0xc1f00000, v170
	v_mul_f32_e32 v170, 0xbfb8aa3b, v170
	v_exp_f32_e32 v182, v171
	v_cvt_f32_f16_e32 v171, v173
	v_exp_f32_e32 v183, v170
	v_cvt_f32_f16_sdwa v170, v173 dst_sel:DWORD dst_unused:UNUSED_PAD src0_sel:WORD_1
	v_exp_f32_e32 v32, v32
	v_max_f32_e32 v171, 0xc1f00000, v171
	v_mul_f32_e32 v171, 0xbfb8aa3b, v171
	v_max_f32_e32 v170, 0xc1f00000, v170
	v_mul_f32_e32 v170, 0xbfb8aa3b, v170
	v_add_f32_e32 v35, 1.0, v35
	v_exp_f32_e32 v184, v171
	v_exp_f32_e32 v185, v170
	v_rcp_f32_e32 v170, v35
	v_add_f32_e32 v35, 1.0, v180
	v_rcp_f32_e32 v171, v35
	v_add_f32_e32 v35, 1.0, v181
	v_add_f32_e32 v32, 1.0, v32
	v_rcp_f32_e32 v172, v35
	v_add_f32_e32 v35, 1.0, v182
	v_rcp_f32_e32 v32, v32
	v_rcp_f32_e32 v173, v35
	v_add_f32_e32 v35, 1.0, v183
	v_rcp_f32_e32 v180, v35
	v_add_f32_e32 v35, 1.0, v184
	v_rcp_f32_e32 v181, v35
	v_mov_b32_e32 v182, v129
	v_mov_b32_e32 v183, v130
	v_pk_mul_f32 v[170:171], v[182:183], v[170:171]
	v_pk_mov_b32 v[182:183], v[130:131], v[124:125] op_sel:[1,0]
	v_add_f32_e32 v35, 1.0, v185
	v_fma_mixlo_f16 v32, v128, v32, 0
	v_cvt_pk_f16_f32 v171, v170, v171
	v_pk_mul_f32 v[172:173], v[182:183], v[172:173]
	v_rcp_f32_e32 v35, v35
	v_pack_b32_f16 v170, v32, v171
	v_cvt_pk_f16_f32 v32, v172, v173
	v_mov_b32_e32 v172, v125
	v_mov_b32_e32 v173, v126
	v_pk_mul_f32 v[172:173], v[172:173], v[180:181]
	v_readlane_b32 s15, v252, 10
	v_cvt_pk_f16_f32 v173, v172, v173
	v_alignbit_b32 v172, v173, v32, 16
	v_lshrrev_b32_e32 v173, 16, v173
	v_lshl_add_u64 v[178:179], s[14:15], 0, v[178:179]
	v_alignbit_b32 v171, v32, v171, 16
	v_fma_mixhi_f16 v173, v127, v35, 0
	v_lshl_add_u64 v[178:179], v[178:179], 0, v[166:167]
	global_store_dwordx4 v[178:179], v[170:173], off
	v_cvt_f32_f16_sdwa v35, v174 dst_sel:DWORD dst_unused:UNUSED_PAD src0_sel:WORD_1
	v_cvt_f32_f16_e32 v32, v174
	v_cvt_f32_f16_e32 v170, v175
	v_cvt_f32_f16_sdwa v171, v175 dst_sel:DWORD dst_unused:UNUSED_PAD src0_sel:WORD_1
	v_max_f32_e32 v35, 0xc1f00000, v35
	v_mul_f32_e32 v35, 0xbfb8aa3b, v35
	v_max_f32_e32 v170, 0xc1f00000, v170
	v_mul_f32_e32 v170, 0xbfb8aa3b, v170
	v_exp_f32_e32 v172, v170
	v_max_f32_e32 v170, 0xc1f00000, v171
	v_mul_f32_e32 v170, 0xbfb8aa3b, v170
	v_cvt_f32_f16_e32 v171, v176
	v_exp_f32_e32 v173, v170
	v_cvt_f32_f16_sdwa v170, v176 dst_sel:DWORD dst_unused:UNUSED_PAD src0_sel:WORD_1
	v_exp_f32_e32 v35, v35
	v_max_f32_e32 v171, 0xc1f00000, v171
	v_mul_f32_e32 v171, 0xbfb8aa3b, v171
	v_max_f32_e32 v170, 0xc1f00000, v170
	v_mul_f32_e32 v170, 0xbfb8aa3b, v170
	v_exp_f32_e32 v174, v171
	v_cvt_f32_f16_e32 v171, v177
	v_exp_f32_e32 v175, v170
	v_cvt_f32_f16_sdwa v170, v177 dst_sel:DWORD dst_unused:UNUSED_PAD src0_sel:WORD_1
	v_max_f32_e32 v32, 0xc1f00000, v32
	v_mul_f32_e32 v32, 0xbfb8aa3b, v32
	v_exp_f32_e32 v32, v32
	v_max_f32_e32 v171, 0xc1f00000, v171
	v_max_f32_e32 v170, 0xc1f00000, v170
	v_mul_f32_e32 v171, 0xbfb8aa3b, v171
	v_mul_f32_e32 v170, 0xbfb8aa3b, v170
	v_add_f32_e32 v35, 1.0, v35
	v_exp_f32_e32 v176, v171
	v_exp_f32_e32 v177, v170
	v_rcp_f32_e32 v170, v35
	v_add_f32_e32 v35, 1.0, v172
	v_rcp_f32_e32 v171, v35
	v_add_f32_e32 v35, 1.0, v173
	v_add_f32_e32 v32, 1.0, v32
	v_rcp_f32_e32 v172, v35
	v_add_f32_e32 v35, 1.0, v174
	v_rcp_f32_e32 v32, v32
	v_rcp_f32_e32 v173, v35
	v_add_f32_e32 v35, 1.0, v175
	v_rcp_f32_e32 v174, v35
	v_add_f32_e32 v35, 1.0, v176
	v_rcp_f32_e32 v175, v35
	v_add_f32_e32 v35, 1.0, v177
	v_mov_b32_e32 v176, v97
	v_mov_b32_e32 v177, v98
	v_pk_mul_f32 v[170:171], v[176:177], v[170:171]
	v_pk_mov_b32 v[176:177], v[98:99], v[92:93] op_sel:[1,0]
	v_fma_mixlo_f16 v32, v96, v32, 0
	v_cvt_pk_f16_f32 v171, v170, v171
	v_pk_mul_f32 v[172:173], v[176:177], v[172:173]
	v_rcp_f32_e32 v35, v35
	v_pack_b32_f16 v170, v32, v171
	v_cvt_pk_f16_f32 v32, v172, v173
	v_mov_b32_e32 v172, v93
	v_mov_b32_e32 v173, v94
	v_pk_mul_f32 v[172:173], v[172:173], v[174:175]
	v_alignbit_b32 v171, v32, v171, 16
	v_cvt_pk_f16_f32 v173, v172, v173
	v_alignbit_b32 v172, v173, v32, 16
	v_lshrrev_b32_e32 v173, 16, v173
	v_fma_mixhi_f16 v173, v95, v35, 0
	v_cvt_f32_f16_e32 v32, v152
	v_cvt_f32_f16_sdwa v35, v152 dst_sel:DWORD dst_unused:UNUSED_PAD src0_sel:WORD_1
	v_cvt_f32_f16_e32 v152, v153
	v_cvt_f32_f16_sdwa v153, v153 dst_sel:DWORD dst_unused:UNUSED_PAD src0_sel:WORD_1
	global_store_dwordx4 v[178:179], v[170:173], off offset:256
	v_max_f32_e32 v35, 0xc1f00000, v35
	v_max_f32_e32 v152, 0xc1f00000, v152
	v_mul_f32_e32 v152, 0xbfb8aa3b, v152
	v_lshlrev_b64 v[170:171], 11, v[160:161]
	v_exp_f32_e32 v161, v152
	v_max_f32_e32 v152, 0xc1f00000, v153
	v_mul_f32_e32 v152, 0xbfb8aa3b, v152
	v_cvt_f32_f16_e32 v153, v154
	v_exp_f32_e32 v172, v152
	v_cvt_f32_f16_sdwa v152, v154 dst_sel:DWORD dst_unused:UNUSED_PAD src0_sel:WORD_1
	v_mul_f32_e32 v35, 0xbfb8aa3b, v35
	v_max_f32_e32 v153, 0xc1f00000, v153
	v_mul_f32_e32 v153, 0xbfb8aa3b, v153
	v_max_f32_e32 v152, 0xc1f00000, v152
	v_mul_f32_e32 v152, 0xbfb8aa3b, v152
	v_exp_f32_e32 v173, v153
	v_cvt_f32_f16_e32 v153, v155
	v_exp_f32_e32 v174, v152
	v_cvt_f32_f16_sdwa v152, v155 dst_sel:DWORD dst_unused:UNUSED_PAD src0_sel:WORD_1
	v_exp_f32_e32 v35, v35
	v_max_f32_e32 v32, 0xc1f00000, v32
	v_mul_f32_e32 v32, 0xbfb8aa3b, v32
	v_exp_f32_e32 v32, v32
	v_max_f32_e32 v153, 0xc1f00000, v153
	v_max_f32_e32 v152, 0xc1f00000, v152
	v_mul_f32_e32 v153, 0xbfb8aa3b, v153
	v_mul_f32_e32 v152, 0xbfb8aa3b, v152
	v_add_f32_e32 v35, 1.0, v35
	v_exp_f32_e32 v175, v153
	v_exp_f32_e32 v176, v152
	v_rcp_f32_e32 v152, v35
	v_add_f32_e32 v35, 1.0, v161
	v_rcp_f32_e32 v153, v35
	v_add_f32_e32 v35, 1.0, v172
	v_add_f32_e32 v32, 1.0, v32
	v_rcp_f32_e32 v154, v35
	v_add_f32_e32 v35, 1.0, v173
	v_rcp_f32_e32 v32, v32
	v_rcp_f32_e32 v155, v35
	v_add_f32_e32 v35, 1.0, v174
	v_rcp_f32_e32 v172, v35
	v_add_f32_e32 v35, 1.0, v175
	v_rcp_f32_e32 v173, v35
	v_mov_b32_e32 v174, v121
	v_mov_b32_e32 v175, v122
	v_pk_mul_f32 v[152:153], v[174:175], v[152:153]
	v_pk_mov_b32 v[174:175], v[122:123], v[116:117] op_sel:[1,0]
	v_add_f32_e32 v35, 1.0, v176
	v_fma_mixlo_f16 v32, v120, v32, 0
	v_cvt_pk_f16_f32 v153, v152, v153
	v_pk_mul_f32 v[154:155], v[174:175], v[154:155]
	v_rcp_f32_e32 v35, v35
	v_pack_b32_f16 v152, v32, v153
	v_cvt_pk_f16_f32 v32, v154, v155
	v_mov_b32_e32 v154, v117
	v_mov_b32_e32 v155, v118
	v_pk_mul_f32 v[154:155], v[154:155], v[172:173]
	v_alignbit_b32 v153, v32, v153, 16
	v_cvt_pk_f16_f32 v155, v154, v155
	v_alignbit_b32 v154, v155, v32, 16
	v_lshrrev_b32_e32 v155, 16, v155
	v_fma_mixhi_f16 v155, v119, v35, 0
	v_cvt_f32_f16_e32 v32, v148
	v_cvt_f32_f16_sdwa v35, v148 dst_sel:DWORD dst_unused:UNUSED_PAD src0_sel:WORD_1
	v_cvt_f32_f16_e32 v148, v149
	v_cvt_f32_f16_sdwa v149, v149 dst_sel:DWORD dst_unused:UNUSED_PAD src0_sel:WORD_1
	v_lshl_add_u64 v[170:171], s[14:15], 0, v[170:171]
	v_lshl_add_u64 v[170:171], v[170:171], 0, v[166:167]
	v_max_f32_e32 v148, 0xc1f00000, v148
	v_mul_f32_e32 v148, 0xbfb8aa3b, v148
	global_store_dwordx4 v[170:171], v[152:155], off
	v_max_f32_e32 v35, 0xc1f00000, v35
	v_mul_f32_e32 v35, 0xbfb8aa3b, v35
	v_exp_f32_e32 v152, v148
	v_max_f32_e32 v148, 0xc1f00000, v149
	v_mul_f32_e32 v148, 0xbfb8aa3b, v148
	v_cvt_f32_f16_e32 v149, v150
	v_exp_f32_e32 v153, v148
	v_cvt_f32_f16_sdwa v148, v150 dst_sel:DWORD dst_unused:UNUSED_PAD src0_sel:WORD_1
	v_exp_f32_e32 v35, v35
	v_max_f32_e32 v149, 0xc1f00000, v149
	v_mul_f32_e32 v149, 0xbfb8aa3b, v149
	v_max_f32_e32 v148, 0xc1f00000, v148
	v_mul_f32_e32 v148, 0xbfb8aa3b, v148
	v_exp_f32_e32 v154, v149
	v_cvt_f32_f16_e32 v149, v151
	v_exp_f32_e32 v155, v148
	v_cvt_f32_f16_sdwa v148, v151 dst_sel:DWORD dst_unused:UNUSED_PAD src0_sel:WORD_1
	v_max_f32_e32 v32, 0xc1f00000, v32
	v_mul_f32_e32 v32, 0xbfb8aa3b, v32
	v_exp_f32_e32 v32, v32
	v_max_f32_e32 v149, 0xc1f00000, v149
	v_max_f32_e32 v148, 0xc1f00000, v148
	v_mul_f32_e32 v149, 0xbfb8aa3b, v149
	v_mul_f32_e32 v148, 0xbfb8aa3b, v148
	v_add_f32_e32 v35, 1.0, v35
	v_exp_f32_e32 v161, v149
	v_exp_f32_e32 v172, v148
	v_rcp_f32_e32 v148, v35
	v_add_f32_e32 v35, 1.0, v152
	v_rcp_f32_e32 v149, v35
	v_add_f32_e32 v35, 1.0, v153
	v_add_f32_e32 v32, 1.0, v32
	v_rcp_f32_e32 v150, v35
	v_add_f32_e32 v35, 1.0, v154
	v_rcp_f32_e32 v32, v32
	v_rcp_f32_e32 v151, v35
	v_add_f32_e32 v35, 1.0, v155
	v_rcp_f32_e32 v152, v35
	v_add_f32_e32 v35, 1.0, v161
	v_rcp_f32_e32 v153, v35
	v_mov_b32_e32 v154, v89
	v_mov_b32_e32 v155, v90
	v_pk_mul_f32 v[148:149], v[154:155], v[148:149]
	v_pk_mov_b32 v[154:155], v[90:91], v[84:85] op_sel:[1,0]
	v_add_f32_e32 v35, 1.0, v172
	v_fma_mixlo_f16 v32, v88, v32, 0
	v_cvt_pk_f16_f32 v149, v148, v149
	v_pk_mul_f32 v[150:151], v[154:155], v[150:151]
	v_rcp_f32_e32 v35, v35
	v_pack_b32_f16 v148, v32, v149
	v_cvt_pk_f16_f32 v32, v150, v151
	v_mov_b32_e32 v150, v85
	v_mov_b32_e32 v151, v86
	v_pk_mul_f32 v[150:151], v[150:151], v[152:153]
	v_alignbit_b32 v149, v32, v149, 16
	v_cvt_pk_f16_f32 v151, v150, v151
	v_alignbit_b32 v150, v151, v32, 16
	v_lshrrev_b32_e32 v151, 16, v151
	v_fma_mixhi_f16 v151, v87, v35, 0
	v_cvt_f32_f16_e32 v32, v144
	v_cvt_f32_f16_sdwa v35, v144 dst_sel:DWORD dst_unused:UNUSED_PAD src0_sel:WORD_1
	v_cvt_f32_f16_e32 v144, v145
	v_cvt_f32_f16_sdwa v145, v145 dst_sel:DWORD dst_unused:UNUSED_PAD src0_sel:WORD_1
	global_store_dwordx4 v[170:171], v[148:151], off offset:256
	v_max_f32_e32 v35, 0xc1f00000, v35
	v_max_f32_e32 v144, 0xc1f00000, v144
	v_mul_f32_e32 v144, 0xbfb8aa3b, v144
	v_exp_f32_e32 v150, v144
	v_max_f32_e32 v144, 0xc1f00000, v145
	v_mul_f32_e32 v144, 0xbfb8aa3b, v144
	v_cvt_f32_f16_e32 v145, v146
	v_exp_f32_e32 v151, v144
	v_cvt_f32_f16_sdwa v144, v146 dst_sel:DWORD dst_unused:UNUSED_PAD src0_sel:WORD_1
	v_mul_f32_e32 v35, 0xbfb8aa3b, v35
	v_max_f32_e32 v145, 0xc1f00000, v145
	v_mul_f32_e32 v145, 0xbfb8aa3b, v145
	v_max_f32_e32 v144, 0xc1f00000, v144
	v_mul_f32_e32 v144, 0xbfb8aa3b, v144
	v_exp_f32_e32 v152, v145
	v_cvt_f32_f16_e32 v145, v147
	v_exp_f32_e32 v153, v144
	v_cvt_f32_f16_sdwa v144, v147 dst_sel:DWORD dst_unused:UNUSED_PAD src0_sel:WORD_1
	v_exp_f32_e32 v35, v35
	v_max_f32_e32 v32, 0xc1f00000, v32
	v_mul_f32_e32 v32, 0xbfb8aa3b, v32
	v_exp_f32_e32 v32, v32
	v_max_f32_e32 v145, 0xc1f00000, v145
	v_max_f32_e32 v144, 0xc1f00000, v144
	v_mul_f32_e32 v145, 0xbfb8aa3b, v145
	v_mul_f32_e32 v144, 0xbfb8aa3b, v144
	v_add_f32_e32 v35, 1.0, v35
	v_exp_f32_e32 v154, v145
	v_exp_f32_e32 v155, v144
	v_rcp_f32_e32 v144, v35
	v_add_f32_e32 v35, 1.0, v150
	v_rcp_f32_e32 v145, v35
	v_add_f32_e32 v35, 1.0, v151
	v_add_f32_e32 v32, 1.0, v32
	v_rcp_f32_e32 v146, v35
	v_add_f32_e32 v35, 1.0, v152
	v_rcp_f32_e32 v32, v32
	v_rcp_f32_e32 v147, v35
	v_add_f32_e32 v35, 1.0, v153
	v_rcp_f32_e32 v150, v35
	v_add_f32_e32 v35, 1.0, v154
	v_rcp_f32_e32 v151, v35
	v_mov_b32_e32 v152, v113
	v_mov_b32_e32 v153, v114
	v_pk_mul_f32 v[144:145], v[152:153], v[144:145]
	v_pk_mov_b32 v[152:153], v[114:115], v[108:109] op_sel:[1,0]
	v_add_f32_e32 v35, 1.0, v155
	v_fma_mixlo_f16 v32, v112, v32, 0
	v_cvt_pk_f16_f32 v145, v144, v145
	v_pk_mul_f32 v[146:147], v[152:153], v[146:147]
	v_rcp_f32_e32 v35, v35
	v_pack_b32_f16 v144, v32, v145
	v_cvt_pk_f16_f32 v32, v146, v147
	v_mov_b32_e32 v146, v109
	v_mov_b32_e32 v147, v110
	v_pk_mul_f32 v[146:147], v[146:147], v[150:151]
	v_alignbit_b32 v145, v32, v145, 16
	v_cvt_pk_f16_f32 v147, v146, v147
	v_alignbit_b32 v146, v147, v32, 16
	v_lshrrev_b32_e32 v147, 16, v147
	v_fma_mixhi_f16 v147, v111, v35, 0
	v_cvt_f32_f16_e32 v32, v140
	v_cvt_f32_f16_sdwa v35, v140 dst_sel:DWORD dst_unused:UNUSED_PAD src0_sel:WORD_1
	v_cvt_f32_f16_e32 v140, v141
	v_cvt_f32_f16_sdwa v141, v141 dst_sel:DWORD dst_unused:UNUSED_PAD src0_sel:WORD_1
	v_lshlrev_b64 v[148:149], 11, v[162:163]
	v_lshl_add_u64 v[148:149], s[14:15], 0, v[148:149]
	v_max_f32_e32 v140, 0xc1f00000, v140
	v_lshl_add_u64 v[148:149], v[148:149], 0, v[166:167]
	v_mul_f32_e32 v140, 0xbfb8aa3b, v140
	global_store_dwordx4 v[148:149], v[144:147], off
	v_max_f32_e32 v35, 0xc1f00000, v35
	v_mul_f32_e32 v35, 0xbfb8aa3b, v35
	v_exp_f32_e32 v144, v140
	v_max_f32_e32 v140, 0xc1f00000, v141
	v_mul_f32_e32 v140, 0xbfb8aa3b, v140
	v_cvt_f32_f16_e32 v141, v142
	v_exp_f32_e32 v145, v140
	v_cvt_f32_f16_sdwa v140, v142 dst_sel:DWORD dst_unused:UNUSED_PAD src0_sel:WORD_1
	v_exp_f32_e32 v35, v35
	v_max_f32_e32 v141, 0xc1f00000, v141
	v_mul_f32_e32 v141, 0xbfb8aa3b, v141
	v_max_f32_e32 v140, 0xc1f00000, v140
	v_mul_f32_e32 v140, 0xbfb8aa3b, v140
	v_exp_f32_e32 v146, v141
	v_cvt_f32_f16_e32 v141, v143
	v_exp_f32_e32 v147, v140
	v_cvt_f32_f16_sdwa v140, v143 dst_sel:DWORD dst_unused:UNUSED_PAD src0_sel:WORD_1
	v_max_f32_e32 v32, 0xc1f00000, v32
	v_mul_f32_e32 v32, 0xbfb8aa3b, v32
	v_exp_f32_e32 v32, v32
	v_max_f32_e32 v141, 0xc1f00000, v141
	v_max_f32_e32 v140, 0xc1f00000, v140
	v_mul_f32_e32 v141, 0xbfb8aa3b, v141
	v_mul_f32_e32 v140, 0xbfb8aa3b, v140
	v_add_f32_e32 v35, 1.0, v35
	v_exp_f32_e32 v150, v141
	v_exp_f32_e32 v151, v140
	v_rcp_f32_e32 v140, v35
	v_add_f32_e32 v35, 1.0, v144
	v_rcp_f32_e32 v141, v35
	v_add_f32_e32 v35, 1.0, v145
	v_add_f32_e32 v32, 1.0, v32
	v_rcp_f32_e32 v142, v35
	v_add_f32_e32 v35, 1.0, v146
	v_rcp_f32_e32 v32, v32
	v_rcp_f32_e32 v143, v35
	v_add_f32_e32 v35, 1.0, v147
	v_rcp_f32_e32 v144, v35
	v_add_f32_e32 v35, 1.0, v150
	v_rcp_f32_e32 v145, v35
	v_mov_b32_e32 v146, v81
	v_mov_b32_e32 v147, v82
	v_pk_mul_f32 v[140:141], v[146:147], v[140:141]
	v_pk_mov_b32 v[146:147], v[82:83], v[76:77] op_sel:[1,0]
	v_add_f32_e32 v35, 1.0, v151
	v_fma_mixlo_f16 v32, v80, v32, 0
	v_cvt_pk_f16_f32 v141, v140, v141
	v_pk_mul_f32 v[142:143], v[146:147], v[142:143]
	v_rcp_f32_e32 v35, v35
	v_pack_b32_f16 v140, v32, v141
	v_cvt_pk_f16_f32 v32, v142, v143
	v_mov_b32_e32 v142, v77
	v_mov_b32_e32 v143, v78
	v_pk_mul_f32 v[142:143], v[142:143], v[144:145]
	v_alignbit_b32 v141, v32, v141, 16
	v_cvt_pk_f16_f32 v143, v142, v143
	v_alignbit_b32 v142, v143, v32, 16
	v_lshrrev_b32_e32 v143, 16, v143
	v_fma_mixhi_f16 v143, v79, v35, 0
	v_cvt_f32_f16_e32 v32, v136
	v_cvt_f32_f16_sdwa v35, v136 dst_sel:DWORD dst_unused:UNUSED_PAD src0_sel:WORD_1
	v_cvt_f32_f16_e32 v136, v137
	v_cvt_f32_f16_sdwa v137, v137 dst_sel:DWORD dst_unused:UNUSED_PAD src0_sel:WORD_1
	global_store_dwordx4 v[148:149], v[140:143], off offset:256
	v_max_f32_e32 v35, 0xc1f00000, v35
	v_max_f32_e32 v136, 0xc1f00000, v136
	v_mul_f32_e32 v136, 0xbfb8aa3b, v136
	v_exp_f32_e32 v142, v136
	v_max_f32_e32 v136, 0xc1f00000, v137
	v_mul_f32_e32 v136, 0xbfb8aa3b, v136
	v_cvt_f32_f16_e32 v137, v138
	v_exp_f32_e32 v143, v136
	v_cvt_f32_f16_sdwa v136, v138 dst_sel:DWORD dst_unused:UNUSED_PAD src0_sel:WORD_1
	v_mul_f32_e32 v35, 0xbfb8aa3b, v35
	v_max_f32_e32 v137, 0xc1f00000, v137
	v_mul_f32_e32 v137, 0xbfb8aa3b, v137
	v_max_f32_e32 v136, 0xc1f00000, v136
	v_mul_f32_e32 v136, 0xbfb8aa3b, v136
	v_exp_f32_e32 v144, v137
	v_cvt_f32_f16_e32 v137, v139
	v_exp_f32_e32 v145, v136
	v_cvt_f32_f16_sdwa v136, v139 dst_sel:DWORD dst_unused:UNUSED_PAD src0_sel:WORD_1
	v_exp_f32_e32 v35, v35
	v_max_f32_e32 v32, 0xc1f00000, v32
	v_mul_f32_e32 v32, 0xbfb8aa3b, v32
	v_exp_f32_e32 v32, v32
	v_max_f32_e32 v137, 0xc1f00000, v137
	v_max_f32_e32 v136, 0xc1f00000, v136
	v_mul_f32_e32 v137, 0xbfb8aa3b, v137
	v_mul_f32_e32 v136, 0xbfb8aa3b, v136
	v_add_f32_e32 v35, 1.0, v35
	v_exp_f32_e32 v146, v137
	v_exp_f32_e32 v147, v136
	v_rcp_f32_e32 v136, v35
	v_add_f32_e32 v35, 1.0, v142
	v_rcp_f32_e32 v137, v35
	v_add_f32_e32 v35, 1.0, v143
	v_add_f32_e32 v32, 1.0, v32
	v_rcp_f32_e32 v138, v35
	v_add_f32_e32 v35, 1.0, v144
	v_rcp_f32_e32 v32, v32
	v_rcp_f32_e32 v139, v35
	v_add_f32_e32 v35, 1.0, v145
	v_rcp_f32_e32 v142, v35
	v_add_f32_e32 v35, 1.0, v146
	v_rcp_f32_e32 v143, v35
	v_mov_b32_e32 v144, v105
	v_mov_b32_e32 v145, v106
	v_pk_mul_f32 v[136:137], v[144:145], v[136:137]
	v_pk_mov_b32 v[144:145], v[106:107], v[100:101] op_sel:[1,0]
	v_add_f32_e32 v35, 1.0, v147
	v_fma_mixlo_f16 v32, v104, v32, 0
	v_cvt_pk_f16_f32 v137, v136, v137
	v_pk_mul_f32 v[138:139], v[144:145], v[138:139]
	v_rcp_f32_e32 v35, v35
	v_pack_b32_f16 v136, v32, v137
	v_cvt_pk_f16_f32 v32, v138, v139
	v_mov_b32_e32 v138, v101
	v_mov_b32_e32 v139, v102
	v_pk_mul_f32 v[138:139], v[138:139], v[142:143]
	v_alignbit_b32 v137, v32, v137, 16
	v_cvt_pk_f16_f32 v139, v138, v139
	v_alignbit_b32 v138, v139, v32, 16
	v_lshrrev_b32_e32 v139, 16, v139
	v_fma_mixhi_f16 v139, v103, v35, 0
	v_cvt_f32_f16_e32 v32, v132
	v_cvt_f32_f16_sdwa v35, v132 dst_sel:DWORD dst_unused:UNUSED_PAD src0_sel:WORD_1
	v_cvt_f32_f16_e32 v132, v133
	v_cvt_f32_f16_sdwa v133, v133 dst_sel:DWORD dst_unused:UNUSED_PAD src0_sel:WORD_1
	v_lshlrev_b64 v[140:141], 11, v[164:165]
	v_lshl_add_u64 v[140:141], s[14:15], 0, v[140:141]
	v_max_f32_e32 v132, 0xc1f00000, v132
	v_lshl_add_u64 v[140:141], v[140:141], 0, v[166:167]
	v_mul_f32_e32 v132, 0xbfb8aa3b, v132
	global_store_dwordx4 v[140:141], v[136:139], off
	v_max_f32_e32 v35, 0xc1f00000, v35
	v_mul_f32_e32 v35, 0xbfb8aa3b, v35
	v_exp_f32_e32 v136, v132
	v_max_f32_e32 v132, 0xc1f00000, v133
	v_mul_f32_e32 v132, 0xbfb8aa3b, v132
	v_cvt_f32_f16_e32 v133, v134
	v_exp_f32_e32 v137, v132
	v_cvt_f32_f16_sdwa v132, v134 dst_sel:DWORD dst_unused:UNUSED_PAD src0_sel:WORD_1
	v_exp_f32_e32 v35, v35
	v_max_f32_e32 v133, 0xc1f00000, v133
	v_mul_f32_e32 v133, 0xbfb8aa3b, v133
	v_max_f32_e32 v132, 0xc1f00000, v132
	v_mul_f32_e32 v132, 0xbfb8aa3b, v132
	v_exp_f32_e32 v138, v133
	v_cvt_f32_f16_e32 v133, v135
	v_exp_f32_e32 v139, v132
	v_cvt_f32_f16_sdwa v132, v135 dst_sel:DWORD dst_unused:UNUSED_PAD src0_sel:WORD_1
	v_max_f32_e32 v32, 0xc1f00000, v32
	v_mul_f32_e32 v32, 0xbfb8aa3b, v32
	v_exp_f32_e32 v32, v32
	v_max_f32_e32 v133, 0xc1f00000, v133
	v_max_f32_e32 v132, 0xc1f00000, v132
	v_mul_f32_e32 v133, 0xbfb8aa3b, v133
	v_mul_f32_e32 v132, 0xbfb8aa3b, v132
	v_add_f32_e32 v35, 1.0, v35
	v_exp_f32_e32 v142, v133
	v_exp_f32_e32 v143, v132
	v_rcp_f32_e32 v132, v35
	v_add_f32_e32 v35, 1.0, v136
	v_rcp_f32_e32 v133, v35
	v_add_f32_e32 v35, 1.0, v137
	v_add_f32_e32 v32, 1.0, v32
	v_rcp_f32_e32 v134, v35
	v_add_f32_e32 v35, 1.0, v138
	v_rcp_f32_e32 v32, v32
	v_rcp_f32_e32 v135, v35
	v_add_f32_e32 v35, 1.0, v139
	v_rcp_f32_e32 v136, v35
	v_add_f32_e32 v35, 1.0, v142
	v_rcp_f32_e32 v137, v35
	v_mov_b32_e32 v138, v73
	v_mov_b32_e32 v139, v74
	v_pk_mul_f32 v[132:133], v[138:139], v[132:133]
	v_pk_mov_b32 v[138:139], v[74:75], v[68:69] op_sel:[1,0]
	v_add_f32_e32 v35, 1.0, v143
	v_fma_mixlo_f16 v32, v72, v32, 0
	v_cvt_pk_f16_f32 v133, v132, v133
	v_pk_mul_f32 v[134:135], v[138:139], v[134:135]
	v_rcp_f32_e32 v35, v35
	v_pack_b32_f16 v132, v32, v133
	v_cvt_pk_f16_f32 v32, v134, v135
	v_mov_b32_e32 v134, v69
	v_mov_b32_e32 v135, v70
	v_pk_mul_f32 v[134:135], v[134:135], v[136:137]
	v_alignbit_b32 v133, v32, v133, 16
	v_cvt_pk_f16_f32 v135, v134, v135
	v_alignbit_b32 v134, v135, v32, 16
	v_lshrrev_b32_e32 v135, 16, v135
	v_fma_mixhi_f16 v135, v71, v35, 0
	global_store_dwordx4 v[140:141], v[132:135], off offset:256
	v_add_u32_e32 v184, 0x80, v34
	s_nop 0
	v_mad_i64_i32 v[132:133], s[12:13], v184, s33, v[168:169]
	v_lshl_add_u64 v[132:133], v[132:133], 0, v[166:167]
	v_add_u32_e32 v174, 0x90, v34
	v_lshl_add_u64 v[134:135], v[132:133], 0, s[16:17]
	v_mad_i64_i32 v[136:137], s[12:13], v174, s33, v[168:169]
	v_add_co_u32_e32 v132, vcc, s1, v132
	v_lshl_add_u64 v[136:137], v[136:137], 0, v[166:167]
	v_add_u32_e32 v172, 0xa0, v34
	v_addc_co_u32_e32 v133, vcc, 0, v133, vcc
	v_lshl_add_u64 v[138:139], v[136:137], 0, s[16:17]
	v_mad_i64_i32 v[140:141], s[12:13], v172, s33, v[168:169]
	v_add_co_u32_e32 v136, vcc, s1, v136
	v_lshl_add_u64 v[140:141], v[140:141], 0, v[166:167]
	v_add_u32_e32 v170, 0xb0, v34
	v_addc_co_u32_e32 v137, vcc, 0, v137, vcc
	v_mad_i64_i32 v[144:145], s[12:13], v170, s33, v[168:169]
	global_load_dwordx4 v[176:179], v[132:133], off offset:2048
	global_load_dwordx4 v[152:155], v[136:137], off offset:2048
	global_load_dwordx4 v[180:183], v[134:135], off offset:256
	global_load_dwordx4 v[148:151], v[138:139], off offset:256
	v_add_co_u32_e32 v132, vcc, s1, v140
	v_lshl_add_u64 v[144:145], v[144:145], 0, v[166:167]
	s_nop 0
	v_addc_co_u32_e32 v133, vcc, 0, v141, vcc
	v_add_co_u32_e32 v134, vcc, s1, v144
	v_lshl_add_u64 v[142:143], v[140:141], 0, s[16:17]
	s_nop 0
	v_addc_co_u32_e32 v135, vcc, 0, v145, vcc
	v_lshl_add_u64 v[168:169], v[144:145], 0, s[16:17]
	global_load_dwordx4 v[144:147], v[132:133], off offset:2048
	global_load_dwordx4 v[136:139], v[134:135], off offset:2048
	s_nop 0
	global_load_dwordx4 v[140:143], v[142:143], off offset:256
	s_nop 0
	global_load_dwordx4 v[132:135], v[168:169], off offset:256
	v_ashrrev_i32_e32 v185, 31, v184
	v_ashrrev_i32_e32 v175, 31, v174
	v_ashrrev_i32_e32 v173, 31, v172
	v_ashrrev_i32_e32 v171, 31, v170
	s_waitcnt vmcnt(0)
	v_cvt_f32_f16_e32 v32, v176
	v_cvt_f32_f16_sdwa v35, v176 dst_sel:DWORD dst_unused:UNUSED_PAD src0_sel:WORD_1
	v_cvt_f32_f16_sdwa v176, v178 dst_sel:DWORD dst_unused:UNUSED_PAD src0_sel:WORD_1
	v_cvt_f32_f16_e32 v161, v177
	v_cvt_f32_f16_sdwa v163, v177 dst_sel:DWORD dst_unused:UNUSED_PAD src0_sel:WORD_1
	v_cvt_f32_f16_e32 v165, v178
	v_max_f32_e32 v176, 0xc1f00000, v176
	v_max_f32_e32 v35, 0xc1f00000, v35
	v_mul_f32_e32 v176, 0xbfb8aa3b, v176
	v_lshlrev_b64 v[168:169], 11, v[184:185]
	v_mul_f32_e32 v35, 0xbfb8aa3b, v35
	v_max_f32_e32 v161, 0xc1f00000, v161
	v_cvt_f32_f16_e32 v177, v179
	v_exp_f32_e32 v184, v176
	v_cvt_f32_f16_sdwa v176, v179 dst_sel:DWORD dst_unused:UNUSED_PAD src0_sel:WORD_1
	v_exp_f32_e32 v35, v35
	v_mul_f32_e32 v161, 0xbfb8aa3b, v161
	v_max_f32_e32 v163, 0xc1f00000, v163
	v_max_f32_e32 v32, 0xc1f00000, v32
	v_exp_f32_e32 v161, v161
	v_mul_f32_e32 v163, 0xbfb8aa3b, v163
	v_max_f32_e32 v165, 0xc1f00000, v165
	v_mul_f32_e32 v32, 0xbfb8aa3b, v32
	v_exp_f32_e32 v163, v163
	v_mul_f32_e32 v165, 0xbfb8aa3b, v165
	v_exp_f32_e32 v32, v32
	v_exp_f32_e32 v165, v165
	v_max_f32_e32 v177, 0xc1f00000, v177
	v_max_f32_e32 v176, 0xc1f00000, v176
	v_mul_f32_e32 v177, 0xbfb8aa3b, v177
	v_mul_f32_e32 v176, 0xbfb8aa3b, v176
	v_add_f32_e32 v35, 1.0, v35
	v_exp_f32_e32 v185, v177
	v_exp_f32_e32 v186, v176
	v_rcp_f32_e32 v176, v35
	v_add_f32_e32 v35, 1.0, v161
	v_rcp_f32_e32 v177, v35
	v_add_f32_e32 v35, 1.0, v163
	v_add_f32_e32 v32, 1.0, v32
	v_rcp_f32_e32 v178, v35
	v_add_f32_e32 v35, 1.0, v165
	v_rcp_f32_e32 v32, v32
	v_rcp_f32_e32 v179, v35
	v_add_f32_e32 v35, 1.0, v184
	v_rcp_f32_e32 v184, v35
	v_add_f32_e32 v35, 1.0, v185
	v_rcp_f32_e32 v185, v35
	v_add_f32_e32 v35, 1.0, v186
	v_mov_b32_e32 v186, v65
	v_mov_b32_e32 v187, v66
	v_pk_mul_f32 v[176:177], v[186:187], v[176:177]
	v_pk_mov_b32 v[186:187], v[66:67], v[60:61] op_sel:[1,0]
	v_fma_mixlo_f16 v32, v64, v32, 0
	v_cvt_pk_f16_f32 v161, v176, v177
	v_pk_mul_f32 v[178:179], v[186:187], v[178:179]
	v_rcp_f32_e32 v35, v35
	v_pack_b32_f16 v176, v32, v161
	v_cvt_pk_f16_f32 v32, v178, v179
	v_mov_b32_e32 v178, v61
	v_mov_b32_e32 v179, v62
	v_pk_mul_f32 v[178:179], v[178:179], v[184:185]
	v_alignbit_b32 v177, v32, v161, 16
	v_cvt_pk_f16_f32 v161, v178, v179
	v_lshrrev_b32_e32 v179, 16, v161
	v_lshl_add_u64 v[168:169], s[14:15], 0, v[168:169]
	v_alignbit_b32 v178, v161, v32, 16
	v_fma_mixhi_f16 v179, v63, v35, 0
	v_lshl_add_u64 v[168:169], v[168:169], 0, v[166:167]
	global_store_dwordx4 v[168:169], v[176:179], off
	v_cvt_f32_f16_sdwa v35, v180 dst_sel:DWORD dst_unused:UNUSED_PAD src0_sel:WORD_1
	v_cvt_f32_f16_e32 v161, v181
	v_cvt_f32_f16_sdwa v176, v182 dst_sel:DWORD dst_unused:UNUSED_PAD src0_sel:WORD_1
	v_cvt_f32_f16_sdwa v163, v181 dst_sel:DWORD dst_unused:UNUSED_PAD src0_sel:WORD_1
	v_cvt_f32_f16_e32 v32, v180
	v_cvt_f32_f16_e32 v165, v182
	v_max_f32_e32 v176, 0xc1f00000, v176
	v_max_f32_e32 v35, 0xc1f00000, v35
	v_mul_f32_e32 v176, 0xbfb8aa3b, v176
	v_mul_f32_e32 v35, 0xbfb8aa3b, v35
	v_max_f32_e32 v161, 0xc1f00000, v161
	v_cvt_f32_f16_e32 v177, v183
	v_exp_f32_e32 v180, v176
	v_cvt_f32_f16_sdwa v176, v183 dst_sel:DWORD dst_unused:UNUSED_PAD src0_sel:WORD_1
	v_exp_f32_e32 v35, v35
	v_mul_f32_e32 v161, 0xbfb8aa3b, v161
	v_max_f32_e32 v163, 0xc1f00000, v163
	v_max_f32_e32 v32, 0xc1f00000, v32
	v_exp_f32_e32 v161, v161
	v_mul_f32_e32 v163, 0xbfb8aa3b, v163
	v_max_f32_e32 v165, 0xc1f00000, v165
	v_mul_f32_e32 v32, 0xbfb8aa3b, v32
	v_exp_f32_e32 v163, v163
	v_mul_f32_e32 v165, 0xbfb8aa3b, v165
	v_exp_f32_e32 v32, v32
	v_exp_f32_e32 v165, v165
	v_max_f32_e32 v177, 0xc1f00000, v177
	v_max_f32_e32 v176, 0xc1f00000, v176
	v_mul_f32_e32 v177, 0xbfb8aa3b, v177
	v_mul_f32_e32 v176, 0xbfb8aa3b, v176
	v_add_f32_e32 v35, 1.0, v35
	v_exp_f32_e32 v181, v177
	v_exp_f32_e32 v182, v176
	v_rcp_f32_e32 v176, v35
	v_add_f32_e32 v35, 1.0, v161
	v_rcp_f32_e32 v177, v35
	v_add_f32_e32 v35, 1.0, v163
	v_add_f32_e32 v32, 1.0, v32
	v_rcp_f32_e32 v178, v35
	v_add_f32_e32 v35, 1.0, v165
	v_rcp_f32_e32 v32, v32
	v_rcp_f32_e32 v179, v35
	v_add_f32_e32 v35, 1.0, v180
	v_rcp_f32_e32 v180, v35
	v_add_f32_e32 v35, 1.0, v181
	v_rcp_f32_e32 v181, v35
	v_add_f32_e32 v35, 1.0, v182
	v_mov_b32_e32 v182, v29
	v_mov_b32_e32 v183, v30
	v_pk_mul_f32 v[176:177], v[182:183], v[176:177]
	v_pk_mov_b32 v[182:183], v[30:31], v[24:25] op_sel:[1,0]
	v_fma_mixlo_f16 v32, v28, v32, 0
	v_cvt_pk_f16_f32 v161, v176, v177
	v_pk_mul_f32 v[178:179], v[182:183], v[178:179]
	v_rcp_f32_e32 v35, v35
	v_pack_b32_f16 v176, v32, v161
	v_cvt_pk_f16_f32 v32, v178, v179
	v_mov_b32_e32 v178, v25
	v_mov_b32_e32 v179, v26
	v_pk_mul_f32 v[178:179], v[178:179], v[180:181]
	v_alignbit_b32 v177, v32, v161, 16
	v_cvt_pk_f16_f32 v161, v178, v179
	v_lshrrev_b32_e32 v179, 16, v161
	v_alignbit_b32 v178, v161, v32, 16
	v_fma_mixhi_f16 v179, v27, v35, 0
	v_cvt_f32_f16_e32 v32, v152
	v_cvt_f32_f16_sdwa v35, v152 dst_sel:DWORD dst_unused:UNUSED_PAD src0_sel:WORD_1
	v_cvt_f32_f16_e32 v152, v153
	v_cvt_f32_f16_sdwa v153, v153 dst_sel:DWORD dst_unused:UNUSED_PAD src0_sel:WORD_1
	global_store_dwordx4 v[168:169], v[176:179], off offset:256
	v_max_f32_e32 v35, 0xc1f00000, v35
	v_max_f32_e32 v152, 0xc1f00000, v152
	v_mul_f32_e32 v152, 0xbfb8aa3b, v152
	v_exp_f32_e32 v161, v152
	v_max_f32_e32 v152, 0xc1f00000, v153
	v_mul_f32_e32 v152, 0xbfb8aa3b, v152
	v_cvt_f32_f16_e32 v153, v154
	v_exp_f32_e32 v163, v152
	v_cvt_f32_f16_sdwa v152, v154 dst_sel:DWORD dst_unused:UNUSED_PAD src0_sel:WORD_1
	v_lshlrev_b64 v[168:169], 11, v[174:175]
	v_max_f32_e32 v153, 0xc1f00000, v153
	v_mul_f32_e32 v153, 0xbfb8aa3b, v153
	v_max_f32_e32 v152, 0xc1f00000, v152
	v_mul_f32_e32 v152, 0xbfb8aa3b, v152
	v_mul_f32_e32 v35, 0xbfb8aa3b, v35
	v_exp_f32_e32 v165, v153
	v_cvt_f32_f16_e32 v153, v155
	v_exp_f32_e32 v174, v152
	v_cvt_f32_f16_sdwa v152, v155 dst_sel:DWORD dst_unused:UNUSED_PAD src0_sel:WORD_1
	v_exp_f32_e32 v35, v35
	v_max_f32_e32 v32, 0xc1f00000, v32
	v_mul_f32_e32 v32, 0xbfb8aa3b, v32
	v_exp_f32_e32 v32, v32
	v_max_f32_e32 v153, 0xc1f00000, v153
	v_max_f32_e32 v152, 0xc1f00000, v152
	v_mul_f32_e32 v153, 0xbfb8aa3b, v153
	v_mul_f32_e32 v152, 0xbfb8aa3b, v152
	v_add_f32_e32 v35, 1.0, v35
	v_exp_f32_e32 v175, v153
	v_exp_f32_e32 v176, v152
	v_rcp_f32_e32 v152, v35
	v_add_f32_e32 v35, 1.0, v161
	v_rcp_f32_e32 v153, v35
	v_add_f32_e32 v35, 1.0, v163
	v_add_f32_e32 v32, 1.0, v32
	v_rcp_f32_e32 v154, v35
	v_add_f32_e32 v35, 1.0, v165
	v_rcp_f32_e32 v32, v32
	v_rcp_f32_e32 v155, v35
	v_add_f32_e32 v35, 1.0, v174
	v_rcp_f32_e32 v174, v35
	v_add_f32_e32 v35, 1.0, v175
	v_rcp_f32_e32 v175, v35
	v_add_f32_e32 v35, 1.0, v176
	v_mov_b32_e32 v176, v57
	v_mov_b32_e32 v177, v58
	v_pk_mul_f32 v[152:153], v[176:177], v[152:153]
	v_pk_mov_b32 v[176:177], v[58:59], v[52:53] op_sel:[1,0]
	v_fma_mixlo_f16 v32, v56, v32, 0
	v_cvt_pk_f16_f32 v153, v152, v153
	v_pk_mul_f32 v[154:155], v[176:177], v[154:155]
	v_rcp_f32_e32 v35, v35
	v_pack_b32_f16 v152, v32, v153
	v_cvt_pk_f16_f32 v32, v154, v155
	v_mov_b32_e32 v154, v53
	v_mov_b32_e32 v155, v54
	v_pk_mul_f32 v[154:155], v[154:155], v[174:175]
	v_alignbit_b32 v153, v32, v153, 16
	v_cvt_pk_f16_f32 v155, v154, v155
	v_alignbit_b32 v154, v155, v32, 16
	v_lshrrev_b32_e32 v155, 16, v155
	v_fma_mixhi_f16 v155, v55, v35, 0
	v_cvt_f32_f16_e32 v32, v148
	v_cvt_f32_f16_sdwa v35, v148 dst_sel:DWORD dst_unused:UNUSED_PAD src0_sel:WORD_1
	v_cvt_f32_f16_e32 v148, v149
	v_cvt_f32_f16_sdwa v149, v149 dst_sel:DWORD dst_unused:UNUSED_PAD src0_sel:WORD_1
	v_lshl_add_u64 v[168:169], s[14:15], 0, v[168:169]
	v_lshl_add_u64 v[168:169], v[168:169], 0, v[166:167]
	v_max_f32_e32 v148, 0xc1f00000, v148
	v_mul_f32_e32 v148, 0xbfb8aa3b, v148
	global_store_dwordx4 v[168:169], v[152:155], off
	v_max_f32_e32 v35, 0xc1f00000, v35
	v_mul_f32_e32 v35, 0xbfb8aa3b, v35
	v_exp_f32_e32 v152, v148
	v_max_f32_e32 v148, 0xc1f00000, v149
	v_mul_f32_e32 v148, 0xbfb8aa3b, v148
	v_cvt_f32_f16_e32 v149, v150
	v_exp_f32_e32 v153, v148
	v_cvt_f32_f16_sdwa v148, v150 dst_sel:DWORD dst_unused:UNUSED_PAD src0_sel:WORD_1
	v_exp_f32_e32 v35, v35
	v_max_f32_e32 v149, 0xc1f00000, v149
	v_mul_f32_e32 v149, 0xbfb8aa3b, v149
	v_max_f32_e32 v148, 0xc1f00000, v148
	v_mul_f32_e32 v148, 0xbfb8aa3b, v148
	v_exp_f32_e32 v154, v149
	v_cvt_f32_f16_e32 v149, v151
	v_exp_f32_e32 v155, v148
	v_cvt_f32_f16_sdwa v148, v151 dst_sel:DWORD dst_unused:UNUSED_PAD src0_sel:WORD_1
	v_max_f32_e32 v32, 0xc1f00000, v32
	v_mul_f32_e32 v32, 0xbfb8aa3b, v32
	v_exp_f32_e32 v32, v32
	v_max_f32_e32 v149, 0xc1f00000, v149
	v_max_f32_e32 v148, 0xc1f00000, v148
	v_mul_f32_e32 v149, 0xbfb8aa3b, v149
	v_mul_f32_e32 v148, 0xbfb8aa3b, v148
	v_add_f32_e32 v35, 1.0, v35
	v_exp_f32_e32 v161, v149
	v_exp_f32_e32 v163, v148
	v_rcp_f32_e32 v148, v35
	v_add_f32_e32 v35, 1.0, v152
	v_rcp_f32_e32 v149, v35
	v_add_f32_e32 v35, 1.0, v153
	v_add_f32_e32 v32, 1.0, v32
	v_rcp_f32_e32 v150, v35
	v_add_f32_e32 v35, 1.0, v154
	v_rcp_f32_e32 v32, v32
	v_rcp_f32_e32 v151, v35
	v_add_f32_e32 v35, 1.0, v155
	v_rcp_f32_e32 v152, v35
	v_add_f32_e32 v35, 1.0, v161
	v_rcp_f32_e32 v153, v35
	v_mov_b32_e32 v154, v21
	v_mov_b32_e32 v155, v22
	v_pk_mul_f32 v[148:149], v[154:155], v[148:149]
	v_pk_mov_b32 v[154:155], v[22:23], v[16:17] op_sel:[1,0]
	v_add_f32_e32 v35, 1.0, v163
	v_fma_mixlo_f16 v32, v20, v32, 0
	v_cvt_pk_f16_f32 v149, v148, v149
	v_pk_mul_f32 v[150:151], v[154:155], v[150:151]
	v_rcp_f32_e32 v35, v35
	v_pack_b32_f16 v148, v32, v149
	v_cvt_pk_f16_f32 v32, v150, v151
	v_mov_b32_e32 v150, v17
	v_mov_b32_e32 v151, v18
	v_pk_mul_f32 v[150:151], v[150:151], v[152:153]
	v_alignbit_b32 v149, v32, v149, 16
	v_cvt_pk_f16_f32 v151, v150, v151
	v_alignbit_b32 v150, v151, v32, 16
	v_lshrrev_b32_e32 v151, 16, v151
	v_fma_mixhi_f16 v151, v19, v35, 0
	v_cvt_f32_f16_e32 v32, v144
	v_cvt_f32_f16_sdwa v35, v144 dst_sel:DWORD dst_unused:UNUSED_PAD src0_sel:WORD_1
	v_cvt_f32_f16_e32 v144, v145
	v_cvt_f32_f16_sdwa v145, v145 dst_sel:DWORD dst_unused:UNUSED_PAD src0_sel:WORD_1
	global_store_dwordx4 v[168:169], v[148:151], off offset:256
	v_max_f32_e32 v35, 0xc1f00000, v35
	v_max_f32_e32 v144, 0xc1f00000, v144
	v_mul_f32_e32 v144, 0xbfb8aa3b, v144
	v_exp_f32_e32 v150, v144
	v_max_f32_e32 v144, 0xc1f00000, v145
	v_mul_f32_e32 v144, 0xbfb8aa3b, v144
	v_cvt_f32_f16_e32 v145, v146
	v_exp_f32_e32 v151, v144
	v_cvt_f32_f16_sdwa v144, v146 dst_sel:DWORD dst_unused:UNUSED_PAD src0_sel:WORD_1
	v_mul_f32_e32 v35, 0xbfb8aa3b, v35
	v_max_f32_e32 v145, 0xc1f00000, v145
	v_mul_f32_e32 v145, 0xbfb8aa3b, v145
	v_max_f32_e32 v144, 0xc1f00000, v144
	v_mul_f32_e32 v144, 0xbfb8aa3b, v144
	v_exp_f32_e32 v152, v145
	v_cvt_f32_f16_e32 v145, v147
	v_exp_f32_e32 v153, v144
	v_cvt_f32_f16_sdwa v144, v147 dst_sel:DWORD dst_unused:UNUSED_PAD src0_sel:WORD_1
	v_exp_f32_e32 v35, v35
	v_max_f32_e32 v32, 0xc1f00000, v32
	v_mul_f32_e32 v32, 0xbfb8aa3b, v32
	v_exp_f32_e32 v32, v32
	v_max_f32_e32 v145, 0xc1f00000, v145
	v_max_f32_e32 v144, 0xc1f00000, v144
	v_mul_f32_e32 v145, 0xbfb8aa3b, v145
	v_mul_f32_e32 v144, 0xbfb8aa3b, v144
	v_add_f32_e32 v35, 1.0, v35
	v_exp_f32_e32 v154, v145
	v_exp_f32_e32 v155, v144
	v_rcp_f32_e32 v144, v35
	v_add_f32_e32 v35, 1.0, v150
	v_rcp_f32_e32 v145, v35
	v_add_f32_e32 v35, 1.0, v151
	v_add_f32_e32 v32, 1.0, v32
	v_rcp_f32_e32 v146, v35
	v_add_f32_e32 v35, 1.0, v152
	v_rcp_f32_e32 v32, v32
	v_rcp_f32_e32 v147, v35
	v_add_f32_e32 v35, 1.0, v153
	v_rcp_f32_e32 v150, v35
	v_add_f32_e32 v35, 1.0, v154
	v_rcp_f32_e32 v151, v35
	v_mov_b32_e32 v152, v49
	v_mov_b32_e32 v153, v50
	v_pk_mul_f32 v[144:145], v[152:153], v[144:145]
	v_pk_mov_b32 v[152:153], v[50:51], v[44:45] op_sel:[1,0]
	v_add_f32_e32 v35, 1.0, v155
	v_fma_mixlo_f16 v32, v48, v32, 0
	v_cvt_pk_f16_f32 v145, v144, v145
	v_pk_mul_f32 v[146:147], v[152:153], v[146:147]
	v_rcp_f32_e32 v35, v35
	v_pack_b32_f16 v144, v32, v145
	v_cvt_pk_f16_f32 v32, v146, v147
	v_mov_b32_e32 v146, v45
	v_mov_b32_e32 v147, v46
	v_pk_mul_f32 v[146:147], v[146:147], v[150:151]
	v_alignbit_b32 v145, v32, v145, 16
	v_cvt_pk_f16_f32 v147, v146, v147
	v_alignbit_b32 v146, v147, v32, 16
	v_lshrrev_b32_e32 v147, 16, v147
	v_fma_mixhi_f16 v147, v47, v35, 0
	v_cvt_f32_f16_e32 v32, v140
	v_cvt_f32_f16_sdwa v35, v140 dst_sel:DWORD dst_unused:UNUSED_PAD src0_sel:WORD_1
	v_cvt_f32_f16_e32 v140, v141
	v_cvt_f32_f16_sdwa v141, v141 dst_sel:DWORD dst_unused:UNUSED_PAD src0_sel:WORD_1
	v_lshlrev_b64 v[148:149], 11, v[172:173]
	v_lshl_add_u64 v[148:149], s[14:15], 0, v[148:149]
	v_max_f32_e32 v140, 0xc1f00000, v140
	v_lshl_add_u64 v[148:149], v[148:149], 0, v[166:167]
	v_mul_f32_e32 v140, 0xbfb8aa3b, v140
	global_store_dwordx4 v[148:149], v[144:147], off
	v_max_f32_e32 v35, 0xc1f00000, v35
	v_mul_f32_e32 v35, 0xbfb8aa3b, v35
	v_exp_f32_e32 v144, v140
	v_max_f32_e32 v140, 0xc1f00000, v141
	v_mul_f32_e32 v140, 0xbfb8aa3b, v140
	v_cvt_f32_f16_e32 v141, v142
	v_exp_f32_e32 v145, v140
	v_cvt_f32_f16_sdwa v140, v142 dst_sel:DWORD dst_unused:UNUSED_PAD src0_sel:WORD_1
	v_exp_f32_e32 v35, v35
	v_max_f32_e32 v141, 0xc1f00000, v141
	v_mul_f32_e32 v141, 0xbfb8aa3b, v141
	v_max_f32_e32 v140, 0xc1f00000, v140
	v_mul_f32_e32 v140, 0xbfb8aa3b, v140
	v_exp_f32_e32 v146, v141
	v_cvt_f32_f16_e32 v141, v143
	v_exp_f32_e32 v147, v140
	v_cvt_f32_f16_sdwa v140, v143 dst_sel:DWORD dst_unused:UNUSED_PAD src0_sel:WORD_1
	v_max_f32_e32 v32, 0xc1f00000, v32
	v_mul_f32_e32 v32, 0xbfb8aa3b, v32
	v_exp_f32_e32 v32, v32
	v_max_f32_e32 v141, 0xc1f00000, v141
	v_max_f32_e32 v140, 0xc1f00000, v140
	v_mul_f32_e32 v141, 0xbfb8aa3b, v141
	v_mul_f32_e32 v140, 0xbfb8aa3b, v140
	v_add_f32_e32 v35, 1.0, v35
	v_exp_f32_e32 v150, v141
	v_exp_f32_e32 v151, v140
	v_rcp_f32_e32 v140, v35
	v_add_f32_e32 v35, 1.0, v144
	v_rcp_f32_e32 v141, v35
	v_add_f32_e32 v35, 1.0, v145
	v_add_f32_e32 v32, 1.0, v32
	v_rcp_f32_e32 v142, v35
	v_add_f32_e32 v35, 1.0, v146
	v_rcp_f32_e32 v32, v32
	v_rcp_f32_e32 v143, v35
	v_add_f32_e32 v35, 1.0, v147
	v_rcp_f32_e32 v144, v35
	v_add_f32_e32 v35, 1.0, v150
	v_rcp_f32_e32 v145, v35
	v_mov_b32_e32 v146, v13
	v_mov_b32_e32 v147, v14
	v_pk_mul_f32 v[140:141], v[146:147], v[140:141]
	v_pk_mov_b32 v[146:147], v[14:15], v[8:9] op_sel:[1,0]
	v_add_f32_e32 v35, 1.0, v151
	v_fma_mixlo_f16 v32, v12, v32, 0
	v_cvt_pk_f16_f32 v141, v140, v141
	v_pk_mul_f32 v[142:143], v[146:147], v[142:143]
	v_rcp_f32_e32 v35, v35
	v_pack_b32_f16 v140, v32, v141
	v_cvt_pk_f16_f32 v32, v142, v143
	v_mov_b32_e32 v142, v9
	v_mov_b32_e32 v143, v10
	v_pk_mul_f32 v[142:143], v[142:143], v[144:145]
	v_alignbit_b32 v141, v32, v141, 16
	v_cvt_pk_f16_f32 v143, v142, v143
	v_alignbit_b32 v142, v143, v32, 16
	v_lshrrev_b32_e32 v143, 16, v143
	v_fma_mixhi_f16 v143, v11, v35, 0
	v_cvt_f32_f16_e32 v32, v136
	v_cvt_f32_f16_sdwa v35, v136 dst_sel:DWORD dst_unused:UNUSED_PAD src0_sel:WORD_1
	v_cvt_f32_f16_e32 v136, v137
	v_cvt_f32_f16_sdwa v137, v137 dst_sel:DWORD dst_unused:UNUSED_PAD src0_sel:WORD_1
	global_store_dwordx4 v[148:149], v[140:143], off offset:256
	v_max_f32_e32 v35, 0xc1f00000, v35
	v_max_f32_e32 v136, 0xc1f00000, v136
	v_mul_f32_e32 v136, 0xbfb8aa3b, v136
	v_exp_f32_e32 v142, v136
	v_max_f32_e32 v136, 0xc1f00000, v137
	v_mul_f32_e32 v136, 0xbfb8aa3b, v136
	v_cvt_f32_f16_e32 v137, v138
	v_exp_f32_e32 v143, v136
	v_cvt_f32_f16_sdwa v136, v138 dst_sel:DWORD dst_unused:UNUSED_PAD src0_sel:WORD_1
	v_mul_f32_e32 v35, 0xbfb8aa3b, v35
	v_max_f32_e32 v137, 0xc1f00000, v137
	v_mul_f32_e32 v137, 0xbfb8aa3b, v137
	v_max_f32_e32 v136, 0xc1f00000, v136
	v_mul_f32_e32 v136, 0xbfb8aa3b, v136
	v_exp_f32_e32 v144, v137
	v_cvt_f32_f16_e32 v137, v139
	v_exp_f32_e32 v145, v136
	v_cvt_f32_f16_sdwa v136, v139 dst_sel:DWORD dst_unused:UNUSED_PAD src0_sel:WORD_1
	v_exp_f32_e32 v35, v35
	v_max_f32_e32 v32, 0xc1f00000, v32
	v_mul_f32_e32 v32, 0xbfb8aa3b, v32
	v_exp_f32_e32 v32, v32
	v_max_f32_e32 v137, 0xc1f00000, v137
	v_max_f32_e32 v136, 0xc1f00000, v136
	v_mul_f32_e32 v137, 0xbfb8aa3b, v137
	v_mul_f32_e32 v136, 0xbfb8aa3b, v136
	v_add_f32_e32 v35, 1.0, v35
	v_exp_f32_e32 v146, v137
	v_exp_f32_e32 v147, v136
	v_rcp_f32_e32 v136, v35
	v_add_f32_e32 v35, 1.0, v142
	v_rcp_f32_e32 v137, v35
	v_add_f32_e32 v35, 1.0, v143
	v_add_f32_e32 v32, 1.0, v32
	v_rcp_f32_e32 v138, v35
	v_add_f32_e32 v35, 1.0, v144
	v_rcp_f32_e32 v32, v32
	v_rcp_f32_e32 v139, v35
	v_add_f32_e32 v35, 1.0, v145
	v_rcp_f32_e32 v142, v35
	v_add_f32_e32 v35, 1.0, v146
	v_rcp_f32_e32 v143, v35
	v_mov_b32_e32 v144, v41
	v_mov_b32_e32 v145, v42
	v_pk_mul_f32 v[136:137], v[144:145], v[136:137]
	v_pk_mov_b32 v[144:145], v[42:43], v[36:37] op_sel:[1,0]
	v_add_f32_e32 v35, 1.0, v147
	v_fma_mixlo_f16 v32, v40, v32, 0
	v_cvt_pk_f16_f32 v137, v136, v137
	v_pk_mul_f32 v[138:139], v[144:145], v[138:139]
	v_rcp_f32_e32 v35, v35
	v_pack_b32_f16 v136, v32, v137
	v_cvt_pk_f16_f32 v32, v138, v139
	v_mov_b32_e32 v138, v37
	v_mov_b32_e32 v139, v38
	v_pk_mul_f32 v[138:139], v[138:139], v[142:143]
	v_alignbit_b32 v137, v32, v137, 16
	v_cvt_pk_f16_f32 v139, v138, v139
	v_alignbit_b32 v138, v139, v32, 16
	v_lshrrev_b32_e32 v139, 16, v139
	v_fma_mixhi_f16 v139, v39, v35, 0
	v_cvt_f32_f16_e32 v32, v132
	v_cvt_f32_f16_sdwa v35, v132 dst_sel:DWORD dst_unused:UNUSED_PAD src0_sel:WORD_1
	v_cvt_f32_f16_e32 v132, v133
	v_cvt_f32_f16_sdwa v133, v133 dst_sel:DWORD dst_unused:UNUSED_PAD src0_sel:WORD_1
	v_lshlrev_b64 v[140:141], 11, v[170:171]
	v_lshl_add_u64 v[140:141], s[14:15], 0, v[140:141]
	v_max_f32_e32 v132, 0xc1f00000, v132
	v_lshl_add_u64 v[140:141], v[140:141], 0, v[166:167]
	v_mul_f32_e32 v132, 0xbfb8aa3b, v132
	global_store_dwordx4 v[140:141], v[136:139], off
	v_max_f32_e32 v35, 0xc1f00000, v35
	v_mul_f32_e32 v35, 0xbfb8aa3b, v35
	v_exp_f32_e32 v136, v132
	v_max_f32_e32 v132, 0xc1f00000, v133
	v_mul_f32_e32 v132, 0xbfb8aa3b, v132
	v_cvt_f32_f16_e32 v133, v134
	v_exp_f32_e32 v137, v132
	v_cvt_f32_f16_sdwa v132, v134 dst_sel:DWORD dst_unused:UNUSED_PAD src0_sel:WORD_1
	v_exp_f32_e32 v35, v35
	v_max_f32_e32 v133, 0xc1f00000, v133
	v_mul_f32_e32 v133, 0xbfb8aa3b, v133
	v_max_f32_e32 v132, 0xc1f00000, v132
	v_mul_f32_e32 v132, 0xbfb8aa3b, v132
	v_exp_f32_e32 v138, v133
	v_cvt_f32_f16_e32 v133, v135
	v_exp_f32_e32 v139, v132
	v_cvt_f32_f16_sdwa v132, v135 dst_sel:DWORD dst_unused:UNUSED_PAD src0_sel:WORD_1
	v_max_f32_e32 v32, 0xc1f00000, v32
	v_mul_f32_e32 v32, 0xbfb8aa3b, v32
	v_exp_f32_e32 v32, v32
	v_max_f32_e32 v133, 0xc1f00000, v133
	v_max_f32_e32 v132, 0xc1f00000, v132
	v_mul_f32_e32 v133, 0xbfb8aa3b, v133
	v_mul_f32_e32 v132, 0xbfb8aa3b, v132
	v_add_f32_e32 v35, 1.0, v35
	v_exp_f32_e32 v142, v133
	v_exp_f32_e32 v143, v132
	v_rcp_f32_e32 v132, v35
	v_add_f32_e32 v35, 1.0, v136
	v_rcp_f32_e32 v133, v35
	v_add_f32_e32 v35, 1.0, v137
	v_add_f32_e32 v32, 1.0, v32
	v_rcp_f32_e32 v134, v35
	v_add_f32_e32 v35, 1.0, v138
	v_rcp_f32_e32 v32, v32
	v_rcp_f32_e32 v135, v35
	v_add_f32_e32 v35, 1.0, v139
	v_rcp_f32_e32 v136, v35
	v_add_f32_e32 v35, 1.0, v142
	v_rcp_f32_e32 v137, v35
	v_mov_b32_e32 v138, v5
	v_mov_b32_e32 v139, v6
	v_pk_mul_f32 v[132:133], v[138:139], v[132:133]
	v_pk_mov_b32 v[138:139], v[6:7], v[0:1] op_sel:[1,0]
	v_add_f32_e32 v35, 1.0, v143
	v_fma_mixlo_f16 v32, v4, v32, 0
	v_cvt_pk_f16_f32 v133, v132, v133
	v_pk_mul_f32 v[134:135], v[138:139], v[134:135]
	v_rcp_f32_e32 v35, v35
	v_pack_b32_f16 v132, v32, v133
	v_cvt_pk_f16_f32 v32, v134, v135
	v_mov_b32_e32 v134, v1
	v_mov_b32_e32 v135, v2
	v_pk_mul_f32 v[134:135], v[134:135], v[136:137]
	v_alignbit_b32 v133, v32, v133, 16
	v_cvt_pk_f16_f32 v135, v134, v135
	v_alignbit_b32 v134, v135, v32, 16
	v_lshrrev_b32_e32 v135, 16, v135
	v_fma_mixhi_f16 v135, v3, v35, 0
	global_store_dwordx4 v[140:141], v[132:135], off offset:256
	s_cbranch_execnz .LBB0_944

.LBB0_958:
	s_add_u32 s12, s10, 0x100
	s_addc_u32 s13, s11, 0
	s_add_i32 s38, 0, 0x10000
	v_add_u32_e32 v142, s38, v196
	ds_read_b128 v[122:125], v142
	ds_read_b128 v[138:141], v142 offset:2048
	ds_read_b128 v[130:133], v142 offset:1024
	ds_read_b128 v[142:145], v142 offset:3072
	s_cmp_eq_u32 s37, 12
	s_cselect_b32 s17, s7, s13
	s_cselect_b32 s16, s6, s12
	s_cselect_b32 s15, s9, s36
	s_cselect_b32 s14, s8, s35
	v_lshl_add_u64 v[230:231], s[10:11], 0, v[188:189]
	s_add_i32 m0, s21, 0xc000
	ds_read_b128 v[146:149], v198
	ds_read_b128 v[192:195], v198 offset:2048
	ds_read_b128 v[204:207], v198 offset:4096
	ds_read_b128 v[212:215], v198 offset:6144
	ds_read_b128 v[150:153], v198 offset:1024
	ds_read_b128 v[200:203], v198 offset:3072
	ds_read_b128 v[208:211], v198 offset:5120
	ds_read_b128 v[216:219], v198 offset:7168
	global_load_lds_dwordx4 v[230:231], off
	v_lshl_add_u64 v[230:231], s[10:11], 0, v[190:191]
	s_add_i32 m0, s21, 0xe000
	s_nop 0
	global_load_lds_dwordx4 v[230:231], off
	s_waitcnt lgkmcnt(8)
	s_barrier
	s_waitcnt lgkmcnt(6)
	s_setprio 1
	v_mfma_f32_16x16x32_f16 v[134:137], v[122:125], v[146:149], v[134:137]
	v_mfma_f32_16x16x32_f16 v[126:129], v[138:141], v[146:149], v[126:129]
	v_mfma_f32_16x16x32_f16 v[110:113], v[122:125], v[192:195], v[110:113]
	v_mfma_f32_16x16x32_f16 v[106:109], v[138:141], v[192:195], v[106:109]
	s_waitcnt lgkmcnt(4)
	v_mfma_f32_16x16x32_f16 v[94:97], v[122:125], v[204:207], v[94:97]
	v_mfma_f32_16x16x32_f16 v[90:93], v[138:141], v[204:207], v[90:93]
	v_mfma_f32_16x16x32_f16 v[78:81], v[122:125], v[212:215], v[78:81]
	v_mfma_f32_16x16x32_f16 v[74:77], v[138:141], v[212:215], v[74:77]
	s_waitcnt lgkmcnt(2)
	v_mfma_f32_16x16x32_f16 v[134:137], v[130:133], v[150:153], v[134:137]
	v_mfma_f32_16x16x32_f16 v[126:129], v[142:145], v[150:153], v[126:129]
	v_mfma_f32_16x16x32_f16 v[110:113], v[130:133], v[200:203], v[110:113]
	v_mfma_f32_16x16x32_f16 v[106:109], v[142:145], v[200:203], v[106:109]
	s_waitcnt lgkmcnt(0)
	v_mfma_f32_16x16x32_f16 v[94:97], v[130:133], v[208:211], v[94:97]
	v_mfma_f32_16x16x32_f16 v[90:93], v[142:145], v[208:211], v[90:93]
	v_mfma_f32_16x16x32_f16 v[78:81], v[130:133], v[216:219], v[78:81]
	v_mfma_f32_16x16x32_f16 v[74:77], v[142:145], v[216:219], v[74:77]
	s_setprio 0
	s_barrier
	s_add_i32 s39, 0, 0x14000
	s_add_i32 s10, s38, s20
	v_add_u32_e32 v199, s39, v196
	v_lshl_add_u64 v[246:247], s[14:15], 0, v[32:33]
	s_mov_b32 m0, s10
	ds_read_b128 v[230:233], v199
	ds_read_b128 v[238:241], v199 offset:2048
	ds_read_b128 v[234:237], v199 offset:1024
	ds_read_b128 v[242:245], v199 offset:3072
	global_load_lds_dwordx4 v[246:247], off
	v_lshl_add_u64 v[248:249], s[14:15], 0, v[154:155]
	s_add_i32 m0, s10, 0x2000
	s_nop 0
	global_load_lds_dwordx4 v[248:249], off
	s_barrier
	s_waitcnt lgkmcnt(2)
	s_setprio 1
	v_mfma_f32_16x16x32_f16 v[118:121], v[230:233], v[146:149], v[118:121]
	v_mfma_f32_16x16x32_f16 v[114:117], v[238:241], v[146:149], v[114:117]
	v_mfma_f32_16x16x32_f16 v[102:105], v[230:233], v[192:195], v[102:105]
	v_mfma_f32_16x16x32_f16 v[98:101], v[238:241], v[192:195], v[98:101]
	v_mfma_f32_16x16x32_f16 v[86:89], v[230:233], v[204:207], v[86:89]
	v_mfma_f32_16x16x32_f16 v[82:85], v[238:241], v[204:207], v[82:85]
	v_mfma_f32_16x16x32_f16 v[70:73], v[230:233], v[212:215], v[70:73]
	v_mfma_f32_16x16x32_f16 v[66:69], v[238:241], v[212:215], v[66:69]
	s_waitcnt lgkmcnt(0)
	v_mfma_f32_16x16x32_f16 v[118:121], v[234:237], v[150:153], v[118:121]
	v_mfma_f32_16x16x32_f16 v[114:117], v[242:245], v[150:153], v[114:117]
	v_mfma_f32_16x16x32_f16 v[102:105], v[234:237], v[200:203], v[102:105]
	v_mfma_f32_16x16x32_f16 v[98:101], v[242:245], v[200:203], v[98:101]
	v_mfma_f32_16x16x32_f16 v[86:89], v[234:237], v[208:211], v[86:89]
	v_mfma_f32_16x16x32_f16 v[82:85], v[242:245], v[208:211], v[82:85]
	v_mfma_f32_16x16x32_f16 v[70:73], v[234:237], v[216:219], v[70:73]
	v_mfma_f32_16x16x32_f16 v[66:69], v[242:245], v[216:219], v[66:69]
	s_setprio 0
	s_mov_b32 m0, s21
	v_lshl_add_u64 v[228:229], s[16:17], 0, v[32:33]
	s_barrier
	ds_read_b128 v[146:149], v198 offset:16384
	ds_read_b128 v[192:195], v198 offset:18432
	ds_read_b128 v[204:207], v198 offset:20480
	ds_read_b128 v[212:215], v198 offset:22528
	ds_read_b128 v[150:153], v198 offset:17408
	ds_read_b128 v[200:203], v198 offset:19456
	ds_read_b128 v[208:211], v198 offset:21504
	ds_read_b128 v[216:219], v198 offset:23552
	global_load_lds_dwordx4 v[228:229], off
	v_lshl_add_u64 v[222:223], s[16:17], 0, v[154:155]
	s_mov_b32 m0, s22
	s_nop 0
	global_load_lds_dwordx4 v[222:223], off
	s_barrier
	s_waitcnt lgkmcnt(6)
	s_setprio 1
	v_mfma_f32_16x16x32_f16 v[62:65], v[122:125], v[146:149], v[62:65]
	v_mfma_f32_16x16x32_f16 v[58:61], v[138:141], v[146:149], v[58:61]
	v_mfma_f32_16x16x32_f16 v[46:49], v[122:125], v[192:195], v[46:49]
	v_mfma_f32_16x16x32_f16 v[42:45], v[138:141], v[192:195], v[42:45]
	s_waitcnt lgkmcnt(4)
	v_mfma_f32_16x16x32_f16 v[28:31], v[122:125], v[204:207], v[28:31]
	v_mfma_f32_16x16x32_f16 v[24:27], v[138:141], v[204:207], v[24:27]
	v_mfma_f32_16x16x32_f16 v[12:15], v[122:125], v[212:215], v[12:15]
	v_mfma_f32_16x16x32_f16 v[8:11], v[138:141], v[212:215], v[8:11]
	s_waitcnt lgkmcnt(2)
	v_mfma_f32_16x16x32_f16 v[62:65], v[130:133], v[150:153], v[62:65]
	v_mfma_f32_16x16x32_f16 v[58:61], v[142:145], v[150:153], v[58:61]
	v_mfma_f32_16x16x32_f16 v[46:49], v[130:133], v[200:203], v[46:49]
	v_mfma_f32_16x16x32_f16 v[42:45], v[142:145], v[200:203], v[42:45]
	s_waitcnt lgkmcnt(0)
	v_mfma_f32_16x16x32_f16 v[28:31], v[130:133], v[208:211], v[28:31]
	v_mfma_f32_16x16x32_f16 v[24:27], v[142:145], v[208:211], v[24:27]
	v_mfma_f32_16x16x32_f16 v[12:15], v[130:133], v[216:219], v[12:15]
	v_mfma_f32_16x16x32_f16 v[8:11], v[142:145], v[216:219], v[8:11]
	s_setprio 0
	s_barrier
	s_add_u32 s10, s14, 0x40000
	s_addc_u32 s11, s15, 0
	s_add_i32 s38, s39, s20
	v_lshl_add_u64 v[122:123], s[10:11], 0, v[32:33]
	s_mov_b32 m0, s38
	s_nop 0
	global_load_lds_dwordx4 v[122:123], off
	v_lshl_add_u64 v[122:123], s[10:11], 0, v[154:155]
	s_add_i32 m0, s38, 0x2000
	s_nop 0
	global_load_lds_dwordx4 v[122:123], off
	s_waitcnt vmcnt(6)
	s_barrier
	s_setprio 1
	v_mfma_f32_16x16x32_f16 v[54:57], v[230:233], v[146:149], v[54:57]
	v_mfma_f32_16x16x32_f16 v[50:53], v[238:241], v[146:149], v[50:53]
	v_mfma_f32_16x16x32_f16 v[38:41], v[230:233], v[192:195], v[38:41]
	v_mfma_f32_16x16x32_f16 v[34:37], v[238:241], v[192:195], v[34:37]
	v_mfma_f32_16x16x32_f16 v[20:23], v[230:233], v[204:207], v[20:23]
	v_mfma_f32_16x16x32_f16 v[16:19], v[238:241], v[204:207], v[16:19]
	v_mfma_f32_16x16x32_f16 v[4:7], v[230:233], v[212:215], v[4:7]
	v_mfma_f32_16x16x32_f16 v[0:3], v[238:241], v[212:215], v[0:3]
	v_mfma_f32_16x16x32_f16 v[54:57], v[234:237], v[150:153], v[54:57]
	v_mfma_f32_16x16x32_f16 v[50:53], v[242:245], v[150:153], v[50:53]
	v_mfma_f32_16x16x32_f16 v[38:41], v[234:237], v[200:203], v[38:41]
	v_mfma_f32_16x16x32_f16 v[34:37], v[242:245], v[200:203], v[34:37]
	v_mfma_f32_16x16x32_f16 v[20:23], v[234:237], v[208:211], v[20:23]
	v_mfma_f32_16x16x32_f16 v[16:19], v[242:245], v[208:211], v[16:19]
	v_mfma_f32_16x16x32_f16 v[4:7], v[234:237], v[216:219], v[4:7]
	v_mfma_f32_16x16x32_f16 v[0:3], v[242:245], v[216:219], v[0:3]
	s_setprio 0
	s_add_i32 s38, 0, 0x18000
	v_add_u32_e32 v142, s38, v196
	s_barrier
	ds_read_b128 v[122:125], v142
	ds_read_b128 v[138:141], v142 offset:2048
	ds_read_b128 v[130:133], v142 offset:1024
	ds_read_b128 v[142:145], v142 offset:3072
	s_add_u32 s10, s16, 0x40000
	s_addc_u32 s11, s17, 0
	s_mov_b32 m0, s23
	v_lshl_add_u64 v[230:231], s[10:11], 0, v[32:33]
	ds_read_b128 v[146:149], v198 offset:32768
	ds_read_b128 v[192:195], v198 offset:34816
	ds_read_b128 v[204:207], v198 offset:36864
	ds_read_b128 v[212:215], v198 offset:38912
	ds_read_b128 v[150:153], v198 offset:33792
	ds_read_b128 v[200:203], v198 offset:35840
	ds_read_b128 v[208:211], v198 offset:37888
	ds_read_b128 v[216:219], v198 offset:39936
	global_load_lds_dwordx4 v[230:231], off
	v_lshl_add_u64 v[230:231], s[10:11], 0, v[154:155]
	s_mov_b32 m0, s24
	s_nop 0
	global_load_lds_dwordx4 v[230:231], off
	s_waitcnt lgkmcnt(8)
	s_barrier
	s_waitcnt lgkmcnt(6)
	s_setprio 1
	v_mfma_f32_16x16x32_f16 v[134:137], v[122:125], v[146:149], v[134:137]
	v_mfma_f32_16x16x32_f16 v[126:129], v[138:141], v[146:149], v[126:129]
	v_mfma_f32_16x16x32_f16 v[110:113], v[122:125], v[192:195], v[110:113]
	v_mfma_f32_16x16x32_f16 v[106:109], v[138:141], v[192:195], v[106:109]
	s_waitcnt lgkmcnt(4)
	v_mfma_f32_16x16x32_f16 v[94:97], v[122:125], v[204:207], v[94:97]
	v_mfma_f32_16x16x32_f16 v[90:93], v[138:141], v[204:207], v[90:93]
	v_mfma_f32_16x16x32_f16 v[78:81], v[122:125], v[212:215], v[78:81]
	v_mfma_f32_16x16x32_f16 v[74:77], v[138:141], v[212:215], v[74:77]
	s_waitcnt lgkmcnt(2)
	v_mfma_f32_16x16x32_f16 v[134:137], v[130:133], v[150:153], v[134:137]
	v_mfma_f32_16x16x32_f16 v[126:129], v[142:145], v[150:153], v[126:129]
	v_mfma_f32_16x16x32_f16 v[110:113], v[130:133], v[200:203], v[110:113]
	v_mfma_f32_16x16x32_f16 v[106:109], v[142:145], v[200:203], v[106:109]
	s_waitcnt lgkmcnt(0)
	v_mfma_f32_16x16x32_f16 v[94:97], v[130:133], v[208:211], v[94:97]
	v_mfma_f32_16x16x32_f16 v[90:93], v[142:145], v[208:211], v[90:93]
	v_mfma_f32_16x16x32_f16 v[78:81], v[130:133], v[216:219], v[78:81]
	v_mfma_f32_16x16x32_f16 v[74:77], v[142:145], v[216:219], v[74:77]
	s_setprio 0
	s_barrier
	s_add_i32 s16, 0, 0x1c000
	s_add_i32 s10, s38, s20
	v_add_u32_e32 v199, s16, v196
	v_lshl_add_u64 v[246:247], v[246:247], 0, s[84:85]
	s_mov_b32 m0, s10
	ds_read_b128 v[230:233], v199
	ds_read_b128 v[238:241], v199 offset:2048
	ds_read_b128 v[234:237], v199 offset:1024
	ds_read_b128 v[242:245], v199 offset:3072
	global_load_lds_dwordx4 v[246:247], off
	v_lshl_add_u64 v[246:247], v[248:249], 0, s[84:85]
	s_add_i32 m0, s10, 0x2000
	s_nop 0
	global_load_lds_dwordx4 v[246:247], off
	s_barrier
	s_waitcnt lgkmcnt(2)
	s_setprio 1
	v_mfma_f32_16x16x32_f16 v[118:121], v[230:233], v[146:149], v[118:121]
	v_mfma_f32_16x16x32_f16 v[114:117], v[238:241], v[146:149], v[114:117]
	v_mfma_f32_16x16x32_f16 v[102:105], v[230:233], v[192:195], v[102:105]
	v_mfma_f32_16x16x32_f16 v[98:101], v[238:241], v[192:195], v[98:101]
	v_mfma_f32_16x16x32_f16 v[86:89], v[230:233], v[204:207], v[86:89]
	v_mfma_f32_16x16x32_f16 v[82:85], v[238:241], v[204:207], v[82:85]
	v_mfma_f32_16x16x32_f16 v[70:73], v[230:233], v[212:215], v[70:73]
	v_mfma_f32_16x16x32_f16 v[66:69], v[238:241], v[212:215], v[66:69]
	s_waitcnt lgkmcnt(0)
	v_mfma_f32_16x16x32_f16 v[118:121], v[234:237], v[150:153], v[118:121]
	v_mfma_f32_16x16x32_f16 v[114:117], v[242:245], v[150:153], v[114:117]
	v_mfma_f32_16x16x32_f16 v[102:105], v[234:237], v[200:203], v[102:105]
	v_mfma_f32_16x16x32_f16 v[98:101], v[242:245], v[200:203], v[98:101]
	v_mfma_f32_16x16x32_f16 v[86:89], v[234:237], v[208:211], v[86:89]
	v_mfma_f32_16x16x32_f16 v[82:85], v[242:245], v[208:211], v[82:85]
	v_mfma_f32_16x16x32_f16 v[70:73], v[234:237], v[216:219], v[70:73]
	v_mfma_f32_16x16x32_f16 v[66:69], v[242:245], v[216:219], v[66:69]
	s_setprio 0
	s_mov_b32 m0, s25
	v_lshl_add_u64 v[228:229], v[228:229], 0, s[84:85]
	s_barrier
	ds_read_b128 v[146:149], v198 offset:49152
	ds_read_b128 v[192:195], v198 offset:51200
	ds_read_b128 v[204:207], v198 offset:53248
	ds_read_b128 v[212:215], v198 offset:55296
	ds_read_b128 v[150:153], v198 offset:50176
	ds_read_b128 v[200:203], v198 offset:52224
	ds_read_b128 v[208:211], v198 offset:54272
	ds_read_b128 v[216:219], v198 offset:56320
	global_load_lds_dwordx4 v[228:229], off
	v_lshl_add_u64 v[222:223], v[222:223], 0, s[84:85]
	s_mov_b32 m0, s27
	s_nop 0
	global_load_lds_dwordx4 v[222:223], off
	s_barrier
	s_waitcnt lgkmcnt(6)
	s_setprio 1
	v_mfma_f32_16x16x32_f16 v[62:65], v[122:125], v[146:149], v[62:65]
	v_mfma_f32_16x16x32_f16 v[58:61], v[138:141], v[146:149], v[58:61]
	v_mfma_f32_16x16x32_f16 v[46:49], v[122:125], v[192:195], v[46:49]
	v_mfma_f32_16x16x32_f16 v[42:45], v[138:141], v[192:195], v[42:45]
	s_waitcnt lgkmcnt(4)
	v_mfma_f32_16x16x32_f16 v[28:31], v[122:125], v[204:207], v[28:31]
	v_mfma_f32_16x16x32_f16 v[24:27], v[138:141], v[204:207], v[24:27]
	v_mfma_f32_16x16x32_f16 v[12:15], v[122:125], v[212:215], v[12:15]
	v_mfma_f32_16x16x32_f16 v[8:11], v[138:141], v[212:215], v[8:11]
	s_waitcnt lgkmcnt(2)
	v_mfma_f32_16x16x32_f16 v[62:65], v[130:133], v[150:153], v[62:65]
	v_mfma_f32_16x16x32_f16 v[58:61], v[142:145], v[150:153], v[58:61]
	v_mfma_f32_16x16x32_f16 v[46:49], v[130:133], v[200:203], v[46:49]
	v_mfma_f32_16x16x32_f16 v[42:45], v[142:145], v[200:203], v[42:45]
	s_waitcnt lgkmcnt(0)
	v_mfma_f32_16x16x32_f16 v[28:31], v[130:133], v[208:211], v[28:31]
	v_mfma_f32_16x16x32_f16 v[24:27], v[142:145], v[208:211], v[24:27]
	v_mfma_f32_16x16x32_f16 v[12:15], v[130:133], v[216:219], v[12:15]
	v_mfma_f32_16x16x32_f16 v[8:11], v[142:145], v[216:219], v[8:11]
	s_setprio 0
	s_barrier
	s_add_u32 s10, s14, 0x40080
	s_addc_u32 s11, s15, 0
	s_add_i32 s14, s16, s20
	v_lshl_add_u64 v[122:123], s[10:11], 0, v[32:33]
	s_mov_b32 m0, s14
	s_nop 0
	global_load_lds_dwordx4 v[122:123], off
	v_lshl_add_u64 v[122:123], s[10:11], 0, v[154:155]
	s_add_i32 m0, s14, 0x2000
	s_nop 0
	global_load_lds_dwordx4 v[122:123], off
	s_waitcnt vmcnt(6)
	s_barrier
	s_setprio 1
	v_mfma_f32_16x16x32_f16 v[54:57], v[230:233], v[146:149], v[54:57]
	v_mfma_f32_16x16x32_f16 v[50:53], v[238:241], v[146:149], v[50:53]
	v_mfma_f32_16x16x32_f16 v[38:41], v[230:233], v[192:195], v[38:41]
	v_mfma_f32_16x16x32_f16 v[34:37], v[238:241], v[192:195], v[34:37]
	v_mfma_f32_16x16x32_f16 v[20:23], v[230:233], v[204:207], v[20:23]
	v_mfma_f32_16x16x32_f16 v[16:19], v[238:241], v[204:207], v[16:19]
	v_mfma_f32_16x16x32_f16 v[4:7], v[230:233], v[212:215], v[4:7]
	v_mfma_f32_16x16x32_f16 v[0:3], v[238:241], v[212:215], v[0:3]
	v_mfma_f32_16x16x32_f16 v[54:57], v[234:237], v[150:153], v[54:57]
	v_mfma_f32_16x16x32_f16 v[50:53], v[242:245], v[150:153], v[50:53]
	v_mfma_f32_16x16x32_f16 v[38:41], v[234:237], v[200:203], v[38:41]
	v_mfma_f32_16x16x32_f16 v[34:37], v[242:245], v[200:203], v[34:37]
	v_mfma_f32_16x16x32_f16 v[20:23], v[234:237], v[208:211], v[20:23]
	v_mfma_f32_16x16x32_f16 v[16:19], v[242:245], v[208:211], v[16:19]
	v_mfma_f32_16x16x32_f16 v[4:7], v[234:237], v[216:219], v[4:7]
	v_mfma_f32_16x16x32_f16 v[0:3], v[242:245], v[216:219], v[0:3]
	s_setprio 0
	s_add_i32 s37, s37, 2
	s_add_u32 s35, s35, 0x100
	s_addc_u32 s36, s36, 0
	s_cmp_gt_u32 s37, 13
	s_mov_b64 s[10:11], s[12:13]
	s_barrier
	s_cbranch_scc0 .LBB0_958
	s_cmp_eq_u32 s34, 2
	s_movk_i32 s6, 0x2800
	v_lshl_or_b32 v122, s31, 8, v197
	s_cselect_b32 s6, 0x2000, s6
	s_mov_b32 s7, 0x23a3c000
	s_cselect_b32 s8, s7, 0x23abc000
	s_add_u32 s6, s70, s6
	v_ashrrev_i32_e32 v123, 31, v122
	s_addc_u32 s7, s71, 0
	v_lshlrev_b64 v[192:193], 1, v[122:123]
	v_lshl_add_u64 v[194:195], s[6:7], 0, v[192:193]
	v_lshl_add_u64 v[122:123], v[194:195], 0, v[156:157]
	v_lshl_add_u64 v[124:125], v[194:195], 0, v[158:159]
	v_lshl_add_u64 v[130:131], v[194:195], 0, v[160:161]
	v_lshl_add_u64 v[208:209], v[194:195], 0, v[162:163]
	global_load_dwordx4 v[200:203], v[122:123], off
	global_load_dwordx4 v[204:207], v[122:123], off offset:256
	global_load_dwordx4 v[150:153], v[124:125], off
	global_load_dwordx4 v[146:149], v[124:125], off offset:256
	global_load_dwordx4 v[142:145], v[130:131], off
	global_load_dwordx4 v[138:141], v[130:131], off offset:256
	s_nop 0
	global_load_dwordx4 v[130:133], v[208:209], off
	global_load_dwordx4 v[122:125], v[208:209], off offset:256
	v_readlane_b32 s36, v252, 26
	v_readlane_b32 s42, v252, 32
	v_readlane_b32 s43, v252, 33
	s_add_u32 s6, s42, s8
	s_addc_u32 s7, s43, 0
	v_readlane_b32 s37, v252, 27
	v_readlane_b32 s38, v252, 28
	v_readlane_b32 s39, v252, 29
	v_readlane_b32 s40, v252, 30
	v_readlane_b32 s41, v252, 31
	v_lshl_add_u64 v[192:193], s[6:7], 0, v[192:193]
	s_waitcnt vmcnt(0)
	v_cvt_f32_f16_e32 v199, v200
	v_cvt_f32_f16_sdwa v200, v200 dst_sel:DWORD dst_unused:UNUSED_PAD src0_sel:WORD_1
	v_cvt_f32_f16_e32 v210, v201
	v_lshl_add_u64 v[208:209], v[192:193], 0, v[164:165]
	v_max_f32_e32 v199, 0xc1f00000, v199
	v_mul_f32_e32 v199, 0xbfb8aa3b, v199
	v_exp_f32_e32 v199, v199
	v_max_f32_e32 v200, 0xc1f00000, v200
	v_max_f32_e32 v210, 0xc1f00000, v210
	v_mul_f32_e32 v200, 0xbfb8aa3b, v200
	v_add_f32_e32 v199, 1.0, v199
	v_rcp_f32_e32 v199, v199
	v_exp_f32_e32 v200, v200
	v_mul_f32_e32 v210, 0xbfb8aa3b, v210
	v_exp_f32_e32 v211, v210
	v_fma_mixlo_f16 v199, v134, v199, 0
	v_add_f32_e32 v134, 1.0, v200
	v_rcp_f32_e32 v210, v134
	v_add_f32_e32 v134, 1.0, v211
	v_cvt_f32_f16_sdwa v200, v201 dst_sel:DWORD dst_unused:UNUSED_PAD src0_sel:WORD_1
	v_rcp_f32_e32 v211, v134
	v_mov_b32_e32 v134, v135
	v_mov_b32_e32 v135, v136
	v_cvt_f32_f16_e32 v136, v202
	v_max_f32_e32 v200, 0xc1f00000, v200
	v_mul_f32_e32 v200, 0xbfb8aa3b, v200
	v_exp_f32_e32 v200, v200
	v_max_f32_e32 v136, 0xc1f00000, v136
	v_mul_f32_e32 v136, 0xbfb8aa3b, v136
	v_exp_f32_e32 v136, v136
	v_pk_mul_f32 v[134:135], v[134:135], v[210:211]
	s_nop 0
	v_cvt_pk_f16_f32 v135, v134, v135
	v_add_f32_e32 v134, 1.0, v200
	v_rcp_f32_e32 v200, v134
	v_add_f32_e32 v134, 1.0, v136
	v_rcp_f32_e32 v201, v134
	v_pk_mov_b32 v[136:137], v[136:137], v[126:127] op_sel:[1,0]
	v_cvt_f32_f16_sdwa v126, v202 dst_sel:DWORD dst_unused:UNUSED_PAD src0_sel:WORD_1
	v_pack_b32_f16 v134, v199, v135
	v_pk_mul_f32 v[136:137], v[136:137], v[200:201]
	v_cvt_f32_f16_sdwa v200, v203 dst_sel:DWORD dst_unused:UNUSED_PAD src0_sel:WORD_1
	v_cvt_pk_f16_f32 v199, v136, v137
	v_cvt_f32_f16_e32 v136, v203
	v_max_f32_e32 v126, 0xc1f00000, v126
	v_mul_f32_e32 v126, 0xbfb8aa3b, v126
	v_exp_f32_e32 v126, v126
	v_max_f32_e32 v136, 0xc1f00000, v136
	v_mul_f32_e32 v136, 0xbfb8aa3b, v136
	v_exp_f32_e32 v137, v136
	v_add_f32_e32 v126, 1.0, v126
	v_rcp_f32_e32 v136, v126
	v_alignbit_b32 v135, v199, v135, 16
	v_add_f32_e32 v126, 1.0, v137
	v_rcp_f32_e32 v137, v126
	v_mov_b32_e32 v126, v127
	v_mov_b32_e32 v127, v128
	v_cvt_f32_f16_e32 v128, v204
	v_pk_mul_f32 v[126:127], v[126:127], v[136:137]
	s_nop 0
	v_cvt_pk_f16_f32 v126, v126, v127
	v_max_f32_e32 v127, 0xc1f00000, v200
	v_mul_f32_e32 v127, 0xbfb8aa3b, v127
	v_exp_f32_e32 v127, v127
	v_alignbit_b32 v136, v126, v199, 16
	v_lshrrev_b32_e32 v137, 16, v126
	v_add_f32_e32 v126, 1.0, v127
	v_rcp_f32_e32 v126, v126
	v_max_f32_e32 v127, 0xc1f00000, v128
	v_mul_f32_e32 v127, 0xbfb8aa3b, v127
	v_exp_f32_e32 v127, v127
	v_fma_mixhi_f16 v137, v129, v126, 0
	v_cvt_f32_f16_sdwa v126, v204 dst_sel:DWORD dst_unused:UNUSED_PAD src0_sel:WORD_1
	v_cvt_f32_f16_e32 v128, v205
	v_add_f32_e32 v127, 1.0, v127
	v_rcp_f32_e32 v127, v127
	v_max_f32_e32 v126, 0xc1f00000, v126
	v_mul_f32_e32 v126, 0xbfb8aa3b, v126
	v_max_f32_e32 v128, 0xc1f00000, v128
	v_exp_f32_e32 v126, v126
	v_mul_f32_e32 v128, 0xbfb8aa3b, v128
	v_exp_f32_e32 v128, v128
	v_fma_mixlo_f16 v129, v118, v127, 0
	v_add_f32_e32 v118, 1.0, v126
	v_rcp_f32_e32 v126, v118
	v_add_f32_e32 v118, 1.0, v128
	v_rcp_f32_e32 v127, v118
	v_cvt_f32_f16_sdwa v128, v205 dst_sel:DWORD dst_unused:UNUSED_PAD src0_sel:WORD_1
	v_mov_b32_e32 v118, v119
	v_mov_b32_e32 v119, v120
	v_cvt_f32_f16_e32 v120, v206
	v_max_f32_e32 v128, 0xc1f00000, v128
	v_mul_f32_e32 v128, 0xbfb8aa3b, v128
	v_exp_f32_e32 v128, v128
	v_max_f32_e32 v120, 0xc1f00000, v120
	v_mul_f32_e32 v120, 0xbfb8aa3b, v120
	v_exp_f32_e32 v120, v120
	v_pk_mul_f32 v[118:119], v[118:119], v[126:127]
	v_add_f32_e32 v126, 1.0, v128
	v_rcp_f32_e32 v126, v126
	v_add_f32_e32 v120, 1.0, v120
	v_rcp_f32_e32 v127, v120
	v_pk_mov_b32 v[120:121], v[120:121], v[114:115] op_sel:[1,0]
	v_cvt_f32_f16_sdwa v114, v206 dst_sel:DWORD dst_unused:UNUSED_PAD src0_sel:WORD_1
	v_cvt_pk_f16_f32 v119, v118, v119
	v_pk_mul_f32 v[120:121], v[120:121], v[126:127]
	v_cvt_f32_f16_sdwa v127, v207 dst_sel:DWORD dst_unused:UNUSED_PAD src0_sel:WORD_1
	v_cvt_pk_f16_f32 v126, v120, v121
	v_cvt_f32_f16_e32 v120, v207
	v_max_f32_e32 v114, 0xc1f00000, v114
	v_mul_f32_e32 v114, 0xbfb8aa3b, v114
	v_exp_f32_e32 v114, v114
	v_max_f32_e32 v120, 0xc1f00000, v120
	v_mul_f32_e32 v120, 0xbfb8aa3b, v120
	v_exp_f32_e32 v121, v120
	v_add_f32_e32 v114, 1.0, v114
	v_rcp_f32_e32 v120, v114
	v_pack_b32_f16 v118, v129, v119
	v_add_f32_e32 v114, 1.0, v121
	v_rcp_f32_e32 v121, v114
	v_mov_b32_e32 v114, v115
	v_max_f32_e32 v115, 0xc1f00000, v127
	v_mul_f32_e32 v115, 0xbfb8aa3b, v115
	v_exp_f32_e32 v127, v115
	v_mov_b32_e32 v115, v116
	v_pk_mul_f32 v[114:115], v[114:115], v[120:121]
	v_cvt_f32_f16_e32 v116, v150
	v_cvt_pk_f16_f32 v114, v114, v115
	v_add_f32_e32 v115, 1.0, v127
	v_rcp_f32_e32 v115, v115
	v_alignbit_b32 v120, v114, v126, 16
	v_lshrrev_b32_e32 v121, 16, v114
	v_max_f32_e32 v114, 0xc1f00000, v116
	v_alignbit_b32 v119, v126, v119, 16
	v_fma_mixhi_f16 v121, v117, v115, 0
	v_mul_f32_e32 v114, 0xbfb8aa3b, v114
	v_cvt_f32_f16_sdwa v117, v150 dst_sel:DWORD dst_unused:UNUSED_PAD src0_sel:WORD_1
	v_exp_f32_e32 v116, v114
	global_store_dwordx4 v[208:209], v[118:121], off offset:256
	v_lshl_add_u64 v[114:115], v[192:193], 0, v[166:167]
	v_max_f32_e32 v117, 0xc1f00000, v117
	v_cvt_f32_f16_e32 v118, v151
	v_add_f32_e32 v116, 1.0, v116
	v_mul_f32_e32 v117, 0xbfb8aa3b, v117
	v_rcp_f32_e32 v116, v116
	v_max_f32_e32 v118, 0xc1f00000, v118
	v_exp_f32_e32 v117, v117
	v_mul_f32_e32 v118, 0xbfb8aa3b, v118
	v_exp_f32_e32 v118, v118
	v_fma_mixlo_f16 v119, v110, v116, 0
	v_add_f32_e32 v110, 1.0, v117
	v_rcp_f32_e32 v116, v110
	v_add_f32_e32 v110, 1.0, v118
	v_rcp_f32_e32 v117, v110
	v_cvt_f32_f16_sdwa v118, v151 dst_sel:DWORD dst_unused:UNUSED_PAD src0_sel:WORD_1
	v_mov_b32_e32 v110, v111
	v_mov_b32_e32 v111, v112
	v_cvt_f32_f16_e32 v112, v152
	v_pk_mul_f32 v[110:111], v[110:111], v[116:117]
	v_max_f32_e32 v116, 0xc1f00000, v118
	v_mul_f32_e32 v116, 0xbfb8aa3b, v116
	v_max_f32_e32 v112, 0xc1f00000, v112
	v_exp_f32_e32 v116, v116
	v_mul_f32_e32 v112, 0xbfb8aa3b, v112
	v_exp_f32_e32 v112, v112
	v_cvt_pk_f16_f32 v111, v110, v111
	v_add_f32_e32 v110, 1.0, v116
	v_rcp_f32_e32 v116, v110
	v_add_f32_e32 v110, 1.0, v112
	v_rcp_f32_e32 v117, v110
	v_pk_mov_b32 v[112:113], v[112:113], v[106:107] op_sel:[1,0]
	v_cvt_f32_f16_sdwa v106, v152 dst_sel:DWORD dst_unused:UNUSED_PAD src0_sel:WORD_1
	v_pack_b32_f16 v110, v119, v111
	v_pk_mul_f32 v[112:113], v[112:113], v[116:117]
	v_cvt_f32_f16_sdwa v117, v153 dst_sel:DWORD dst_unused:UNUSED_PAD src0_sel:WORD_1
	v_cvt_pk_f16_f32 v116, v112, v113
	v_cvt_f32_f16_e32 v112, v153
	v_max_f32_e32 v106, 0xc1f00000, v106
	v_mul_f32_e32 v106, 0xbfb8aa3b, v106
	v_exp_f32_e32 v106, v106
	v_max_f32_e32 v112, 0xc1f00000, v112
	v_mul_f32_e32 v112, 0xbfb8aa3b, v112
	v_exp_f32_e32 v113, v112
	v_add_f32_e32 v106, 1.0, v106
	v_rcp_f32_e32 v112, v106
	v_alignbit_b32 v111, v116, v111, 16
	v_add_f32_e32 v106, 1.0, v113
	v_rcp_f32_e32 v113, v106
	v_mov_b32_e32 v106, v107
	v_mov_b32_e32 v107, v108
	v_cvt_f32_f16_e32 v108, v146
	v_pk_mul_f32 v[106:107], v[106:107], v[112:113]
	global_store_dwordx4 v[208:209], v[134:137], off
	v_cvt_pk_f16_f32 v106, v106, v107
	v_max_f32_e32 v107, 0xc1f00000, v117
	v_mul_f32_e32 v107, 0xbfb8aa3b, v107
	v_exp_f32_e32 v107, v107
	v_alignbit_b32 v112, v106, v116, 16
	v_lshrrev_b32_e32 v113, 16, v106
	v_add_f32_e32 v106, 1.0, v107
	v_rcp_f32_e32 v106, v106
	v_max_f32_e32 v107, 0xc1f00000, v108
	v_mul_f32_e32 v107, 0xbfb8aa3b, v107
	v_exp_f32_e32 v107, v107
	v_fma_mixhi_f16 v113, v109, v106, 0
	v_cvt_f32_f16_sdwa v106, v146 dst_sel:DWORD dst_unused:UNUSED_PAD src0_sel:WORD_1
	v_cvt_f32_f16_e32 v108, v147
	v_add_f32_e32 v107, 1.0, v107
	v_rcp_f32_e32 v107, v107
	v_max_f32_e32 v106, 0xc1f00000, v106
	v_mul_f32_e32 v106, 0xbfb8aa3b, v106
	v_max_f32_e32 v108, 0xc1f00000, v108
	v_exp_f32_e32 v106, v106
	v_mul_f32_e32 v108, 0xbfb8aa3b, v108
	v_exp_f32_e32 v108, v108
	v_fma_mixlo_f16 v109, v102, v107, 0
	v_add_f32_e32 v102, 1.0, v106
	v_rcp_f32_e32 v106, v102
	v_add_f32_e32 v102, 1.0, v108
	v_rcp_f32_e32 v107, v102
	v_cvt_f32_f16_sdwa v108, v147 dst_sel:DWORD dst_unused:UNUSED_PAD src0_sel:WORD_1
	v_mov_b32_e32 v102, v103
	v_mov_b32_e32 v103, v104
	v_cvt_f32_f16_e32 v104, v148
	v_max_f32_e32 v108, 0xc1f00000, v108
	v_mul_f32_e32 v108, 0xbfb8aa3b, v108
	v_exp_f32_e32 v108, v108
	v_max_f32_e32 v104, 0xc1f00000, v104
	v_mul_f32_e32 v104, 0xbfb8aa3b, v104
	v_exp_f32_e32 v104, v104
	v_pk_mul_f32 v[102:103], v[102:103], v[106:107]
	v_add_f32_e32 v106, 1.0, v108
	v_rcp_f32_e32 v106, v106
	v_add_f32_e32 v104, 1.0, v104
	v_rcp_f32_e32 v107, v104
	v_pk_mov_b32 v[104:105], v[104:105], v[98:99] op_sel:[1,0]
	v_cvt_f32_f16_sdwa v98, v148 dst_sel:DWORD dst_unused:UNUSED_PAD src0_sel:WORD_1
	v_cvt_pk_f16_f32 v103, v102, v103
	v_pk_mul_f32 v[104:105], v[104:105], v[106:107]
	v_cvt_f32_f16_sdwa v107, v149 dst_sel:DWORD dst_unused:UNUSED_PAD src0_sel:WORD_1
	v_cvt_pk_f16_f32 v106, v104, v105
	v_cvt_f32_f16_e32 v104, v149
	v_max_f32_e32 v98, 0xc1f00000, v98
	v_mul_f32_e32 v98, 0xbfb8aa3b, v98
	v_exp_f32_e32 v98, v98
	v_max_f32_e32 v104, 0xc1f00000, v104
	v_mul_f32_e32 v104, 0xbfb8aa3b, v104
	v_exp_f32_e32 v105, v104
	v_add_f32_e32 v98, 1.0, v98
	v_rcp_f32_e32 v104, v98
	v_pack_b32_f16 v102, v109, v103
	v_add_f32_e32 v98, 1.0, v105
	v_rcp_f32_e32 v105, v98
	v_mov_b32_e32 v98, v99
	v_max_f32_e32 v99, 0xc1f00000, v107
	v_mul_f32_e32 v99, 0xbfb8aa3b, v99
	v_exp_f32_e32 v107, v99
	v_mov_b32_e32 v99, v100
	v_pk_mul_f32 v[98:99], v[98:99], v[104:105]
	v_cvt_f32_f16_e32 v100, v142
	v_cvt_pk_f16_f32 v98, v98, v99
	v_add_f32_e32 v99, 1.0, v107
	v_rcp_f32_e32 v99, v99
	v_alignbit_b32 v104, v98, v106, 16
	v_lshrrev_b32_e32 v105, 16, v98
	v_max_f32_e32 v98, 0xc1f00000, v100
	v_alignbit_b32 v103, v106, v103, 16
	v_fma_mixhi_f16 v105, v101, v99, 0
	v_mul_f32_e32 v98, 0xbfb8aa3b, v98
	v_cvt_f32_f16_sdwa v101, v142 dst_sel:DWORD dst_unused:UNUSED_PAD src0_sel:WORD_1
	v_exp_f32_e32 v100, v98
	global_store_dwordx4 v[114:115], v[102:105], off offset:256
	v_lshl_add_u64 v[98:99], v[192:193], 0, v[168:169]
	v_max_f32_e32 v101, 0xc1f00000, v101
	v_cvt_f32_f16_e32 v102, v143
	v_add_f32_e32 v100, 1.0, v100
	v_mul_f32_e32 v101, 0xbfb8aa3b, v101
	v_rcp_f32_e32 v100, v100
	v_max_f32_e32 v102, 0xc1f00000, v102
	v_exp_f32_e32 v101, v101
	v_mul_f32_e32 v102, 0xbfb8aa3b, v102
	v_exp_f32_e32 v102, v102
	v_fma_mixlo_f16 v103, v94, v100, 0
	v_add_f32_e32 v94, 1.0, v101
	v_rcp_f32_e32 v100, v94
	v_add_f32_e32 v94, 1.0, v102
	v_rcp_f32_e32 v101, v94
	v_cvt_f32_f16_sdwa v102, v143 dst_sel:DWORD dst_unused:UNUSED_PAD src0_sel:WORD_1
	v_mov_b32_e32 v94, v95
	v_mov_b32_e32 v95, v96
	v_cvt_f32_f16_e32 v96, v144
	v_pk_mul_f32 v[94:95], v[94:95], v[100:101]
	v_max_f32_e32 v100, 0xc1f00000, v102
	v_mul_f32_e32 v100, 0xbfb8aa3b, v100
	v_max_f32_e32 v96, 0xc1f00000, v96
	v_exp_f32_e32 v100, v100
	v_mul_f32_e32 v96, 0xbfb8aa3b, v96
	v_exp_f32_e32 v96, v96
	v_cvt_pk_f16_f32 v95, v94, v95
	v_add_f32_e32 v94, 1.0, v100
	v_rcp_f32_e32 v100, v94
	v_add_f32_e32 v94, 1.0, v96
	v_rcp_f32_e32 v101, v94
	v_pk_mov_b32 v[96:97], v[96:97], v[90:91] op_sel:[1,0]
	v_cvt_f32_f16_sdwa v90, v144 dst_sel:DWORD dst_unused:UNUSED_PAD src0_sel:WORD_1
	v_pack_b32_f16 v94, v103, v95
	v_pk_mul_f32 v[96:97], v[96:97], v[100:101]
	v_cvt_f32_f16_sdwa v101, v145 dst_sel:DWORD dst_unused:UNUSED_PAD src0_sel:WORD_1
	v_cvt_pk_f16_f32 v100, v96, v97
	v_cvt_f32_f16_e32 v96, v145
	v_max_f32_e32 v90, 0xc1f00000, v90
	v_mul_f32_e32 v90, 0xbfb8aa3b, v90
	v_exp_f32_e32 v90, v90
	v_max_f32_e32 v96, 0xc1f00000, v96
	v_mul_f32_e32 v96, 0xbfb8aa3b, v96
	v_exp_f32_e32 v97, v96
	v_add_f32_e32 v90, 1.0, v90
	v_rcp_f32_e32 v96, v90
	v_alignbit_b32 v95, v100, v95, 16
	v_add_f32_e32 v90, 1.0, v97
	v_rcp_f32_e32 v97, v90
	v_mov_b32_e32 v90, v91
	v_mov_b32_e32 v91, v92
	v_cvt_f32_f16_e32 v92, v138
	v_pk_mul_f32 v[90:91], v[90:91], v[96:97]
	global_store_dwordx4 v[114:115], v[110:113], off
	v_cvt_pk_f16_f32 v90, v90, v91
	v_max_f32_e32 v91, 0xc1f00000, v101
	v_mul_f32_e32 v91, 0xbfb8aa3b, v91
	v_exp_f32_e32 v91, v91
	v_alignbit_b32 v96, v90, v100, 16
	v_lshrrev_b32_e32 v97, 16, v90
	v_add_f32_e32 v90, 1.0, v91
	v_rcp_f32_e32 v90, v90
	v_max_f32_e32 v91, 0xc1f00000, v92
	v_mul_f32_e32 v91, 0xbfb8aa3b, v91
	v_exp_f32_e32 v91, v91
	v_fma_mixhi_f16 v97, v93, v90, 0
	v_cvt_f32_f16_sdwa v90, v138 dst_sel:DWORD dst_unused:UNUSED_PAD src0_sel:WORD_1
	v_cvt_f32_f16_e32 v92, v139
	v_add_f32_e32 v91, 1.0, v91
	v_rcp_f32_e32 v91, v91
	v_max_f32_e32 v90, 0xc1f00000, v90
	v_mul_f32_e32 v90, 0xbfb8aa3b, v90
	v_max_f32_e32 v92, 0xc1f00000, v92
	v_exp_f32_e32 v90, v90
	v_mul_f32_e32 v92, 0xbfb8aa3b, v92
	v_exp_f32_e32 v92, v92
	v_fma_mixlo_f16 v93, v86, v91, 0
	v_add_f32_e32 v86, 1.0, v90
	v_rcp_f32_e32 v90, v86
	v_add_f32_e32 v86, 1.0, v92
	v_rcp_f32_e32 v91, v86
	v_cvt_f32_f16_sdwa v92, v139 dst_sel:DWORD dst_unused:UNUSED_PAD src0_sel:WORD_1
	v_mov_b32_e32 v86, v87
	v_mov_b32_e32 v87, v88
	v_cvt_f32_f16_e32 v88, v140
	v_max_f32_e32 v92, 0xc1f00000, v92
	v_mul_f32_e32 v92, 0xbfb8aa3b, v92
	v_exp_f32_e32 v92, v92
	v_max_f32_e32 v88, 0xc1f00000, v88
	v_mul_f32_e32 v88, 0xbfb8aa3b, v88
	v_exp_f32_e32 v88, v88
	v_pk_mul_f32 v[86:87], v[86:87], v[90:91]
	v_add_f32_e32 v90, 1.0, v92
	v_rcp_f32_e32 v90, v90
	v_add_f32_e32 v88, 1.0, v88
	v_rcp_f32_e32 v91, v88
	v_pk_mov_b32 v[88:89], v[88:89], v[82:83] op_sel:[1,0]
	v_cvt_f32_f16_sdwa v82, v140 dst_sel:DWORD dst_unused:UNUSED_PAD src0_sel:WORD_1
	v_cvt_pk_f16_f32 v87, v86, v87
	v_pk_mul_f32 v[88:89], v[88:89], v[90:91]
	v_cvt_f32_f16_sdwa v91, v141 dst_sel:DWORD dst_unused:UNUSED_PAD src0_sel:WORD_1
	v_cvt_pk_f16_f32 v90, v88, v89
	v_cvt_f32_f16_e32 v88, v141
	v_max_f32_e32 v82, 0xc1f00000, v82
	v_mul_f32_e32 v82, 0xbfb8aa3b, v82
	v_exp_f32_e32 v82, v82
	v_max_f32_e32 v88, 0xc1f00000, v88
	v_mul_f32_e32 v88, 0xbfb8aa3b, v88
	v_exp_f32_e32 v89, v88
	v_add_f32_e32 v82, 1.0, v82
	v_rcp_f32_e32 v88, v82
	v_pack_b32_f16 v86, v93, v87
	v_add_f32_e32 v82, 1.0, v89
	v_rcp_f32_e32 v89, v82
	v_mov_b32_e32 v82, v83
	v_max_f32_e32 v83, 0xc1f00000, v91
	v_mul_f32_e32 v83, 0xbfb8aa3b, v83
	v_exp_f32_e32 v91, v83
	v_mov_b32_e32 v83, v84
	v_pk_mul_f32 v[82:83], v[82:83], v[88:89]
	v_cvt_f32_f16_e32 v84, v130
	v_cvt_pk_f16_f32 v82, v82, v83
	v_add_f32_e32 v83, 1.0, v91
	v_rcp_f32_e32 v83, v83
	v_alignbit_b32 v88, v82, v90, 16
	v_lshrrev_b32_e32 v89, 16, v82
	v_max_f32_e32 v82, 0xc1f00000, v84
	v_alignbit_b32 v87, v90, v87, 16
	v_fma_mixhi_f16 v89, v85, v83, 0
	v_mul_f32_e32 v82, 0xbfb8aa3b, v82
	v_cvt_f32_f16_sdwa v85, v130 dst_sel:DWORD dst_unused:UNUSED_PAD src0_sel:WORD_1
	v_exp_f32_e32 v84, v82
	global_store_dwordx4 v[98:99], v[86:89], off offset:256
	v_lshl_add_u64 v[82:83], v[192:193], 0, v[170:171]
	v_max_f32_e32 v85, 0xc1f00000, v85
	v_cvt_f32_f16_e32 v86, v131
	v_add_f32_e32 v84, 1.0, v84
	v_mul_f32_e32 v85, 0xbfb8aa3b, v85
	v_rcp_f32_e32 v84, v84
	v_max_f32_e32 v86, 0xc1f00000, v86
	v_exp_f32_e32 v85, v85
	v_mul_f32_e32 v86, 0xbfb8aa3b, v86
	v_exp_f32_e32 v86, v86
	v_fma_mixlo_f16 v87, v78, v84, 0
	v_add_f32_e32 v78, 1.0, v85
	v_rcp_f32_e32 v84, v78
	v_add_f32_e32 v78, 1.0, v86
	v_rcp_f32_e32 v85, v78
	v_cvt_f32_f16_sdwa v86, v131 dst_sel:DWORD dst_unused:UNUSED_PAD src0_sel:WORD_1
	v_mov_b32_e32 v78, v79
	v_mov_b32_e32 v79, v80
	v_cvt_f32_f16_e32 v80, v132
	v_pk_mul_f32 v[78:79], v[78:79], v[84:85]
	v_max_f32_e32 v84, 0xc1f00000, v86
	v_mul_f32_e32 v84, 0xbfb8aa3b, v84
	v_max_f32_e32 v80, 0xc1f00000, v80
	v_exp_f32_e32 v84, v84
	v_mul_f32_e32 v80, 0xbfb8aa3b, v80
	v_exp_f32_e32 v80, v80
	v_cvt_pk_f16_f32 v79, v78, v79
	v_add_f32_e32 v78, 1.0, v84
	v_rcp_f32_e32 v84, v78
	v_add_f32_e32 v78, 1.0, v80
	v_rcp_f32_e32 v85, v78
	v_pk_mov_b32 v[80:81], v[80:81], v[74:75] op_sel:[1,0]
	v_cvt_f32_f16_sdwa v74, v132 dst_sel:DWORD dst_unused:UNUSED_PAD src0_sel:WORD_1
	v_pack_b32_f16 v78, v87, v79
	v_pk_mul_f32 v[80:81], v[80:81], v[84:85]
	v_cvt_f32_f16_sdwa v85, v133 dst_sel:DWORD dst_unused:UNUSED_PAD src0_sel:WORD_1
	v_cvt_pk_f16_f32 v84, v80, v81
	v_cvt_f32_f16_e32 v80, v133
	v_max_f32_e32 v74, 0xc1f00000, v74
	v_mul_f32_e32 v74, 0xbfb8aa3b, v74
	v_exp_f32_e32 v74, v74
	v_max_f32_e32 v80, 0xc1f00000, v80
	v_mul_f32_e32 v80, 0xbfb8aa3b, v80
	v_exp_f32_e32 v81, v80
	v_add_f32_e32 v74, 1.0, v74
	v_rcp_f32_e32 v80, v74
	v_alignbit_b32 v79, v84, v79, 16
	v_add_f32_e32 v74, 1.0, v81
	v_rcp_f32_e32 v81, v74
	v_mov_b32_e32 v74, v75
	v_mov_b32_e32 v75, v76
	v_cvt_f32_f16_e32 v76, v122
	v_pk_mul_f32 v[74:75], v[74:75], v[80:81]
	global_store_dwordx4 v[98:99], v[94:97], off
	v_cvt_pk_f16_f32 v74, v74, v75
	v_max_f32_e32 v75, 0xc1f00000, v85
	v_mul_f32_e32 v75, 0xbfb8aa3b, v75
	v_exp_f32_e32 v75, v75
	v_alignbit_b32 v80, v74, v84, 16
	v_lshrrev_b32_e32 v81, 16, v74
	v_add_f32_e32 v74, 1.0, v75
	v_rcp_f32_e32 v74, v74
	v_max_f32_e32 v75, 0xc1f00000, v76
	v_mul_f32_e32 v75, 0xbfb8aa3b, v75
	v_exp_f32_e32 v75, v75
	v_fma_mixhi_f16 v81, v77, v74, 0
	v_cvt_f32_f16_sdwa v74, v122 dst_sel:DWORD dst_unused:UNUSED_PAD src0_sel:WORD_1
	v_cvt_f32_f16_e32 v76, v123
	v_add_f32_e32 v75, 1.0, v75
	v_rcp_f32_e32 v75, v75
	v_max_f32_e32 v74, 0xc1f00000, v74
	v_mul_f32_e32 v74, 0xbfb8aa3b, v74
	v_max_f32_e32 v76, 0xc1f00000, v76
	v_exp_f32_e32 v74, v74
	v_mul_f32_e32 v76, 0xbfb8aa3b, v76
	v_exp_f32_e32 v76, v76
	v_fma_mixlo_f16 v77, v70, v75, 0
	v_add_f32_e32 v70, 1.0, v74
	v_rcp_f32_e32 v74, v70
	v_add_f32_e32 v70, 1.0, v76
	v_rcp_f32_e32 v75, v70
	v_cvt_f32_f16_sdwa v76, v123 dst_sel:DWORD dst_unused:UNUSED_PAD src0_sel:WORD_1
	v_mov_b32_e32 v70, v71
	v_mov_b32_e32 v71, v72
	v_cvt_f32_f16_e32 v72, v124
	v_max_f32_e32 v76, 0xc1f00000, v76
	v_mul_f32_e32 v76, 0xbfb8aa3b, v76
	v_exp_f32_e32 v76, v76
	v_max_f32_e32 v72, 0xc1f00000, v72
	v_mul_f32_e32 v72, 0xbfb8aa3b, v72
	v_exp_f32_e32 v72, v72
	v_pk_mul_f32 v[70:71], v[70:71], v[74:75]
	v_add_f32_e32 v74, 1.0, v76
	v_rcp_f32_e32 v74, v74
	v_add_f32_e32 v72, 1.0, v72
	v_rcp_f32_e32 v75, v72
	v_pk_mov_b32 v[72:73], v[72:73], v[66:67] op_sel:[1,0]
	v_cvt_f32_f16_sdwa v66, v124 dst_sel:DWORD dst_unused:UNUSED_PAD src0_sel:WORD_1
	v_cvt_pk_f16_f32 v71, v70, v71
	v_pk_mul_f32 v[72:73], v[72:73], v[74:75]
	v_cvt_f32_f16_sdwa v75, v125 dst_sel:DWORD dst_unused:UNUSED_PAD src0_sel:WORD_1
	v_cvt_pk_f16_f32 v74, v72, v73
	v_cvt_f32_f16_e32 v72, v125
	v_max_f32_e32 v66, 0xc1f00000, v66
	v_mul_f32_e32 v66, 0xbfb8aa3b, v66
	v_exp_f32_e32 v66, v66
	v_max_f32_e32 v72, 0xc1f00000, v72
	v_mul_f32_e32 v72, 0xbfb8aa3b, v72
	v_exp_f32_e32 v73, v72
	v_add_f32_e32 v66, 1.0, v66
	v_rcp_f32_e32 v72, v66
	v_pack_b32_f16 v70, v77, v71
	v_add_f32_e32 v66, 1.0, v73
	v_rcp_f32_e32 v73, v66
	v_max_f32_e32 v66, 0xc1f00000, v75
	v_mul_f32_e32 v66, 0xbfb8aa3b, v66
	v_exp_f32_e32 v75, v66
	v_mov_b32_e32 v66, v67
	v_mov_b32_e32 v67, v68
	v_pk_mul_f32 v[66:67], v[66:67], v[72:73]
	v_add_f32_e32 v68, 1.0, v75
	v_rcp_f32_e32 v68, v68
	v_cvt_pk_f16_f32 v66, v66, v67
	v_lshrrev_b32_e32 v73, 16, v66
	v_alignbit_b32 v71, v74, v71, 16
	v_alignbit_b32 v72, v66, v74, 16
	v_fma_mixhi_f16 v73, v69, v68, 0
	global_store_dwordx4 v[82:83], v[78:81], off
	global_store_dwordx4 v[82:83], v[70:73], off offset:256
	v_lshl_add_u64 v[66:67], v[194:195], 0, v[172:173]
	v_lshl_add_u64 v[68:69], v[194:195], 0, v[174:175]
	v_lshl_add_u64 v[70:71], v[194:195], 0, v[176:177]
	v_lshl_add_u64 v[98:99], v[194:195], 0, v[178:179]
	global_load_dwordx4 v[90:93], v[66:67], off
	global_load_dwordx4 v[94:97], v[66:67], off offset:256
	global_load_dwordx4 v[86:89], v[68:69], off
	global_load_dwordx4 v[82:85], v[68:69], off offset:256
	global_load_dwordx4 v[78:81], v[70:71], off
	global_load_dwordx4 v[74:77], v[70:71], off offset:256
	s_nop 0
	global_load_dwordx4 v[70:73], v[98:99], off
	global_load_dwordx4 v[66:69], v[98:99], off offset:256
	s_waitcnt vmcnt(0)
	v_cvt_f32_f16_e32 v100, v90
	v_cvt_f32_f16_sdwa v90, v90 dst_sel:DWORD dst_unused:UNUSED_PAD src0_sel:WORD_1
	v_cvt_f32_f16_e32 v101, v91
	v_lshl_add_u64 v[98:99], v[192:193], 0, v[180:181]
	v_max_f32_e32 v100, 0xc1f00000, v100
	v_mul_f32_e32 v100, 0xbfb8aa3b, v100
	v_exp_f32_e32 v100, v100
	v_max_f32_e32 v90, 0xc1f00000, v90
	v_max_f32_e32 v101, 0xc1f00000, v101
	v_mul_f32_e32 v90, 0xbfb8aa3b, v90
	v_add_f32_e32 v100, 1.0, v100
	v_rcp_f32_e32 v100, v100
	v_exp_f32_e32 v90, v90
	v_mul_f32_e32 v101, 0xbfb8aa3b, v101
	v_exp_f32_e32 v101, v101
	v_fma_mixlo_f16 v102, v62, v100, 0
	v_add_f32_e32 v62, 1.0, v90
	v_rcp_f32_e32 v100, v62
	v_add_f32_e32 v62, 1.0, v101
	v_cvt_f32_f16_sdwa v90, v91 dst_sel:DWORD dst_unused:UNUSED_PAD src0_sel:WORD_1
	v_rcp_f32_e32 v101, v62
	v_mov_b32_e32 v62, v63
	v_mov_b32_e32 v63, v64
	v_cvt_f32_f16_e32 v64, v92
	v_max_f32_e32 v90, 0xc1f00000, v90
	v_mul_f32_e32 v90, 0xbfb8aa3b, v90
	v_exp_f32_e32 v90, v90
	v_max_f32_e32 v64, 0xc1f00000, v64
	v_mul_f32_e32 v64, 0xbfb8aa3b, v64
	v_exp_f32_e32 v64, v64
	v_pk_mul_f32 v[62:63], v[62:63], v[100:101]
	s_nop 0
	v_cvt_pk_f16_f32 v63, v62, v63
	v_add_f32_e32 v62, 1.0, v90
	v_rcp_f32_e32 v90, v62
	v_add_f32_e32 v62, 1.0, v64
	v_rcp_f32_e32 v91, v62
	v_pk_mov_b32 v[64:65], v[64:65], v[58:59] op_sel:[1,0]
	v_cvt_f32_f16_sdwa v58, v92 dst_sel:DWORD dst_unused:UNUSED_PAD src0_sel:WORD_1
	v_pack_b32_f16 v62, v102, v63
	v_pk_mul_f32 v[64:65], v[64:65], v[90:91]
	v_cvt_f32_f16_sdwa v91, v93 dst_sel:DWORD dst_unused:UNUSED_PAD src0_sel:WORD_1
	v_cvt_pk_f16_f32 v90, v64, v65
	v_cvt_f32_f16_e32 v64, v93
	v_max_f32_e32 v58, 0xc1f00000, v58
	v_mul_f32_e32 v58, 0xbfb8aa3b, v58
	v_exp_f32_e32 v58, v58
	v_max_f32_e32 v64, 0xc1f00000, v64
	v_mul_f32_e32 v64, 0xbfb8aa3b, v64
	v_exp_f32_e32 v65, v64
	v_add_f32_e32 v58, 1.0, v58
	v_rcp_f32_e32 v64, v58
	v_alignbit_b32 v63, v90, v63, 16
	v_add_f32_e32 v58, 1.0, v65
	v_rcp_f32_e32 v65, v58
	v_mov_b32_e32 v58, v59
	v_mov_b32_e32 v59, v60
	v_cvt_f32_f16_e32 v60, v94
	v_pk_mul_f32 v[58:59], v[58:59], v[64:65]
	s_nop 0
	v_cvt_pk_f16_f32 v58, v58, v59
	v_max_f32_e32 v59, 0xc1f00000, v91
	v_mul_f32_e32 v59, 0xbfb8aa3b, v59
	v_exp_f32_e32 v59, v59
	v_alignbit_b32 v64, v58, v90, 16
	v_lshrrev_b32_e32 v65, 16, v58
	v_add_f32_e32 v58, 1.0, v59
	v_rcp_f32_e32 v58, v58
	v_max_f32_e32 v59, 0xc1f00000, v60
	v_mul_f32_e32 v59, 0xbfb8aa3b, v59
	v_exp_f32_e32 v59, v59
	v_fma_mixhi_f16 v65, v61, v58, 0
	v_cvt_f32_f16_sdwa v58, v94 dst_sel:DWORD dst_unused:UNUSED_PAD src0_sel:WORD_1
	v_cvt_f32_f16_e32 v60, v95
	v_add_f32_e32 v59, 1.0, v59
	v_rcp_f32_e32 v59, v59
	v_max_f32_e32 v58, 0xc1f00000, v58
	v_mul_f32_e32 v58, 0xbfb8aa3b, v58
	v_max_f32_e32 v60, 0xc1f00000, v60
	v_exp_f32_e32 v58, v58
	v_mul_f32_e32 v60, 0xbfb8aa3b, v60
	v_exp_f32_e32 v60, v60
	v_fma_mixlo_f16 v61, v54, v59, 0
	v_add_f32_e32 v54, 1.0, v58
	v_rcp_f32_e32 v58, v54
	v_add_f32_e32 v54, 1.0, v60
	v_rcp_f32_e32 v59, v54
	v_cvt_f32_f16_sdwa v60, v95 dst_sel:DWORD dst_unused:UNUSED_PAD src0_sel:WORD_1
	v_mov_b32_e32 v54, v55
	v_mov_b32_e32 v55, v56
	v_cvt_f32_f16_e32 v56, v96
	v_max_f32_e32 v60, 0xc1f00000, v60
	v_mul_f32_e32 v60, 0xbfb8aa3b, v60
	v_exp_f32_e32 v60, v60
	v_max_f32_e32 v56, 0xc1f00000, v56
	v_mul_f32_e32 v56, 0xbfb8aa3b, v56
	v_exp_f32_e32 v56, v56
	v_pk_mul_f32 v[54:55], v[54:55], v[58:59]
	v_add_f32_e32 v58, 1.0, v60
	v_rcp_f32_e32 v58, v58
	v_add_f32_e32 v56, 1.0, v56
	v_rcp_f32_e32 v59, v56
	v_pk_mov_b32 v[56:57], v[56:57], v[50:51] op_sel:[1,0]
	v_cvt_f32_f16_sdwa v50, v96 dst_sel:DWORD dst_unused:UNUSED_PAD src0_sel:WORD_1
	v_cvt_pk_f16_f32 v55, v54, v55
	v_pk_mul_f32 v[56:57], v[56:57], v[58:59]
	v_cvt_f32_f16_sdwa v59, v97 dst_sel:DWORD dst_unused:UNUSED_PAD src0_sel:WORD_1
	v_cvt_pk_f16_f32 v58, v56, v57
	v_cvt_f32_f16_e32 v56, v97
	v_max_f32_e32 v50, 0xc1f00000, v50
	v_mul_f32_e32 v50, 0xbfb8aa3b, v50
	v_exp_f32_e32 v50, v50
	v_max_f32_e32 v56, 0xc1f00000, v56
	v_mul_f32_e32 v56, 0xbfb8aa3b, v56
	v_exp_f32_e32 v57, v56
	v_add_f32_e32 v50, 1.0, v50
	v_rcp_f32_e32 v56, v50
	v_pack_b32_f16 v54, v61, v55
	v_add_f32_e32 v50, 1.0, v57
	v_rcp_f32_e32 v57, v50
	v_mov_b32_e32 v50, v51
	v_max_f32_e32 v51, 0xc1f00000, v59
	v_mul_f32_e32 v51, 0xbfb8aa3b, v51
	v_exp_f32_e32 v59, v51
	v_mov_b32_e32 v51, v52
	v_pk_mul_f32 v[50:51], v[50:51], v[56:57]
	v_cvt_f32_f16_e32 v52, v86
	v_cvt_pk_f16_f32 v50, v50, v51
	v_add_f32_e32 v51, 1.0, v59
	v_rcp_f32_e32 v51, v51
	v_alignbit_b32 v56, v50, v58, 16
	v_lshrrev_b32_e32 v57, 16, v50
	v_max_f32_e32 v50, 0xc1f00000, v52
	v_alignbit_b32 v55, v58, v55, 16
	v_fma_mixhi_f16 v57, v53, v51, 0
	v_mul_f32_e32 v50, 0xbfb8aa3b, v50
	v_cvt_f32_f16_sdwa v53, v86 dst_sel:DWORD dst_unused:UNUSED_PAD src0_sel:WORD_1
	v_exp_f32_e32 v52, v50
	global_store_dwordx4 v[98:99], v[54:57], off offset:256
	v_lshl_add_u64 v[50:51], v[192:193], 0, v[182:183]
	v_max_f32_e32 v53, 0xc1f00000, v53
	v_cvt_f32_f16_e32 v54, v87
	v_add_f32_e32 v52, 1.0, v52
	v_mul_f32_e32 v53, 0xbfb8aa3b, v53
	v_rcp_f32_e32 v52, v52
	v_max_f32_e32 v54, 0xc1f00000, v54
	v_exp_f32_e32 v53, v53
	v_mul_f32_e32 v54, 0xbfb8aa3b, v54
	v_exp_f32_e32 v54, v54
	v_fma_mixlo_f16 v55, v46, v52, 0
	v_add_f32_e32 v46, 1.0, v53
	v_rcp_f32_e32 v52, v46
	v_add_f32_e32 v46, 1.0, v54
	v_rcp_f32_e32 v53, v46
	v_cvt_f32_f16_sdwa v54, v87 dst_sel:DWORD dst_unused:UNUSED_PAD src0_sel:WORD_1
	v_mov_b32_e32 v46, v47
	v_mov_b32_e32 v47, v48
	v_cvt_f32_f16_e32 v48, v88
	v_pk_mul_f32 v[46:47], v[46:47], v[52:53]
	v_max_f32_e32 v52, 0xc1f00000, v54
	v_mul_f32_e32 v52, 0xbfb8aa3b, v52
	v_max_f32_e32 v48, 0xc1f00000, v48
	v_exp_f32_e32 v52, v52
	v_mul_f32_e32 v48, 0xbfb8aa3b, v48
	v_exp_f32_e32 v48, v48
	v_cvt_pk_f16_f32 v47, v46, v47
	v_add_f32_e32 v46, 1.0, v52
	v_rcp_f32_e32 v52, v46
	v_add_f32_e32 v46, 1.0, v48
	v_rcp_f32_e32 v53, v46
	v_pk_mov_b32 v[48:49], v[48:49], v[42:43] op_sel:[1,0]
	v_cvt_f32_f16_sdwa v42, v88 dst_sel:DWORD dst_unused:UNUSED_PAD src0_sel:WORD_1
	v_pack_b32_f16 v46, v55, v47
	v_pk_mul_f32 v[48:49], v[48:49], v[52:53]
	v_cvt_f32_f16_sdwa v53, v89 dst_sel:DWORD dst_unused:UNUSED_PAD src0_sel:WORD_1
	v_cvt_pk_f16_f32 v52, v48, v49
	v_cvt_f32_f16_e32 v48, v89
	v_max_f32_e32 v42, 0xc1f00000, v42
	v_mul_f32_e32 v42, 0xbfb8aa3b, v42
	v_exp_f32_e32 v42, v42
	v_max_f32_e32 v48, 0xc1f00000, v48
	v_mul_f32_e32 v48, 0xbfb8aa3b, v48
	v_exp_f32_e32 v49, v48
	v_add_f32_e32 v42, 1.0, v42
	v_rcp_f32_e32 v48, v42
	v_alignbit_b32 v47, v52, v47, 16
	v_add_f32_e32 v42, 1.0, v49
	v_rcp_f32_e32 v49, v42
	v_mov_b32_e32 v42, v43
	v_mov_b32_e32 v43, v44
	v_cvt_f32_f16_e32 v44, v82
	v_pk_mul_f32 v[42:43], v[42:43], v[48:49]
	global_store_dwordx4 v[98:99], v[62:65], off
	v_cvt_pk_f16_f32 v42, v42, v43
	v_max_f32_e32 v43, 0xc1f00000, v53
	v_mul_f32_e32 v43, 0xbfb8aa3b, v43
	v_exp_f32_e32 v43, v43
	v_alignbit_b32 v48, v42, v52, 16
	v_lshrrev_b32_e32 v49, 16, v42
	v_add_f32_e32 v42, 1.0, v43
	v_rcp_f32_e32 v42, v42
	v_max_f32_e32 v43, 0xc1f00000, v44
	v_mul_f32_e32 v43, 0xbfb8aa3b, v43
	v_exp_f32_e32 v43, v43
	v_fma_mixhi_f16 v49, v45, v42, 0
	v_cvt_f32_f16_sdwa v42, v82 dst_sel:DWORD dst_unused:UNUSED_PAD src0_sel:WORD_1
	v_cvt_f32_f16_e32 v44, v83
	v_add_f32_e32 v43, 1.0, v43
	v_rcp_f32_e32 v43, v43
	v_max_f32_e32 v42, 0xc1f00000, v42
	v_mul_f32_e32 v42, 0xbfb8aa3b, v42
	v_max_f32_e32 v44, 0xc1f00000, v44
	v_exp_f32_e32 v42, v42
	v_mul_f32_e32 v44, 0xbfb8aa3b, v44
	v_exp_f32_e32 v44, v44
	v_fma_mixlo_f16 v45, v38, v43, 0
	v_add_f32_e32 v38, 1.0, v42
	v_rcp_f32_e32 v42, v38
	v_add_f32_e32 v38, 1.0, v44
	v_rcp_f32_e32 v43, v38
	v_cvt_f32_f16_sdwa v44, v83 dst_sel:DWORD dst_unused:UNUSED_PAD src0_sel:WORD_1
	v_mov_b32_e32 v38, v39
	v_mov_b32_e32 v39, v40
	v_cvt_f32_f16_e32 v40, v84
	v_max_f32_e32 v44, 0xc1f00000, v44
	v_mul_f32_e32 v44, 0xbfb8aa3b, v44
	v_exp_f32_e32 v44, v44
	v_max_f32_e32 v40, 0xc1f00000, v40
	v_mul_f32_e32 v40, 0xbfb8aa3b, v40
	v_exp_f32_e32 v40, v40
	v_pk_mul_f32 v[38:39], v[38:39], v[42:43]
	v_add_f32_e32 v42, 1.0, v44
	v_rcp_f32_e32 v42, v42
	v_add_f32_e32 v40, 1.0, v40
	v_rcp_f32_e32 v43, v40
	v_pk_mov_b32 v[40:41], v[40:41], v[34:35] op_sel:[1,0]
	v_cvt_f32_f16_sdwa v34, v84 dst_sel:DWORD dst_unused:UNUSED_PAD src0_sel:WORD_1
	v_cvt_pk_f16_f32 v39, v38, v39
	v_pk_mul_f32 v[40:41], v[40:41], v[42:43]
	v_cvt_f32_f16_sdwa v43, v85 dst_sel:DWORD dst_unused:UNUSED_PAD src0_sel:WORD_1
	v_cvt_pk_f16_f32 v42, v40, v41
	v_cvt_f32_f16_e32 v40, v85
	v_max_f32_e32 v34, 0xc1f00000, v34
	v_mul_f32_e32 v34, 0xbfb8aa3b, v34
	v_exp_f32_e32 v34, v34
	v_max_f32_e32 v40, 0xc1f00000, v40
	v_mul_f32_e32 v40, 0xbfb8aa3b, v40
	v_exp_f32_e32 v41, v40
	v_add_f32_e32 v34, 1.0, v34
	v_rcp_f32_e32 v40, v34
	v_pack_b32_f16 v38, v45, v39
	v_add_f32_e32 v34, 1.0, v41
	v_rcp_f32_e32 v41, v34
	v_mov_b32_e32 v34, v35
	v_max_f32_e32 v35, 0xc1f00000, v43
	v_mul_f32_e32 v35, 0xbfb8aa3b, v35
	v_exp_f32_e32 v43, v35
	v_mov_b32_e32 v35, v36
	v_pk_mul_f32 v[34:35], v[34:35], v[40:41]
	v_cvt_f32_f16_e32 v36, v78
	v_cvt_pk_f16_f32 v34, v34, v35
	v_add_f32_e32 v35, 1.0, v43
	v_rcp_f32_e32 v35, v35
	v_alignbit_b32 v40, v34, v42, 16
	v_lshrrev_b32_e32 v41, 16, v34
	v_max_f32_e32 v34, 0xc1f00000, v36
	v_alignbit_b32 v39, v42, v39, 16
	v_fma_mixhi_f16 v41, v37, v35, 0
	v_mul_f32_e32 v34, 0xbfb8aa3b, v34
	v_cvt_f32_f16_sdwa v37, v78 dst_sel:DWORD dst_unused:UNUSED_PAD src0_sel:WORD_1
	v_exp_f32_e32 v36, v34
	global_store_dwordx4 v[50:51], v[38:41], off offset:256
	v_lshl_add_u64 v[34:35], v[192:193], 0, v[184:185]
	v_max_f32_e32 v37, 0xc1f00000, v37
	v_cvt_f32_f16_e32 v38, v79
	v_add_f32_e32 v36, 1.0, v36
	v_mul_f32_e32 v37, 0xbfb8aa3b, v37
	v_rcp_f32_e32 v36, v36
	v_max_f32_e32 v38, 0xc1f00000, v38
	v_exp_f32_e32 v37, v37
	v_mul_f32_e32 v38, 0xbfb8aa3b, v38
	v_exp_f32_e32 v38, v38
	v_fma_mixlo_f16 v39, v28, v36, 0
	v_add_f32_e32 v28, 1.0, v37
	v_rcp_f32_e32 v36, v28
	v_add_f32_e32 v28, 1.0, v38
	v_rcp_f32_e32 v37, v28
	v_cvt_f32_f16_sdwa v38, v79 dst_sel:DWORD dst_unused:UNUSED_PAD src0_sel:WORD_1
	v_mov_b32_e32 v28, v29
	v_mov_b32_e32 v29, v30
	v_cvt_f32_f16_e32 v30, v80
	v_pk_mul_f32 v[28:29], v[28:29], v[36:37]
	v_max_f32_e32 v36, 0xc1f00000, v38
	v_mul_f32_e32 v36, 0xbfb8aa3b, v36
	v_max_f32_e32 v30, 0xc1f00000, v30
	v_exp_f32_e32 v36, v36
	v_mul_f32_e32 v30, 0xbfb8aa3b, v30
	v_exp_f32_e32 v30, v30
	v_cvt_pk_f16_f32 v29, v28, v29
	v_add_f32_e32 v28, 1.0, v36
	v_rcp_f32_e32 v36, v28
	v_add_f32_e32 v28, 1.0, v30
	v_rcp_f32_e32 v37, v28
	v_pk_mov_b32 v[30:31], v[30:31], v[24:25] op_sel:[1,0]
	v_cvt_f32_f16_sdwa v24, v80 dst_sel:DWORD dst_unused:UNUSED_PAD src0_sel:WORD_1
	v_pack_b32_f16 v28, v39, v29
	v_pk_mul_f32 v[30:31], v[30:31], v[36:37]
	v_cvt_f32_f16_sdwa v37, v81 dst_sel:DWORD dst_unused:UNUSED_PAD src0_sel:WORD_1
	v_cvt_pk_f16_f32 v36, v30, v31
	v_cvt_f32_f16_e32 v30, v81
	v_max_f32_e32 v24, 0xc1f00000, v24
	v_mul_f32_e32 v24, 0xbfb8aa3b, v24
	v_exp_f32_e32 v24, v24
	v_max_f32_e32 v30, 0xc1f00000, v30
	v_mul_f32_e32 v30, 0xbfb8aa3b, v30
	v_exp_f32_e32 v31, v30
	v_add_f32_e32 v24, 1.0, v24
	v_rcp_f32_e32 v30, v24
	v_alignbit_b32 v29, v36, v29, 16
	v_add_f32_e32 v24, 1.0, v31
	v_rcp_f32_e32 v31, v24
	v_mov_b32_e32 v24, v25
	v_mov_b32_e32 v25, v26
	v_cvt_f32_f16_e32 v26, v74
	v_pk_mul_f32 v[24:25], v[24:25], v[30:31]
	global_store_dwordx4 v[50:51], v[46:49], off
	v_cvt_pk_f16_f32 v24, v24, v25
	v_max_f32_e32 v25, 0xc1f00000, v37
	v_mul_f32_e32 v25, 0xbfb8aa3b, v25
	v_exp_f32_e32 v25, v25
	v_alignbit_b32 v30, v24, v36, 16
	v_lshrrev_b32_e32 v31, 16, v24
	v_add_f32_e32 v24, 1.0, v25
	v_rcp_f32_e32 v24, v24
	v_max_f32_e32 v25, 0xc1f00000, v26
	v_mul_f32_e32 v25, 0xbfb8aa3b, v25
	v_exp_f32_e32 v25, v25
	v_fma_mixhi_f16 v31, v27, v24, 0
	v_cvt_f32_f16_sdwa v24, v74 dst_sel:DWORD dst_unused:UNUSED_PAD src0_sel:WORD_1
	v_cvt_f32_f16_e32 v26, v75
	v_add_f32_e32 v25, 1.0, v25
	v_rcp_f32_e32 v25, v25
	v_max_f32_e32 v24, 0xc1f00000, v24
	v_mul_f32_e32 v24, 0xbfb8aa3b, v24
	v_max_f32_e32 v26, 0xc1f00000, v26
	v_exp_f32_e32 v24, v24
	v_mul_f32_e32 v26, 0xbfb8aa3b, v26
	v_exp_f32_e32 v26, v26
	v_fma_mixlo_f16 v27, v20, v25, 0
	v_add_f32_e32 v20, 1.0, v24
	v_rcp_f32_e32 v24, v20
	v_add_f32_e32 v20, 1.0, v26
	v_rcp_f32_e32 v25, v20
	v_cvt_f32_f16_sdwa v26, v75 dst_sel:DWORD dst_unused:UNUSED_PAD src0_sel:WORD_1
	v_mov_b32_e32 v20, v21
	v_mov_b32_e32 v21, v22
	v_cvt_f32_f16_e32 v22, v76
	v_max_f32_e32 v26, 0xc1f00000, v26
	v_mul_f32_e32 v26, 0xbfb8aa3b, v26
	v_exp_f32_e32 v26, v26
	v_max_f32_e32 v22, 0xc1f00000, v22
	v_mul_f32_e32 v22, 0xbfb8aa3b, v22
	v_exp_f32_e32 v22, v22
	v_pk_mul_f32 v[20:21], v[20:21], v[24:25]
	v_add_f32_e32 v24, 1.0, v26
	v_rcp_f32_e32 v24, v24
	v_add_f32_e32 v22, 1.0, v22
	v_rcp_f32_e32 v25, v22
	v_pk_mov_b32 v[22:23], v[22:23], v[16:17] op_sel:[1,0]
	v_cvt_f32_f16_sdwa v16, v76 dst_sel:DWORD dst_unused:UNUSED_PAD src0_sel:WORD_1
	v_cvt_pk_f16_f32 v21, v20, v21
	v_pk_mul_f32 v[22:23], v[22:23], v[24:25]
	v_cvt_f32_f16_sdwa v25, v77 dst_sel:DWORD dst_unused:UNUSED_PAD src0_sel:WORD_1
	v_cvt_pk_f16_f32 v24, v22, v23
	v_cvt_f32_f16_e32 v22, v77
	v_max_f32_e32 v16, 0xc1f00000, v16
	v_mul_f32_e32 v16, 0xbfb8aa3b, v16
	v_exp_f32_e32 v16, v16
	v_max_f32_e32 v22, 0xc1f00000, v22
	v_mul_f32_e32 v22, 0xbfb8aa3b, v22
	v_exp_f32_e32 v23, v22
	v_add_f32_e32 v16, 1.0, v16
	v_rcp_f32_e32 v22, v16
	v_pack_b32_f16 v20, v27, v21
	v_add_f32_e32 v16, 1.0, v23
	v_rcp_f32_e32 v23, v16
	v_mov_b32_e32 v16, v17
	v_max_f32_e32 v17, 0xc1f00000, v25
	v_mul_f32_e32 v17, 0xbfb8aa3b, v17
	v_exp_f32_e32 v25, v17
	v_mov_b32_e32 v17, v18
	v_pk_mul_f32 v[16:17], v[16:17], v[22:23]
	v_cvt_f32_f16_e32 v18, v70
	v_cvt_pk_f16_f32 v16, v16, v17
	v_add_f32_e32 v17, 1.0, v25
	v_rcp_f32_e32 v17, v17
	v_alignbit_b32 v22, v16, v24, 16
	v_lshrrev_b32_e32 v23, 16, v16
	v_max_f32_e32 v16, 0xc1f00000, v18
	v_alignbit_b32 v21, v24, v21, 16
	v_fma_mixhi_f16 v23, v19, v17, 0
	v_mul_f32_e32 v16, 0xbfb8aa3b, v16
	v_cvt_f32_f16_sdwa v19, v70 dst_sel:DWORD dst_unused:UNUSED_PAD src0_sel:WORD_1
	v_exp_f32_e32 v18, v16
	global_store_dwordx4 v[34:35], v[20:23], off offset:256
	v_lshl_add_u64 v[16:17], v[192:193], 0, v[186:187]
	v_max_f32_e32 v19, 0xc1f00000, v19
	v_cvt_f32_f16_e32 v20, v71
	v_add_f32_e32 v18, 1.0, v18
	v_mul_f32_e32 v19, 0xbfb8aa3b, v19
	v_rcp_f32_e32 v18, v18
	v_max_f32_e32 v20, 0xc1f00000, v20
	v_exp_f32_e32 v19, v19
	v_mul_f32_e32 v20, 0xbfb8aa3b, v20
	v_exp_f32_e32 v20, v20
	v_fma_mixlo_f16 v21, v12, v18, 0
	v_add_f32_e32 v12, 1.0, v19
	v_rcp_f32_e32 v18, v12
	v_add_f32_e32 v12, 1.0, v20
	v_rcp_f32_e32 v19, v12
	v_cvt_f32_f16_sdwa v20, v71 dst_sel:DWORD dst_unused:UNUSED_PAD src0_sel:WORD_1
	v_mov_b32_e32 v12, v13
	v_mov_b32_e32 v13, v14
	v_cvt_f32_f16_e32 v14, v72
	v_pk_mul_f32 v[12:13], v[12:13], v[18:19]
	v_max_f32_e32 v18, 0xc1f00000, v20
	v_mul_f32_e32 v18, 0xbfb8aa3b, v18
	v_max_f32_e32 v14, 0xc1f00000, v14
	v_exp_f32_e32 v18, v18
	v_mul_f32_e32 v14, 0xbfb8aa3b, v14
	v_exp_f32_e32 v14, v14
	v_cvt_pk_f16_f32 v13, v12, v13
	v_add_f32_e32 v12, 1.0, v18
	v_rcp_f32_e32 v18, v12
	v_add_f32_e32 v12, 1.0, v14
	v_rcp_f32_e32 v19, v12
	v_pk_mov_b32 v[14:15], v[14:15], v[8:9] op_sel:[1,0]
	v_cvt_f32_f16_sdwa v8, v72 dst_sel:DWORD dst_unused:UNUSED_PAD src0_sel:WORD_1
	v_pack_b32_f16 v12, v21, v13
	v_pk_mul_f32 v[14:15], v[14:15], v[18:19]
	v_cvt_f32_f16_sdwa v19, v73 dst_sel:DWORD dst_unused:UNUSED_PAD src0_sel:WORD_1
	v_cvt_pk_f16_f32 v18, v14, v15
	v_cvt_f32_f16_e32 v14, v73
	v_max_f32_e32 v8, 0xc1f00000, v8
	v_mul_f32_e32 v8, 0xbfb8aa3b, v8
	v_exp_f32_e32 v8, v8
	v_max_f32_e32 v14, 0xc1f00000, v14
	v_mul_f32_e32 v14, 0xbfb8aa3b, v14
	v_exp_f32_e32 v15, v14
	v_add_f32_e32 v8, 1.0, v8
	v_rcp_f32_e32 v14, v8
	v_alignbit_b32 v13, v18, v13, 16
	v_add_f32_e32 v8, 1.0, v15
	v_rcp_f32_e32 v15, v8
	v_mov_b32_e32 v8, v9
	v_mov_b32_e32 v9, v10
	v_cvt_f32_f16_e32 v10, v66
	v_pk_mul_f32 v[8:9], v[8:9], v[14:15]
	global_store_dwordx4 v[34:35], v[28:31], off
	v_cvt_pk_f16_f32 v8, v8, v9
	v_max_f32_e32 v9, 0xc1f00000, v19
	v_mul_f32_e32 v9, 0xbfb8aa3b, v9
	v_exp_f32_e32 v9, v9
	v_alignbit_b32 v14, v8, v18, 16
	v_lshrrev_b32_e32 v15, 16, v8
	v_add_f32_e32 v8, 1.0, v9
	v_rcp_f32_e32 v8, v8
	v_max_f32_e32 v9, 0xc1f00000, v10
	v_mul_f32_e32 v9, 0xbfb8aa3b, v9
	v_exp_f32_e32 v9, v9
	v_fma_mixhi_f16 v15, v11, v8, 0
	v_cvt_f32_f16_sdwa v8, v66 dst_sel:DWORD dst_unused:UNUSED_PAD src0_sel:WORD_1
	v_cvt_f32_f16_e32 v10, v67
	v_add_f32_e32 v9, 1.0, v9
	v_rcp_f32_e32 v9, v9
	v_max_f32_e32 v8, 0xc1f00000, v8
	v_mul_f32_e32 v8, 0xbfb8aa3b, v8
	v_max_f32_e32 v10, 0xc1f00000, v10
	v_exp_f32_e32 v8, v8
	v_mul_f32_e32 v10, 0xbfb8aa3b, v10
	v_exp_f32_e32 v10, v10
	v_fma_mixlo_f16 v11, v4, v9, 0
	v_add_f32_e32 v4, 1.0, v8
	v_rcp_f32_e32 v8, v4
	v_add_f32_e32 v4, 1.0, v10
	v_rcp_f32_e32 v9, v4
	v_cvt_f32_f16_sdwa v10, v67 dst_sel:DWORD dst_unused:UNUSED_PAD src0_sel:WORD_1
	v_mov_b32_e32 v4, v5
	v_mov_b32_e32 v5, v6
	v_cvt_f32_f16_e32 v6, v68
	v_max_f32_e32 v10, 0xc1f00000, v10
	v_mul_f32_e32 v10, 0xbfb8aa3b, v10
	v_exp_f32_e32 v10, v10
	v_max_f32_e32 v6, 0xc1f00000, v6
	v_mul_f32_e32 v6, 0xbfb8aa3b, v6
	v_exp_f32_e32 v6, v6
	v_pk_mul_f32 v[4:5], v[4:5], v[8:9]
	v_add_f32_e32 v8, 1.0, v10
	v_rcp_f32_e32 v8, v8
	v_add_f32_e32 v6, 1.0, v6
	v_rcp_f32_e32 v9, v6
	v_pk_mov_b32 v[6:7], v[6:7], v[0:1] op_sel:[1,0]
	v_cvt_f32_f16_sdwa v0, v68 dst_sel:DWORD dst_unused:UNUSED_PAD src0_sel:WORD_1
	v_cvt_pk_f16_f32 v5, v4, v5
	v_pk_mul_f32 v[6:7], v[6:7], v[8:9]
	v_cvt_f32_f16_sdwa v9, v69 dst_sel:DWORD dst_unused:UNUSED_PAD src0_sel:WORD_1
	v_cvt_pk_f16_f32 v8, v6, v7
	v_cvt_f32_f16_e32 v6, v69
	v_max_f32_e32 v0, 0xc1f00000, v0
	v_mul_f32_e32 v0, 0xbfb8aa3b, v0
	v_exp_f32_e32 v0, v0
	v_max_f32_e32 v6, 0xc1f00000, v6
	v_mul_f32_e32 v6, 0xbfb8aa3b, v6
	v_exp_f32_e32 v7, v6
	v_add_f32_e32 v0, 1.0, v0
	v_rcp_f32_e32 v6, v0
	v_pack_b32_f16 v4, v11, v5
	v_add_f32_e32 v0, 1.0, v7
	v_rcp_f32_e32 v7, v0
	v_max_f32_e32 v0, 0xc1f00000, v9
	v_mul_f32_e32 v0, 0xbfb8aa3b, v0
	v_exp_f32_e32 v9, v0
	v_mov_b32_e32 v0, v1
	v_mov_b32_e32 v1, v2
	v_pk_mul_f32 v[0:1], v[0:1], v[6:7]
	v_add_f32_e32 v2, 1.0, v9
	v_rcp_f32_e32 v2, v2
	v_cvt_pk_f16_f32 v0, v0, v1
	v_lshrrev_b32_e32 v7, 16, v0
	v_alignbit_b32 v5, v8, v5, 16
	v_alignbit_b32 v6, v0, v8, 16
	v_fma_mixhi_f16 v7, v3, v2, 0
	global_store_dwordx4 v[16:17], v[12:15], off
	global_store_dwordx4 v[16:17], v[4:7], off offset:256
	s_and_b64 vcc, exec, s[4:5]
	s_mov_b32 s31, s30
	s_mov_b32 s34, s29
	s_mov_b64 s[12:13], s[0:1]
	s_mov_b64 s[10:11], s[2:3]
	s_cbranch_vccz .LBB0_955
	s_waitcnt vmcnt(0)
	s_cmpk_gt_u32 s19, 0xff
	s_cbranch_scc1 .LBB0_962
	s_barrier

.LBB0_1117:
	s_add_i32 s41, s22, 2
	s_add_u32 s20, s14, 0x100
	s_addc_u32 s21, s15, 0
	s_add_i32 s42, 0, 0x10000
	s_waitcnt vmcnt(0)
	v_add_u32_e32 v102, s42, v230
	ds_read_b128 v[78:81], v102
	ds_read_b128 v[94:97], v102 offset:2048
	ds_read_b128 v[86:89], v102 offset:1024
	ds_read_b128 v[102:105], v102 offset:3072
	s_cmp_eq_u32 s38, s22
	s_cselect_b32 s22, s18, s39
	s_cselect_b32 s25, s17, s21
	s_cselect_b32 s24, s16, s20
	s_cselect_b32 s23, s19, s40
	v_lshl_add_u64 v[178:179], s[14:15], 0, v[200:201]
	s_add_i32 m0, s28, 0xc000
	ds_read_b128 v[122:125], v232
	ds_read_b128 v[130:133], v232 offset:2048
	ds_read_b128 v[154:157], v232 offset:4096
	ds_read_b128 v[170:173], v232 offset:6144
	ds_read_b128 v[126:129], v232 offset:1024
	ds_read_b128 v[134:137], v232 offset:3072
	ds_read_b128 v[158:161], v232 offset:5120
	ds_read_b128 v[174:177], v232 offset:7168
	global_load_lds_dwordx4 v[178:179], off
	v_lshl_add_u64 v[178:179], s[14:15], 0, v[202:203]
	s_add_i32 m0, s28, 0xe000
	s_nop 0
	global_load_lds_dwordx4 v[178:179], off
	s_waitcnt lgkmcnt(8)
	s_barrier
	s_waitcnt lgkmcnt(6)
	s_setprio 1
	v_mfma_f32_16x16x32_f16 v[166:169], v[78:81], v[122:125], v[166:169]
	v_mfma_f32_16x16x32_f16 v[162:165], v[94:97], v[122:125], v[162:165]
	v_mfma_f32_16x16x32_f16 v[150:153], v[78:81], v[130:133], v[150:153]
	v_mfma_f32_16x16x32_f16 v[142:145], v[94:97], v[130:133], v[142:145]
	s_waitcnt lgkmcnt(4)
	v_mfma_f32_16x16x32_f16 v[110:113], v[78:81], v[154:157], v[110:113]
	v_mfma_f32_16x16x32_f16 v[106:109], v[94:97], v[154:157], v[106:109]
	v_mfma_f32_16x16x32_f16 v[82:85], v[78:81], v[170:173], v[82:85]
	v_mfma_f32_16x16x32_f16 v[74:77], v[94:97], v[170:173], v[74:77]
	s_waitcnt lgkmcnt(2)
	v_mfma_f32_16x16x32_f16 v[166:169], v[86:89], v[126:129], v[166:169]
	v_mfma_f32_16x16x32_f16 v[162:165], v[102:105], v[126:129], v[162:165]
	v_mfma_f32_16x16x32_f16 v[150:153], v[86:89], v[134:137], v[150:153]
	v_mfma_f32_16x16x32_f16 v[142:145], v[102:105], v[134:137], v[142:145]
	s_waitcnt lgkmcnt(0)
	v_mfma_f32_16x16x32_f16 v[110:113], v[86:89], v[158:161], v[110:113]
	v_mfma_f32_16x16x32_f16 v[106:109], v[102:105], v[158:161], v[106:109]
	v_mfma_f32_16x16x32_f16 v[82:85], v[86:89], v[174:177], v[82:85]
	v_mfma_f32_16x16x32_f16 v[74:77], v[102:105], v[174:177], v[74:77]
	s_setprio 0
	s_barrier
	s_add_i32 s43, 0, 0x14000
	s_add_i32 s14, s42, s13
	v_add_u32_e32 v190, s43, v230
	v_lshl_add_u64 v[204:205], s[22:23], 0, v[32:33]
	s_mov_b32 m0, s14
	ds_read_b128 v[178:181], v190
	ds_read_b128 v[186:189], v190 offset:2048
	ds_read_b128 v[182:185], v190 offset:1024
	ds_read_b128 v[190:193], v190 offset:3072
	global_load_lds_dwordx4 v[204:205], off
	v_lshl_add_u64 v[206:207], s[22:23], 0, v[198:199]
	s_add_i32 m0, s14, 0x2000
	s_nop 0
	global_load_lds_dwordx4 v[206:207], off
	s_barrier
	s_waitcnt lgkmcnt(2)
	s_setprio 1
	v_mfma_f32_16x16x32_f16 v[146:149], v[178:181], v[122:125], v[146:149]
	v_mfma_f32_16x16x32_f16 v[118:121], v[178:181], v[130:133], v[118:121]
	v_mfma_f32_16x16x32_f16 v[114:117], v[186:189], v[130:133], v[114:117]
	v_mfma_f32_16x16x32_f16 v[98:101], v[178:181], v[154:157], v[98:101]
	s_waitcnt lgkmcnt(1)
	v_mfma_f32_16x16x32_f16 v[90:93], v[186:189], v[154:157], v[90:93]
	v_mfma_f32_16x16x32_f16 v[70:73], v[178:181], v[170:173], v[70:73]
	v_mfma_f32_16x16x32_f16 v[66:69], v[186:189], v[170:173], v[66:69]
	v_mfma_f32_16x16x32_f16 v[146:149], v[182:185], v[126:129], v[146:149]
	s_waitcnt lgkmcnt(0)
	v_mfma_f32_16x16x32_f16 v[122:125], v[186:189], v[122:125], v[138:141]
	v_mfma_f32_16x16x32_f16 v[118:121], v[182:185], v[134:137], v[118:121]
	v_mfma_f32_16x16x32_f16 v[114:117], v[190:193], v[134:137], v[114:117]
	v_mfma_f32_16x16x32_f16 v[98:101], v[182:185], v[158:161], v[98:101]
	v_mfma_f32_16x16x32_f16 v[90:93], v[190:193], v[158:161], v[90:93]
	v_mfma_f32_16x16x32_f16 v[70:73], v[182:185], v[174:177], v[70:73]
	v_mfma_f32_16x16x32_f16 v[66:69], v[190:193], v[174:177], v[66:69]
	v_mfma_f32_16x16x32_f16 v[122:125], v[190:193], v[126:129], v[122:125]
	s_setprio 0
	s_mov_b32 m0, s28
	v_lshl_add_u64 v[208:209], s[24:25], 0, v[32:33]
	s_barrier
	ds_read_b128 v[126:129], v232 offset:16384
	ds_read_b128 v[134:137], v232 offset:18432
	ds_read_b128 v[154:157], v232 offset:20480
	ds_read_b128 v[170:173], v232 offset:22528
	ds_read_b128 v[130:133], v232 offset:17408
	ds_read_b128 v[138:141], v232 offset:19456
	ds_read_b128 v[158:161], v232 offset:21504
	ds_read_b128 v[174:177], v232 offset:23552
	global_load_lds_dwordx4 v[208:209], off
	v_lshl_add_u64 v[210:211], s[24:25], 0, v[198:199]
	s_mov_b32 m0, s29
	s_nop 0
	global_load_lds_dwordx4 v[210:211], off
	s_barrier
	s_waitcnt lgkmcnt(6)
	s_setprio 1
	v_mfma_f32_16x16x32_f16 v[62:65], v[78:81], v[126:129], v[62:65]
	v_mfma_f32_16x16x32_f16 v[58:61], v[94:97], v[126:129], v[58:61]
	v_mfma_f32_16x16x32_f16 v[46:49], v[78:81], v[134:137], v[46:49]
	v_mfma_f32_16x16x32_f16 v[42:45], v[94:97], v[134:137], v[42:45]
	s_waitcnt lgkmcnt(4)
	v_mfma_f32_16x16x32_f16 v[28:31], v[78:81], v[154:157], v[28:31]
	v_mfma_f32_16x16x32_f16 v[24:27], v[94:97], v[154:157], v[24:27]
	v_mfma_f32_16x16x32_f16 v[12:15], v[78:81], v[170:173], v[12:15]
	v_mfma_f32_16x16x32_f16 v[8:11], v[94:97], v[170:173], v[8:11]
	s_waitcnt lgkmcnt(2)
	v_mfma_f32_16x16x32_f16 v[62:65], v[86:89], v[130:133], v[62:65]
	v_mfma_f32_16x16x32_f16 v[58:61], v[102:105], v[130:133], v[58:61]
	v_mfma_f32_16x16x32_f16 v[46:49], v[86:89], v[138:141], v[46:49]
	v_mfma_f32_16x16x32_f16 v[42:45], v[102:105], v[138:141], v[42:45]
	s_waitcnt lgkmcnt(0)
	v_mfma_f32_16x16x32_f16 v[28:31], v[86:89], v[158:161], v[28:31]
	v_mfma_f32_16x16x32_f16 v[24:27], v[102:105], v[158:161], v[24:27]
	v_mfma_f32_16x16x32_f16 v[12:15], v[86:89], v[174:177], v[12:15]
	v_mfma_f32_16x16x32_f16 v[8:11], v[102:105], v[174:177], v[8:11]
	s_setprio 0
	s_barrier
	s_add_u32 s14, s22, 0x40000
	s_addc_u32 s15, s23, 0
	s_add_i32 s42, s43, s13
	v_lshl_add_u64 v[78:79], s[14:15], 0, v[32:33]
	s_mov_b32 m0, s42
	s_nop 0
	global_load_lds_dwordx4 v[78:79], off
	v_lshl_add_u64 v[78:79], s[14:15], 0, v[198:199]
	s_add_i32 m0, s42, 0x2000
	s_nop 0
	global_load_lds_dwordx4 v[78:79], off
	s_waitcnt vmcnt(6)
	s_barrier
	s_setprio 1
	v_mfma_f32_16x16x32_f16 v[54:57], v[178:181], v[126:129], v[54:57]
	v_mfma_f32_16x16x32_f16 v[50:53], v[186:189], v[126:129], v[50:53]
	v_mfma_f32_16x16x32_f16 v[38:41], v[178:181], v[134:137], v[38:41]
	v_mfma_f32_16x16x32_f16 v[34:37], v[186:189], v[134:137], v[34:37]
	v_mfma_f32_16x16x32_f16 v[20:23], v[178:181], v[154:157], v[20:23]
	v_mfma_f32_16x16x32_f16 v[16:19], v[186:189], v[154:157], v[16:19]
	v_mfma_f32_16x16x32_f16 v[4:7], v[178:181], v[170:173], v[4:7]
	v_mfma_f32_16x16x32_f16 v[0:3], v[186:189], v[170:173], v[0:3]
	v_mfma_f32_16x16x32_f16 v[54:57], v[182:185], v[130:133], v[54:57]
	v_mfma_f32_16x16x32_f16 v[50:53], v[190:193], v[130:133], v[50:53]
	v_mfma_f32_16x16x32_f16 v[38:41], v[182:185], v[138:141], v[38:41]
	v_mfma_f32_16x16x32_f16 v[34:37], v[190:193], v[138:141], v[34:37]
	v_mfma_f32_16x16x32_f16 v[20:23], v[182:185], v[158:161], v[20:23]
	v_mfma_f32_16x16x32_f16 v[16:19], v[190:193], v[158:161], v[16:19]
	v_mfma_f32_16x16x32_f16 v[4:7], v[182:185], v[174:177], v[4:7]
	v_mfma_f32_16x16x32_f16 v[0:3], v[190:193], v[174:177], v[0:3]
	s_setprio 0
	s_add_i32 s42, 0, 0x18000
	v_add_u32_e32 v102, s42, v230
	s_barrier
	ds_read_b128 v[78:81], v102
	ds_read_b128 v[86:89], v102 offset:1024
	ds_read_b128 v[94:97], v102 offset:2048
	ds_read_b128 v[102:105], v102 offset:3072
	s_add_u32 s14, s24, 0x40000
	s_addc_u32 s15, s25, 0
	s_mov_b32 m0, s30
	v_lshl_add_u64 v[138:139], s[14:15], 0, v[32:33]
	ds_read_b128 v[126:129], v232 offset:32768
	ds_read_b128 v[130:133], v232 offset:33792
	ds_read_b128 v[134:137], v232 offset:34816
	ds_read_b128 v[154:157], v232 offset:35840
	ds_read_b128 v[158:161], v232 offset:36864
	ds_read_b128 v[174:177], v232 offset:38912
	ds_read_b128 v[170:173], v232 offset:37888
	ds_read_b128 v[178:181], v232 offset:39936
	global_load_lds_dwordx4 v[138:139], off
	v_lshl_add_u64 v[138:139], s[14:15], 0, v[198:199]
	s_mov_b32 m0, s31
	s_nop 0
	global_load_lds_dwordx4 v[138:139], off
	s_waitcnt lgkmcnt(8)
	s_barrier
	s_waitcnt lgkmcnt(6)
	s_setprio 1
	v_mfma_f32_16x16x32_f16 v[138:141], v[78:81], v[126:129], v[166:169]
	v_mfma_f32_16x16x32_f16 v[166:169], v[86:89], v[130:133], v[138:141]
	v_mfma_f32_16x16x32_f16 v[138:141], v[94:97], v[126:129], v[162:165]
	v_mfma_f32_16x16x32_f16 v[162:165], v[102:105], v[130:133], v[138:141]
	s_waitcnt lgkmcnt(3)
	v_mfma_f32_16x16x32_f16 v[138:141], v[78:81], v[134:137], v[150:153]
	v_mfma_f32_16x16x32_f16 v[150:153], v[86:89], v[154:157], v[138:141]
	v_mfma_f32_16x16x32_f16 v[138:141], v[94:97], v[134:137], v[142:145]
	v_mfma_f32_16x16x32_f16 v[110:113], v[78:81], v[158:161], v[110:113]
	s_waitcnt lgkmcnt(2)
	v_mfma_f32_16x16x32_f16 v[106:109], v[94:97], v[158:161], v[106:109]
	v_mfma_f32_16x16x32_f16 v[82:85], v[78:81], v[174:177], v[82:85]
	v_mfma_f32_16x16x32_f16 v[74:77], v[94:97], v[174:177], v[74:77]
	v_mfma_f32_16x16x32_f16 v[142:145], v[102:105], v[154:157], v[138:141]
	s_waitcnt lgkmcnt(0)
	v_mfma_f32_16x16x32_f16 v[110:113], v[86:89], v[170:173], v[110:113]
	v_mfma_f32_16x16x32_f16 v[106:109], v[102:105], v[170:173], v[106:109]
	v_mfma_f32_16x16x32_f16 v[82:85], v[86:89], v[178:181], v[82:85]
	v_mfma_f32_16x16x32_f16 v[74:77], v[102:105], v[178:181], v[74:77]
	s_setprio 0
	s_barrier
	s_add_i32 s24, 0, 0x1c000
	v_add_u32_e32 v138, s24, v230
	s_add_i32 s14, s42, s13
	ds_read_b128 v[182:185], v138
	ds_read_b128 v[190:193], v138 offset:2048
	ds_read_b128 v[186:189], v138 offset:1024
	ds_read_b128 v[194:197], v138 offset:3072
	v_lshl_add_u64 v[138:139], v[204:205], 0, s[84:85]
	s_mov_b32 m0, s14
	s_nop 0
	global_load_lds_dwordx4 v[138:139], off
	v_lshl_add_u64 v[138:139], v[206:207], 0, s[84:85]
	s_add_i32 m0, s14, 0x2000
	s_nop 0
	global_load_lds_dwordx4 v[138:139], off
	s_barrier
	s_waitcnt lgkmcnt(2)
	s_setprio 1
	v_mfma_f32_16x16x32_f16 v[138:141], v[182:185], v[126:129], v[146:149]
	v_mfma_f32_16x16x32_f16 v[122:125], v[190:193], v[126:129], v[122:125]
	v_mfma_f32_16x16x32_f16 v[118:121], v[182:185], v[134:137], v[118:121]
	v_mfma_f32_16x16x32_f16 v[114:117], v[190:193], v[134:137], v[114:117]
	v_mfma_f32_16x16x32_f16 v[98:101], v[182:185], v[158:161], v[98:101]
	v_mfma_f32_16x16x32_f16 v[90:93], v[190:193], v[158:161], v[90:93]
	v_mfma_f32_16x16x32_f16 v[70:73], v[182:185], v[174:177], v[70:73]
	v_mfma_f32_16x16x32_f16 v[66:69], v[190:193], v[174:177], v[66:69]
	s_waitcnt lgkmcnt(0)
	v_mfma_f32_16x16x32_f16 v[146:149], v[186:189], v[130:133], v[138:141]
	v_mfma_f32_16x16x32_f16 v[138:141], v[194:197], v[130:133], v[122:125]
	v_mfma_f32_16x16x32_f16 v[118:121], v[186:189], v[154:157], v[118:121]
	v_mfma_f32_16x16x32_f16 v[114:117], v[194:197], v[154:157], v[114:117]
	v_mfma_f32_16x16x32_f16 v[98:101], v[186:189], v[170:173], v[98:101]
	v_mfma_f32_16x16x32_f16 v[90:93], v[194:197], v[170:173], v[90:93]
	v_mfma_f32_16x16x32_f16 v[70:73], v[186:189], v[178:181], v[70:73]
	v_mfma_f32_16x16x32_f16 v[66:69], v[194:197], v[178:181], v[66:69]
	s_setprio 0
	s_mov_b32 m0, s34
	v_lshl_add_u64 v[178:179], v[208:209], 0, s[84:85]
	s_barrier
	ds_read_b128 v[122:125], v232 offset:49152
	ds_read_b128 v[130:133], v232 offset:51200
	ds_read_b128 v[154:157], v232 offset:53248
	ds_read_b128 v[170:173], v232 offset:55296
	ds_read_b128 v[126:129], v232 offset:50176
	ds_read_b128 v[134:137], v232 offset:52224
	ds_read_b128 v[158:161], v232 offset:54272
	ds_read_b128 v[174:177], v232 offset:56320
	global_load_lds_dwordx4 v[178:179], off
	v_lshl_add_u64 v[178:179], v[210:211], 0, s[84:85]
	s_mov_b32 m0, s35
	s_nop 0
	global_load_lds_dwordx4 v[178:179], off
	s_barrier
	s_waitcnt lgkmcnt(6)
	s_setprio 1
	v_mfma_f32_16x16x32_f16 v[62:65], v[78:81], v[122:125], v[62:65]
	v_mfma_f32_16x16x32_f16 v[58:61], v[94:97], v[122:125], v[58:61]
	v_mfma_f32_16x16x32_f16 v[46:49], v[78:81], v[130:133], v[46:49]
	v_mfma_f32_16x16x32_f16 v[42:45], v[94:97], v[130:133], v[42:45]
	s_waitcnt lgkmcnt(4)
	v_mfma_f32_16x16x32_f16 v[28:31], v[78:81], v[154:157], v[28:31]
	v_mfma_f32_16x16x32_f16 v[24:27], v[94:97], v[154:157], v[24:27]
	v_mfma_f32_16x16x32_f16 v[12:15], v[78:81], v[170:173], v[12:15]
	v_mfma_f32_16x16x32_f16 v[8:11], v[94:97], v[170:173], v[8:11]
	s_waitcnt lgkmcnt(2)
	v_mfma_f32_16x16x32_f16 v[62:65], v[86:89], v[126:129], v[62:65]
	v_mfma_f32_16x16x32_f16 v[58:61], v[102:105], v[126:129], v[58:61]
	v_mfma_f32_16x16x32_f16 v[46:49], v[86:89], v[134:137], v[46:49]
	v_mfma_f32_16x16x32_f16 v[42:45], v[102:105], v[134:137], v[42:45]
	s_waitcnt lgkmcnt(0)
	v_mfma_f32_16x16x32_f16 v[28:31], v[86:89], v[158:161], v[28:31]
	v_mfma_f32_16x16x32_f16 v[24:27], v[102:105], v[158:161], v[24:27]
	v_mfma_f32_16x16x32_f16 v[12:15], v[86:89], v[174:177], v[12:15]
	v_mfma_f32_16x16x32_f16 v[8:11], v[102:105], v[174:177], v[8:11]
	s_setprio 0
	s_barrier
	s_add_u32 s14, s22, 0x40080
	s_addc_u32 s15, s23, 0
	s_add_i32 s22, s24, s13
	v_lshl_add_u64 v[78:79], s[14:15], 0, v[32:33]
	s_mov_b32 m0, s22
	s_nop 0
	global_load_lds_dwordx4 v[78:79], off
	v_lshl_add_u64 v[78:79], s[14:15], 0, v[198:199]
	s_add_i32 m0, s22, 0x2000
	s_nop 0
	global_load_lds_dwordx4 v[78:79], off
	s_waitcnt vmcnt(6)
	s_barrier
	s_setprio 1
	v_mfma_f32_16x16x32_f16 v[54:57], v[182:185], v[122:125], v[54:57]
	v_mfma_f32_16x16x32_f16 v[50:53], v[190:193], v[122:125], v[50:53]
	v_mfma_f32_16x16x32_f16 v[38:41], v[182:185], v[130:133], v[38:41]
	v_mfma_f32_16x16x32_f16 v[34:37], v[190:193], v[130:133], v[34:37]
	v_mfma_f32_16x16x32_f16 v[20:23], v[182:185], v[154:157], v[20:23]
	v_mfma_f32_16x16x32_f16 v[16:19], v[190:193], v[154:157], v[16:19]
	v_mfma_f32_16x16x32_f16 v[4:7], v[182:185], v[170:173], v[4:7]
	v_mfma_f32_16x16x32_f16 v[0:3], v[190:193], v[170:173], v[0:3]
	v_mfma_f32_16x16x32_f16 v[54:57], v[186:189], v[126:129], v[54:57]
	v_mfma_f32_16x16x32_f16 v[50:53], v[194:197], v[126:129], v[50:53]
	v_mfma_f32_16x16x32_f16 v[38:41], v[186:189], v[134:137], v[38:41]
	v_mfma_f32_16x16x32_f16 v[34:37], v[194:197], v[134:137], v[34:37]
	v_mfma_f32_16x16x32_f16 v[20:23], v[186:189], v[158:161], v[20:23]
	v_mfma_f32_16x16x32_f16 v[16:19], v[194:197], v[158:161], v[16:19]
	v_mfma_f32_16x16x32_f16 v[4:7], v[186:189], v[174:177], v[4:7]
	v_mfma_f32_16x16x32_f16 v[0:3], v[194:197], v[174:177], v[0:3]
	s_setprio 0
	s_add_u32 s39, s39, 0x100
	s_addc_u32 s40, s40, 0
	s_cmp_ge_u32 s41, s37
	s_mov_b64 s[14:15], s[20:21]
	s_mov_b32 s22, s41
	s_barrier
	s_cbranch_scc0 .LBB0_1117
	v_lshl_or_b32 v124, s12, 8, v231
	s_cmp_eq_u32 s10, 0
	s_movk_i32 s12, 0x5000
	s_cselect_b32 s12, 0xe000, s12
	v_readlane_b32 s14, v252, 51
	s_add_u32 s14, s14, s12
	v_readlane_b32 s12, v252, 52
	s_addc_u32 s15, s12, 0
	v_ashrrev_i32_e32 v125, 31, v124
	v_lshl_add_u64 v[86:87], v[124:125], 2, s[14:15]
	global_load_dwordx4 v[94:97], v[86:87], off offset:16
	global_load_dwordx4 v[102:105], v[86:87], off
	global_load_dwordx4 v[78:81], v[86:87], off offset:528
	s_nop 0
	global_load_dwordx4 v[86:89], v[86:87], off offset:512
	v_lshl_add_u32 v130, s10, 8, v229
	v_or_b32_e32 v128, 16, v130
	v_or_b32_e32 v126, 32, v130
	v_or_b32_e32 v122, 48, v130
	s_cmp_eq_u32 s11, 0
	v_ashrrev_i32_e32 v131, 31, v130
	v_ashrrev_i32_e32 v129, 31, v128
	v_ashrrev_i32_e32 v127, 31, v126
	v_ashrrev_i32_e32 v123, 31, v122
	s_cbranch_scc1 .LBB0_1120
	s_add_i32 s96, s11, -1
	s_lshl_b64 s[10:11], s[96:97], 20
	v_readlane_b32 s14, v252, 11
	v_readlane_b32 s15, v252, 12
	s_add_u32 s10, s14, s10
	s_addc_u32 s11, s15, s11
	v_lshlrev_b64 v[132:133], 2, v[124:125]
	v_lshrrev_b32_e32 v134, 5, v220
	v_mul_u32_u24_e32 v134, 48, v134
	s_nop 0
	v_sub_co_u32_e32 v132, vcc, v132, v134
	s_nop 1
	v_subbrev_co_u32_e32 v133, vcc, 0, v133, vcc
	v_lshl_add_u64 v[132:133], s[10:11], 0, v[132:133]
	s_mov_b64 s[10:11], 0x80000
	v_lshlrev_b64 v[204:205], 12, v[130:131]
	v_lshl_add_u64 v[204:205], v[204:205], 0, v[132:133]
	v_lshl_add_u64 v[212:213], v[204:205], 0, s[10:11]
	v_lshlrev_b64 v[206:207], 12, v[128:129]
	v_lshl_add_u64 v[206:207], v[206:207], 0, v[132:133]
	v_lshl_add_u64 v[214:215], v[206:207], 0, s[10:11]
	v_lshlrev_b64 v[208:209], 12, v[126:127]
	v_lshl_add_u64 v[208:209], v[208:209], 0, v[132:133]
	v_lshl_add_u64 v[216:217], v[208:209], 0, s[10:11]
	v_lshlrev_b64 v[210:211], 12, v[122:123]
	v_lshl_add_u64 v[210:211], v[210:211], 0, v[132:133]
	v_lshl_add_u64 v[218:219], v[210:211], 0, s[10:11]
	s_waitcnt vmcnt(0)
	v_pk_mul_f32 v[172:173], v[166:167], v[102:103]
	v_pk_mul_f32 v[174:175], v[168:169], v[104:105]
	v_pk_mul_f32 v[176:177], v[162:163], v[94:95]
	v_pk_mul_f32 v[178:179], v[164:165], v[96:97]
	s_nop 1
	v_permlane32_swap_b32_e32 v172, v176
	v_permlane32_swap_b32_e32 v173, v177
	v_permlane32_swap_b32_e32 v174, v178
	v_permlane32_swap_b32_e32 v175, v179
	s_nop 0
	global_store_dwordx4 v[204:205], v[172:175], off
	global_store_dwordx4 v[204:205], v[176:179], off offset:64
	v_pk_mul_f32 v[180:181], v[146:147], v[86:87]
	v_pk_mul_f32 v[182:183], v[148:149], v[88:89]
	v_pk_mul_f32 v[184:185], v[138:139], v[78:79]
	v_pk_mul_f32 v[186:187], v[140:141], v[80:81]
	s_nop 1
	v_permlane32_swap_b32_e32 v180, v184
	v_permlane32_swap_b32_e32 v181, v185
	v_permlane32_swap_b32_e32 v182, v186
	v_permlane32_swap_b32_e32 v183, v187
	s_nop 0
	global_store_dwordx4 v[204:205], v[180:183], off offset:512
	global_store_dwordx4 v[204:205], v[184:187], off offset:576
	v_pk_mul_f32 v[188:189], v[150:151], v[102:103]
	v_pk_mul_f32 v[190:191], v[152:153], v[104:105]
	v_pk_mul_f32 v[192:193], v[142:143], v[94:95]
	v_pk_mul_f32 v[194:195], v[144:145], v[96:97]
	s_nop 1
	v_permlane32_swap_b32_e32 v188, v192
	v_permlane32_swap_b32_e32 v189, v193
	v_permlane32_swap_b32_e32 v190, v194
	v_permlane32_swap_b32_e32 v191, v195
	s_nop 0
	global_store_dwordx4 v[206:207], v[188:191], off
	global_store_dwordx4 v[206:207], v[192:195], off offset:64
	v_pk_mul_f32 v[154:155], v[118:119], v[86:87]
	v_pk_mul_f32 v[156:157], v[120:121], v[88:89]
	v_pk_mul_f32 v[158:159], v[114:115], v[78:79]
	v_pk_mul_f32 v[160:161], v[116:117], v[80:81]
	s_nop 1
	v_permlane32_swap_b32_e32 v154, v158
	v_permlane32_swap_b32_e32 v155, v159
	v_permlane32_swap_b32_e32 v156, v160
	v_permlane32_swap_b32_e32 v157, v161
	s_nop 0
	global_store_dwordx4 v[206:207], v[154:157], off offset:512
	global_store_dwordx4 v[206:207], v[158:161], off offset:576
	v_pk_mul_f32 v[172:173], v[110:111], v[102:103]
	v_pk_mul_f32 v[174:175], v[112:113], v[104:105]
	v_pk_mul_f32 v[176:177], v[106:107], v[94:95]
	v_pk_mul_f32 v[178:179], v[108:109], v[96:97]
	s_nop 1
	v_permlane32_swap_b32_e32 v172, v176
	v_permlane32_swap_b32_e32 v173, v177
	v_permlane32_swap_b32_e32 v174, v178
	v_permlane32_swap_b32_e32 v175, v179
	s_nop 0
	global_store_dwordx4 v[208:209], v[172:175], off
	global_store_dwordx4 v[208:209], v[176:179], off offset:64
	v_pk_mul_f32 v[180:181], v[98:99], v[86:87]
	v_pk_mul_f32 v[182:183], v[100:101], v[88:89]
	v_pk_mul_f32 v[184:185], v[90:91], v[78:79]
	v_pk_mul_f32 v[186:187], v[92:93], v[80:81]
	s_nop 1
	v_permlane32_swap_b32_e32 v180, v184
	v_permlane32_swap_b32_e32 v181, v185
	v_permlane32_swap_b32_e32 v182, v186
	v_permlane32_swap_b32_e32 v183, v187
	s_nop 0
	global_store_dwordx4 v[208:209], v[180:183], off offset:512
	global_store_dwordx4 v[208:209], v[184:187], off offset:576
	v_pk_mul_f32 v[188:189], v[82:83], v[102:103]
	v_pk_mul_f32 v[190:191], v[84:85], v[104:105]
	v_pk_mul_f32 v[192:193], v[74:75], v[94:95]
	v_pk_mul_f32 v[194:195], v[76:77], v[96:97]
	s_nop 1
	v_permlane32_swap_b32_e32 v188, v192
	v_permlane32_swap_b32_e32 v189, v193
	v_permlane32_swap_b32_e32 v190, v194
	v_permlane32_swap_b32_e32 v191, v195
	s_nop 0
	global_store_dwordx4 v[210:211], v[188:191], off
	global_store_dwordx4 v[210:211], v[192:195], off offset:64
	v_pk_mul_f32 v[154:155], v[70:71], v[86:87]
	v_pk_mul_f32 v[156:157], v[72:73], v[88:89]
	v_pk_mul_f32 v[158:159], v[66:67], v[78:79]
	v_pk_mul_f32 v[160:161], v[68:69], v[80:81]
	s_nop 1
	v_permlane32_swap_b32_e32 v154, v158
	v_permlane32_swap_b32_e32 v155, v159
	v_permlane32_swap_b32_e32 v156, v160
	v_permlane32_swap_b32_e32 v157, v161
	s_nop 0
	global_store_dwordx4 v[210:211], v[154:157], off offset:512
	global_store_dwordx4 v[210:211], v[158:161], off offset:576
	v_pk_mul_f32 v[172:173], v[62:63], v[102:103]
	v_pk_mul_f32 v[174:175], v[64:65], v[104:105]
	v_pk_mul_f32 v[176:177], v[58:59], v[94:95]
	v_pk_mul_f32 v[178:179], v[60:61], v[96:97]
	s_nop 1
	v_permlane32_swap_b32_e32 v172, v176
	v_permlane32_swap_b32_e32 v173, v177
	v_permlane32_swap_b32_e32 v174, v178
	v_permlane32_swap_b32_e32 v175, v179
	s_nop 0
	global_store_dwordx4 v[212:213], v[172:175], off
	global_store_dwordx4 v[212:213], v[176:179], off offset:64
	v_pk_mul_f32 v[180:181], v[54:55], v[86:87]
	v_pk_mul_f32 v[182:183], v[56:57], v[88:89]
	v_pk_mul_f32 v[184:185], v[50:51], v[78:79]
	v_pk_mul_f32 v[186:187], v[52:53], v[80:81]
	s_nop 1
	v_permlane32_swap_b32_e32 v180, v184
	v_permlane32_swap_b32_e32 v181, v185
	v_permlane32_swap_b32_e32 v182, v186
	v_permlane32_swap_b32_e32 v183, v187
	s_nop 0
	global_store_dwordx4 v[212:213], v[180:183], off offset:512
	global_store_dwordx4 v[212:213], v[184:187], off offset:576
	v_pk_mul_f32 v[188:189], v[46:47], v[102:103]
	v_pk_mul_f32 v[190:191], v[48:49], v[104:105]
	v_pk_mul_f32 v[192:193], v[42:43], v[94:95]
	v_pk_mul_f32 v[194:195], v[44:45], v[96:97]
	s_nop 1
	v_permlane32_swap_b32_e32 v188, v192
	v_permlane32_swap_b32_e32 v189, v193
	v_permlane32_swap_b32_e32 v190, v194
	v_permlane32_swap_b32_e32 v191, v195
	s_nop 0
	global_store_dwordx4 v[214:215], v[188:191], off
	global_store_dwordx4 v[214:215], v[192:195], off offset:64
	v_pk_mul_f32 v[154:155], v[38:39], v[86:87]
	v_pk_mul_f32 v[156:157], v[40:41], v[88:89]
	v_pk_mul_f32 v[158:159], v[34:35], v[78:79]
	v_pk_mul_f32 v[160:161], v[36:37], v[80:81]
	s_nop 1
	v_permlane32_swap_b32_e32 v154, v158
	v_permlane32_swap_b32_e32 v155, v159
	v_permlane32_swap_b32_e32 v156, v160
	v_permlane32_swap_b32_e32 v157, v161
	s_nop 0
	global_store_dwordx4 v[214:215], v[154:157], off offset:512
	global_store_dwordx4 v[214:215], v[158:161], off offset:576
	v_pk_mul_f32 v[172:173], v[28:29], v[102:103]
	v_pk_mul_f32 v[174:175], v[30:31], v[104:105]
	v_pk_mul_f32 v[176:177], v[24:25], v[94:95]
	v_pk_mul_f32 v[178:179], v[26:27], v[96:97]
	s_nop 1
	v_permlane32_swap_b32_e32 v172, v176
	v_permlane32_swap_b32_e32 v173, v177
	v_permlane32_swap_b32_e32 v174, v178
	v_permlane32_swap_b32_e32 v175, v179
	s_nop 0
	global_store_dwordx4 v[216:217], v[172:175], off
	global_store_dwordx4 v[216:217], v[176:179], off offset:64
	v_pk_mul_f32 v[180:181], v[20:21], v[86:87]
	v_pk_mul_f32 v[182:183], v[22:23], v[88:89]
	v_pk_mul_f32 v[184:185], v[16:17], v[78:79]
	v_pk_mul_f32 v[186:187], v[18:19], v[80:81]
	s_nop 1
	v_permlane32_swap_b32_e32 v180, v184
	v_permlane32_swap_b32_e32 v181, v185
	v_permlane32_swap_b32_e32 v182, v186
	v_permlane32_swap_b32_e32 v183, v187
	s_nop 0
	global_store_dwordx4 v[216:217], v[180:183], off offset:512
	global_store_dwordx4 v[216:217], v[184:187], off offset:576
	v_pk_mul_f32 v[188:189], v[12:13], v[102:103]
	v_pk_mul_f32 v[190:191], v[14:15], v[104:105]
	v_pk_mul_f32 v[192:193], v[8:9], v[94:95]
	v_pk_mul_f32 v[194:195], v[10:11], v[96:97]
	s_nop 1
	v_permlane32_swap_b32_e32 v188, v192
	v_permlane32_swap_b32_e32 v189, v193
	v_permlane32_swap_b32_e32 v190, v194
	v_permlane32_swap_b32_e32 v191, v195
	s_nop 0
	global_store_dwordx4 v[218:219], v[188:191], off
	global_store_dwordx4 v[218:219], v[192:195], off offset:64
	v_pk_mul_f32 v[154:155], v[4:5], v[86:87]
	v_pk_mul_f32 v[156:157], v[6:7], v[88:89]
	v_pk_mul_f32 v[158:159], v[0:1], v[78:79]
	v_pk_mul_f32 v[160:161], v[2:3], v[80:81]
	s_nop 1
	v_permlane32_swap_b32_e32 v154, v158
	v_permlane32_swap_b32_e32 v155, v159
	v_permlane32_swap_b32_e32 v156, v160
	v_permlane32_swap_b32_e32 v157, v161
	s_nop 0
	global_store_dwordx4 v[218:219], v[154:157], off offset:512
	global_store_dwordx4 v[218:219], v[158:161], off offset:576
	s_cbranch_execnz .LBB0_1104
	s_branch .LBB0_1103

.LBB0_1276:
	s_add_u32 s16, s14, 0x100
	s_addc_u32 s17, s15, 0
	s_add_i32 s39, 0, 0x10000
	v_add_u32_e32 v152, s39, v137
	ds_read_b128 v[140:143], v152
	ds_read_b128 v[148:151], v152 offset:2048
	ds_read_b128 v[144:147], v152 offset:1024
	ds_read_b128 v[152:155], v152 offset:3072
	s_cmp_eq_u32 s38, 12
	s_cselect_b32 s21, s11, s17
	s_cselect_b32 s20, s10, s16
	s_cselect_b32 s19, s13, s37
	s_cselect_b32 s18, s12, s3
	v_lshl_add_u64 v[188:189], s[14:15], 0, v[132:133]
	s_add_i32 m0, s9, 0xc000
	ds_read_b128 v[156:159], v139
	ds_read_b128 v[164:167], v139 offset:2048
	ds_read_b128 v[172:175], v139 offset:4096
	ds_read_b128 v[180:183], v139 offset:6144
	ds_read_b128 v[160:163], v139 offset:1024
	ds_read_b128 v[168:171], v139 offset:3072
	ds_read_b128 v[176:179], v139 offset:5120
	ds_read_b128 v[184:187], v139 offset:7168
	global_load_lds_dwordx4 v[188:189], off
	v_lshl_add_u64 v[188:189], s[14:15], 0, v[134:135]
	s_add_i32 m0, s9, 0xe000
	s_nop 0
	global_load_lds_dwordx4 v[188:189], off
	s_waitcnt lgkmcnt(8)
	s_barrier
	s_waitcnt lgkmcnt(6)
	s_setprio 1
	v_mfma_f32_16x16x32_f16 v[126:129], v[140:143], v[156:159], v[126:129]
	v_mfma_f32_16x16x32_f16 v[122:125], v[148:151], v[156:159], v[122:125]
	v_mfma_f32_16x16x32_f16 v[110:113], v[140:143], v[164:167], v[110:113]
	v_mfma_f32_16x16x32_f16 v[106:109], v[148:151], v[164:167], v[106:109]
	s_waitcnt lgkmcnt(4)
	v_mfma_f32_16x16x32_f16 v[94:97], v[140:143], v[172:175], v[94:97]
	v_mfma_f32_16x16x32_f16 v[90:93], v[148:151], v[172:175], v[90:93]
	v_mfma_f32_16x16x32_f16 v[78:81], v[140:143], v[180:183], v[78:81]
	v_mfma_f32_16x16x32_f16 v[74:77], v[148:151], v[180:183], v[74:77]
	s_waitcnt lgkmcnt(2)
	v_mfma_f32_16x16x32_f16 v[126:129], v[144:147], v[160:163], v[126:129]
	v_mfma_f32_16x16x32_f16 v[122:125], v[152:155], v[160:163], v[122:125]
	v_mfma_f32_16x16x32_f16 v[110:113], v[144:147], v[168:171], v[110:113]
	v_mfma_f32_16x16x32_f16 v[106:109], v[152:155], v[168:171], v[106:109]
	s_waitcnt lgkmcnt(0)
	v_mfma_f32_16x16x32_f16 v[94:97], v[144:147], v[176:179], v[94:97]
	v_mfma_f32_16x16x32_f16 v[90:93], v[152:155], v[176:179], v[90:93]
	v_mfma_f32_16x16x32_f16 v[78:81], v[144:147], v[184:187], v[78:81]
	v_mfma_f32_16x16x32_f16 v[74:77], v[152:155], v[184:187], v[74:77]
	s_setprio 0
	s_barrier
	s_add_i32 s40, 0, 0x14000
	s_add_i32 s14, s39, s26
	v_add_u32_e32 v200, s40, v137
	v_lshl_add_u64 v[204:205], s[18:19], 0, v[32:33]
	s_mov_b32 m0, s14
	ds_read_b128 v[188:191], v200
	ds_read_b128 v[196:199], v200 offset:2048
	ds_read_b128 v[192:195], v200 offset:1024
	ds_read_b128 v[200:203], v200 offset:3072
	global_load_lds_dwordx4 v[204:205], off
	v_lshl_add_u64 v[206:207], s[18:19], 0, v[130:131]
	s_add_i32 m0, s14, 0x2000
	s_nop 0
	global_load_lds_dwordx4 v[206:207], off
	s_barrier
	s_waitcnt lgkmcnt(2)
	s_setprio 1
	v_mfma_f32_16x16x32_f16 v[118:121], v[188:191], v[156:159], v[118:121]
	v_mfma_f32_16x16x32_f16 v[114:117], v[196:199], v[156:159], v[114:117]
	v_mfma_f32_16x16x32_f16 v[102:105], v[188:191], v[164:167], v[102:105]
	v_mfma_f32_16x16x32_f16 v[98:101], v[196:199], v[164:167], v[98:101]
	v_mfma_f32_16x16x32_f16 v[86:89], v[188:191], v[172:175], v[86:89]
	v_mfma_f32_16x16x32_f16 v[82:85], v[196:199], v[172:175], v[82:85]
	v_mfma_f32_16x16x32_f16 v[70:73], v[188:191], v[180:183], v[70:73]
	v_mfma_f32_16x16x32_f16 v[66:69], v[196:199], v[180:183], v[66:69]
	s_waitcnt lgkmcnt(0)
	v_mfma_f32_16x16x32_f16 v[118:121], v[192:195], v[160:163], v[118:121]
	v_mfma_f32_16x16x32_f16 v[114:117], v[200:203], v[160:163], v[114:117]
	v_mfma_f32_16x16x32_f16 v[102:105], v[192:195], v[168:171], v[102:105]
	v_mfma_f32_16x16x32_f16 v[98:101], v[200:203], v[168:171], v[98:101]
	v_mfma_f32_16x16x32_f16 v[86:89], v[192:195], v[176:179], v[86:89]
	v_mfma_f32_16x16x32_f16 v[82:85], v[200:203], v[176:179], v[82:85]
	v_mfma_f32_16x16x32_f16 v[70:73], v[192:195], v[184:187], v[70:73]
	v_mfma_f32_16x16x32_f16 v[66:69], v[200:203], v[184:187], v[66:69]
	s_setprio 0
	s_mov_b32 m0, s9
	v_lshl_add_u64 v[208:209], s[20:21], 0, v[32:33]
	s_barrier
	ds_read_b128 v[156:159], v139 offset:16384
	ds_read_b128 v[164:167], v139 offset:18432
	ds_read_b128 v[172:175], v139 offset:20480
	ds_read_b128 v[180:183], v139 offset:22528
	ds_read_b128 v[160:163], v139 offset:17408
	ds_read_b128 v[168:171], v139 offset:19456
	ds_read_b128 v[176:179], v139 offset:21504
	ds_read_b128 v[184:187], v139 offset:23552
	global_load_lds_dwordx4 v[208:209], off
	v_lshl_add_u64 v[210:211], s[20:21], 0, v[130:131]
	s_mov_b32 m0, s27
	s_nop 0
	global_load_lds_dwordx4 v[210:211], off
	s_barrier
	s_waitcnt lgkmcnt(6)
	s_setprio 1
	v_mfma_f32_16x16x32_f16 v[62:65], v[140:143], v[156:159], v[62:65]
	v_mfma_f32_16x16x32_f16 v[58:61], v[148:151], v[156:159], v[58:61]
	v_mfma_f32_16x16x32_f16 v[46:49], v[140:143], v[164:167], v[46:49]
	v_mfma_f32_16x16x32_f16 v[42:45], v[148:151], v[164:167], v[42:45]
	s_waitcnt lgkmcnt(4)
	v_mfma_f32_16x16x32_f16 v[28:31], v[140:143], v[172:175], v[28:31]
	v_mfma_f32_16x16x32_f16 v[24:27], v[148:151], v[172:175], v[24:27]
	v_mfma_f32_16x16x32_f16 v[12:15], v[140:143], v[180:183], v[12:15]
	v_mfma_f32_16x16x32_f16 v[8:11], v[148:151], v[180:183], v[8:11]
	s_waitcnt lgkmcnt(2)
	v_mfma_f32_16x16x32_f16 v[62:65], v[144:147], v[160:163], v[62:65]
	v_mfma_f32_16x16x32_f16 v[58:61], v[152:155], v[160:163], v[58:61]
	v_mfma_f32_16x16x32_f16 v[46:49], v[144:147], v[168:171], v[46:49]
	v_mfma_f32_16x16x32_f16 v[42:45], v[152:155], v[168:171], v[42:45]
	s_waitcnt lgkmcnt(0)
	v_mfma_f32_16x16x32_f16 v[28:31], v[144:147], v[176:179], v[28:31]
	v_mfma_f32_16x16x32_f16 v[24:27], v[152:155], v[176:179], v[24:27]
	v_mfma_f32_16x16x32_f16 v[12:15], v[144:147], v[184:187], v[12:15]
	v_mfma_f32_16x16x32_f16 v[8:11], v[152:155], v[184:187], v[8:11]
	s_setprio 0
	s_barrier
	s_add_u32 s14, s18, 0x40000
	s_addc_u32 s15, s19, 0
	s_add_i32 s39, s40, s26
	v_lshl_add_u64 v[140:141], s[14:15], 0, v[32:33]
	s_mov_b32 m0, s39
	s_nop 0
	global_load_lds_dwordx4 v[140:141], off
	v_lshl_add_u64 v[140:141], s[14:15], 0, v[130:131]
	s_add_i32 m0, s39, 0x2000
	s_nop 0
	global_load_lds_dwordx4 v[140:141], off
	s_waitcnt vmcnt(6)
	s_barrier
	s_setprio 1
	v_mfma_f32_16x16x32_f16 v[54:57], v[188:191], v[156:159], v[54:57]
	v_mfma_f32_16x16x32_f16 v[50:53], v[196:199], v[156:159], v[50:53]
	v_mfma_f32_16x16x32_f16 v[38:41], v[188:191], v[164:167], v[38:41]
	v_mfma_f32_16x16x32_f16 v[34:37], v[196:199], v[164:167], v[34:37]
	v_mfma_f32_16x16x32_f16 v[20:23], v[188:191], v[172:175], v[20:23]
	v_mfma_f32_16x16x32_f16 v[16:19], v[196:199], v[172:175], v[16:19]
	v_mfma_f32_16x16x32_f16 v[4:7], v[188:191], v[180:183], v[4:7]
	v_mfma_f32_16x16x32_f16 v[0:3], v[196:199], v[180:183], v[0:3]
	v_mfma_f32_16x16x32_f16 v[54:57], v[192:195], v[160:163], v[54:57]
	v_mfma_f32_16x16x32_f16 v[50:53], v[200:203], v[160:163], v[50:53]
	v_mfma_f32_16x16x32_f16 v[38:41], v[192:195], v[168:171], v[38:41]
	v_mfma_f32_16x16x32_f16 v[34:37], v[200:203], v[168:171], v[34:37]
	v_mfma_f32_16x16x32_f16 v[20:23], v[192:195], v[176:179], v[20:23]
	v_mfma_f32_16x16x32_f16 v[16:19], v[200:203], v[176:179], v[16:19]
	v_mfma_f32_16x16x32_f16 v[4:7], v[192:195], v[184:187], v[4:7]
	v_mfma_f32_16x16x32_f16 v[0:3], v[200:203], v[184:187], v[0:3]
	s_setprio 0
	s_add_i32 s39, 0, 0x18000
	v_add_u32_e32 v152, s39, v137
	s_barrier
	ds_read_b128 v[140:143], v152
	ds_read_b128 v[148:151], v152 offset:2048
	ds_read_b128 v[144:147], v152 offset:1024
	ds_read_b128 v[152:155], v152 offset:3072
	s_add_u32 s14, s20, 0x40000
	s_addc_u32 s15, s21, 0
	s_mov_b32 m0, s28
	v_lshl_add_u64 v[188:189], s[14:15], 0, v[32:33]
	ds_read_b128 v[156:159], v139 offset:32768
	ds_read_b128 v[164:167], v139 offset:34816
	ds_read_b128 v[172:175], v139 offset:36864
	ds_read_b128 v[180:183], v139 offset:38912
	ds_read_b128 v[160:163], v139 offset:33792
	ds_read_b128 v[168:171], v139 offset:35840
	ds_read_b128 v[176:179], v139 offset:37888
	ds_read_b128 v[184:187], v139 offset:39936
	global_load_lds_dwordx4 v[188:189], off
	v_lshl_add_u64 v[188:189], s[14:15], 0, v[130:131]
	s_mov_b32 m0, s29
	s_nop 0
	global_load_lds_dwordx4 v[188:189], off
	s_waitcnt lgkmcnt(8)
	s_barrier
	s_waitcnt lgkmcnt(6)
	s_setprio 1
	v_mfma_f32_16x16x32_f16 v[126:129], v[140:143], v[156:159], v[126:129]
	v_mfma_f32_16x16x32_f16 v[122:125], v[148:151], v[156:159], v[122:125]
	v_mfma_f32_16x16x32_f16 v[110:113], v[140:143], v[164:167], v[110:113]
	v_mfma_f32_16x16x32_f16 v[106:109], v[148:151], v[164:167], v[106:109]
	s_waitcnt lgkmcnt(4)
	v_mfma_f32_16x16x32_f16 v[94:97], v[140:143], v[172:175], v[94:97]
	v_mfma_f32_16x16x32_f16 v[90:93], v[148:151], v[172:175], v[90:93]
	v_mfma_f32_16x16x32_f16 v[78:81], v[140:143], v[180:183], v[78:81]
	v_mfma_f32_16x16x32_f16 v[74:77], v[148:151], v[180:183], v[74:77]
	s_waitcnt lgkmcnt(2)
	v_mfma_f32_16x16x32_f16 v[126:129], v[144:147], v[160:163], v[126:129]
	v_mfma_f32_16x16x32_f16 v[122:125], v[152:155], v[160:163], v[122:125]
	v_mfma_f32_16x16x32_f16 v[110:113], v[144:147], v[168:171], v[110:113]
	v_mfma_f32_16x16x32_f16 v[106:109], v[152:155], v[168:171], v[106:109]
	s_waitcnt lgkmcnt(0)
	v_mfma_f32_16x16x32_f16 v[94:97], v[144:147], v[176:179], v[94:97]
	v_mfma_f32_16x16x32_f16 v[90:93], v[152:155], v[176:179], v[90:93]
	v_mfma_f32_16x16x32_f16 v[78:81], v[144:147], v[184:187], v[78:81]
	v_mfma_f32_16x16x32_f16 v[74:77], v[152:155], v[184:187], v[74:77]
	s_setprio 0
	s_barrier
	s_add_i32 s20, 0, 0x1c000
	s_add_i32 s14, s39, s26
	v_add_u32_e32 v200, s20, v137
	v_lshl_add_u64 v[204:205], v[204:205], 0, s[84:85]
	s_mov_b32 m0, s14
	ds_read_b128 v[188:191], v200
	ds_read_b128 v[196:199], v200 offset:2048
	ds_read_b128 v[192:195], v200 offset:1024
	ds_read_b128 v[200:203], v200 offset:3072
	global_load_lds_dwordx4 v[204:205], off
	v_lshl_add_u64 v[204:205], v[206:207], 0, s[84:85]
	s_add_i32 m0, s14, 0x2000
	s_nop 0
	global_load_lds_dwordx4 v[204:205], off
	s_barrier
	s_waitcnt lgkmcnt(2)
	s_setprio 1
	v_mfma_f32_16x16x32_f16 v[118:121], v[188:191], v[156:159], v[118:121]
	v_mfma_f32_16x16x32_f16 v[114:117], v[196:199], v[156:159], v[114:117]
	v_mfma_f32_16x16x32_f16 v[102:105], v[188:191], v[164:167], v[102:105]
	v_mfma_f32_16x16x32_f16 v[98:101], v[196:199], v[164:167], v[98:101]
	v_mfma_f32_16x16x32_f16 v[86:89], v[188:191], v[172:175], v[86:89]
	v_mfma_f32_16x16x32_f16 v[82:85], v[196:199], v[172:175], v[82:85]
	v_mfma_f32_16x16x32_f16 v[70:73], v[188:191], v[180:183], v[70:73]
	v_mfma_f32_16x16x32_f16 v[66:69], v[196:199], v[180:183], v[66:69]
	s_waitcnt lgkmcnt(0)
	v_mfma_f32_16x16x32_f16 v[118:121], v[192:195], v[160:163], v[118:121]
	v_mfma_f32_16x16x32_f16 v[114:117], v[200:203], v[160:163], v[114:117]
	v_mfma_f32_16x16x32_f16 v[102:105], v[192:195], v[168:171], v[102:105]
	v_mfma_f32_16x16x32_f16 v[98:101], v[200:203], v[168:171], v[98:101]
	v_mfma_f32_16x16x32_f16 v[86:89], v[192:195], v[176:179], v[86:89]
	v_mfma_f32_16x16x32_f16 v[82:85], v[200:203], v[176:179], v[82:85]
	v_mfma_f32_16x16x32_f16 v[70:73], v[192:195], v[184:187], v[70:73]
	v_mfma_f32_16x16x32_f16 v[66:69], v[200:203], v[184:187], v[66:69]
	s_setprio 0
	s_mov_b32 m0, s30
	v_lshl_add_u64 v[204:205], v[208:209], 0, s[84:85]
	s_barrier
	ds_read_b128 v[156:159], v139 offset:49152
	ds_read_b128 v[164:167], v139 offset:51200
	ds_read_b128 v[172:175], v139 offset:53248
	ds_read_b128 v[180:183], v139 offset:55296
	ds_read_b128 v[160:163], v139 offset:50176
	ds_read_b128 v[168:171], v139 offset:52224
	ds_read_b128 v[176:179], v139 offset:54272
	ds_read_b128 v[184:187], v139 offset:56320
	global_load_lds_dwordx4 v[204:205], off
	v_lshl_add_u64 v[204:205], v[210:211], 0, s[84:85]
	s_mov_b32 m0, s31
	s_nop 0
	global_load_lds_dwordx4 v[204:205], off
	s_barrier
	s_waitcnt lgkmcnt(6)
	s_setprio 1
	v_mfma_f32_16x16x32_f16 v[62:65], v[140:143], v[156:159], v[62:65]
	v_mfma_f32_16x16x32_f16 v[58:61], v[148:151], v[156:159], v[58:61]
	v_mfma_f32_16x16x32_f16 v[46:49], v[140:143], v[164:167], v[46:49]
	v_mfma_f32_16x16x32_f16 v[42:45], v[148:151], v[164:167], v[42:45]
	s_waitcnt lgkmcnt(4)
	v_mfma_f32_16x16x32_f16 v[28:31], v[140:143], v[172:175], v[28:31]
	v_mfma_f32_16x16x32_f16 v[24:27], v[148:151], v[172:175], v[24:27]
	v_mfma_f32_16x16x32_f16 v[12:15], v[140:143], v[180:183], v[12:15]
	v_mfma_f32_16x16x32_f16 v[8:11], v[148:151], v[180:183], v[8:11]
	s_waitcnt lgkmcnt(2)
	v_mfma_f32_16x16x32_f16 v[62:65], v[144:147], v[160:163], v[62:65]
	v_mfma_f32_16x16x32_f16 v[58:61], v[152:155], v[160:163], v[58:61]
	v_mfma_f32_16x16x32_f16 v[46:49], v[144:147], v[168:171], v[46:49]
	v_mfma_f32_16x16x32_f16 v[42:45], v[152:155], v[168:171], v[42:45]
	s_waitcnt lgkmcnt(0)
	v_mfma_f32_16x16x32_f16 v[28:31], v[144:147], v[176:179], v[28:31]
	v_mfma_f32_16x16x32_f16 v[24:27], v[152:155], v[176:179], v[24:27]
	v_mfma_f32_16x16x32_f16 v[12:15], v[144:147], v[184:187], v[12:15]
	v_mfma_f32_16x16x32_f16 v[8:11], v[152:155], v[184:187], v[8:11]
	s_setprio 0
	s_barrier
	s_add_u32 s14, s18, 0x40080
	s_addc_u32 s15, s19, 0
	s_add_i32 s18, s20, s26
	v_lshl_add_u64 v[140:141], s[14:15], 0, v[32:33]
	s_mov_b32 m0, s18
	s_nop 0
	global_load_lds_dwordx4 v[140:141], off
	v_lshl_add_u64 v[140:141], s[14:15], 0, v[130:131]
	s_add_i32 m0, s18, 0x2000
	s_nop 0
	global_load_lds_dwordx4 v[140:141], off
	s_waitcnt vmcnt(6)
	s_barrier
	s_setprio 1
	v_mfma_f32_16x16x32_f16 v[54:57], v[188:191], v[156:159], v[54:57]
	v_mfma_f32_16x16x32_f16 v[50:53], v[196:199], v[156:159], v[50:53]
	v_mfma_f32_16x16x32_f16 v[38:41], v[188:191], v[164:167], v[38:41]
	v_mfma_f32_16x16x32_f16 v[34:37], v[196:199], v[164:167], v[34:37]
	v_mfma_f32_16x16x32_f16 v[20:23], v[188:191], v[172:175], v[20:23]
	v_mfma_f32_16x16x32_f16 v[16:19], v[196:199], v[172:175], v[16:19]
	v_mfma_f32_16x16x32_f16 v[4:7], v[188:191], v[180:183], v[4:7]
	v_mfma_f32_16x16x32_f16 v[0:3], v[196:199], v[180:183], v[0:3]
	v_mfma_f32_16x16x32_f16 v[54:57], v[192:195], v[160:163], v[54:57]
	v_mfma_f32_16x16x32_f16 v[50:53], v[200:203], v[160:163], v[50:53]
	v_mfma_f32_16x16x32_f16 v[38:41], v[192:195], v[168:171], v[38:41]
	v_mfma_f32_16x16x32_f16 v[34:37], v[200:203], v[168:171], v[34:37]
	v_mfma_f32_16x16x32_f16 v[20:23], v[192:195], v[176:179], v[20:23]
	v_mfma_f32_16x16x32_f16 v[16:19], v[200:203], v[176:179], v[16:19]
	v_mfma_f32_16x16x32_f16 v[4:7], v[192:195], v[184:187], v[4:7]
	v_mfma_f32_16x16x32_f16 v[0:3], v[200:203], v[184:187], v[0:3]
	s_setprio 0
	s_add_i32 s38, s38, 2
	s_add_u32 s3, s3, 0x100
	s_addc_u32 s37, s37, 0
	s_cmp_gt_u32 s38, 13
	s_mov_b64 s[14:15], s[16:17]
	s_barrier
	s_cbranch_scc0 .LBB0_1276
	v_mul_f32_e32 v144, 0xbfb8aa3b, v127
	v_mul_f32_e32 v141, 0xbfb8aa3b, v126
	v_exp_f32_e32 v145, v144
	v_mul_f32_e32 v144, 0xbfb8aa3b, v128
	v_exp_f32_e32 v141, v141
	v_exp_f32_e32 v146, v144
	v_mul_f32_e32 v144, 0xbfb8aa3b, v129
	v_exp_f32_e32 v147, v144
	v_mul_f32_e32 v144, 0xbfb8aa3b, v122
	v_exp_f32_e32 v148, v144
	v_mul_f32_e32 v144, 0xbfb8aa3b, v123
	v_exp_f32_e32 v149, v144
	v_mul_f32_e32 v144, 0xbfb8aa3b, v124
	v_exp_f32_e32 v150, v144
	v_mul_f32_e32 v144, 0xbfb8aa3b, v125
	v_add_f32_e32 v141, 1.0, v141
	v_exp_f32_e32 v151, v144
	v_rcp_f32_e32 v144, v141
	v_add_f32_e32 v141, 1.0, v145
	v_rcp_f32_e32 v145, v141
	v_add_f32_e32 v141, 1.0, v146
	v_rcp_f32_e32 v146, v141
	v_add_f32_e32 v141, 1.0, v147
	v_rcp_f32_e32 v147, v141
	v_add_f32_e32 v141, 1.0, v148
	v_rcp_f32_e32 v148, v141
	v_add_f32_e32 v141, 1.0, v149
	v_rcp_f32_e32 v149, v141
	v_add_f32_e32 v141, 1.0, v150
	v_rcp_f32_e32 v150, v141
	v_add_f32_e32 v141, 1.0, v151
	v_pk_mul_f32 v[126:127], v[126:127], v[144:145]
	v_rcp_f32_e32 v151, v141
	v_pk_mul_f32 v[118:119], v[126:127], v[118:119]
	v_pk_mul_f32 v[126:127], v[128:129], v[146:147]
	v_cvt_pk_f16_f32 v118, v118, v119
	v_pk_mul_f32 v[120:121], v[126:127], v[120:121]
	v_lshl_or_b32 v142, s36, 7, v138
	v_cvt_pk_f16_f32 v119, v120, v121
	v_pk_mul_f32 v[120:121], v[122:123], v[148:149]
	v_lshl_add_u32 v140, s8, 8, v136
	v_pk_mul_f32 v[114:115], v[120:121], v[114:115]
	v_ashrrev_i32_e32 v143, 31, v142
	v_cvt_pk_f16_f32 v120, v114, v115
	v_pk_mul_f32 v[114:115], v[124:125], v[150:151]
	s_movk_i32 s3, 0x1600
	v_pk_mul_f32 v[114:115], v[114:115], v[116:117]
	v_lshlrev_b64 v[116:117], 1, v[142:143]
	v_cvt_pk_f16_f32 v121, v114, v115
	v_mov_b64_e32 v[114:115], s[92:93]
	v_mad_i64_i32 v[122:123], s[10:11], v140, s3, v[114:115]
	v_lshl_add_u64 v[122:123], v[122:123], 0, v[116:117]
	global_store_dwordx4 v[122:123], v[118:121], off
	v_mul_f32_e32 v122, 0xbfb8aa3b, v106
	v_mul_f32_e32 v123, 0xbfb8aa3b, v107
	v_mul_f32_e32 v118, 0xbfb8aa3b, v110
	v_mul_f32_e32 v119, 0xbfb8aa3b, v111
	v_exp_f32_e32 v118, v118
	v_exp_f32_e32 v119, v119
	v_mul_f32_e32 v120, 0xbfb8aa3b, v112
	v_mul_f32_e32 v121, 0xbfb8aa3b, v113
	v_exp_f32_e32 v120, v120
	v_exp_f32_e32 v121, v121
	v_exp_f32_e32 v122, v122
	v_exp_f32_e32 v123, v123
	v_mul_f32_e32 v124, 0xbfb8aa3b, v108
	v_mul_f32_e32 v125, 0xbfb8aa3b, v109
	v_add_f32_e32 v118, 1.0, v118
	v_add_f32_e32 v119, 1.0, v119
	v_exp_f32_e32 v124, v124
	v_exp_f32_e32 v125, v125
	v_rcp_f32_e32 v118, v118
	v_rcp_f32_e32 v119, v119
	v_add_f32_e32 v120, 1.0, v120
	v_add_f32_e32 v121, 1.0, v121
	v_rcp_f32_e32 v120, v120
	v_rcp_f32_e32 v121, v121
	v_add_f32_e32 v122, 1.0, v122
	v_add_f32_e32 v123, 1.0, v123
	v_rcp_f32_e32 v122, v122
	v_rcp_f32_e32 v123, v123
	v_add_f32_e32 v124, 1.0, v124
	v_add_f32_e32 v125, 1.0, v125
	v_pk_mul_f32 v[110:111], v[110:111], v[118:119]
	v_rcp_f32_e32 v124, v124
	v_rcp_f32_e32 v125, v125
	v_pk_mul_f32 v[102:103], v[110:111], v[102:103]
	v_pk_mul_f32 v[110:111], v[112:113], v[120:121]
	v_cvt_pk_f16_f32 v102, v102, v103
	v_pk_mul_f32 v[104:105], v[110:111], v[104:105]
	s_and_b64 vcc, exec, s[0:1]
	v_cvt_pk_f16_f32 v103, v104, v105
	v_pk_mul_f32 v[104:105], v[106:107], v[122:123]
	s_mov_b32 s36, s35
	v_pk_mul_f32 v[98:99], v[104:105], v[98:99]
	s_mov_b32 s8, s2
	v_cvt_pk_f16_f32 v104, v98, v99
	v_pk_mul_f32 v[98:99], v[108:109], v[124:125]
	s_mov_b64 s[16:17], s[6:7]
	v_pk_mul_f32 v[98:99], v[98:99], v[100:101]
	v_mul_f32_e32 v100, 0xbfb8aa3b, v96
	v_cvt_pk_f16_f32 v105, v98, v99
	v_or_b32_e32 v98, 16, v140
	v_mad_i64_i32 v[98:99], s[10:11], v98, s3, v[114:115]
	v_lshl_add_u64 v[98:99], v[98:99], 0, v[116:117]
	global_store_dwordx4 v[98:99], v[102:105], off
	v_mul_f32_e32 v98, 0xbfb8aa3b, v94
	v_mul_f32_e32 v99, 0xbfb8aa3b, v95
	v_exp_f32_e32 v98, v98
	v_exp_f32_e32 v99, v99
	v_mul_f32_e32 v101, 0xbfb8aa3b, v97
	v_exp_f32_e32 v100, v100
	v_exp_f32_e32 v101, v101
	v_mul_f32_e32 v102, 0xbfb8aa3b, v90
	v_mul_f32_e32 v103, 0xbfb8aa3b, v91
	v_exp_f32_e32 v102, v102
	v_exp_f32_e32 v103, v103
	v_mul_f32_e32 v104, 0xbfb8aa3b, v92
	v_mul_f32_e32 v105, 0xbfb8aa3b, v93
	v_add_f32_e32 v98, 1.0, v98
	v_add_f32_e32 v99, 1.0, v99
	v_exp_f32_e32 v104, v104
	v_exp_f32_e32 v105, v105
	v_rcp_f32_e32 v98, v98
	v_rcp_f32_e32 v99, v99
	v_add_f32_e32 v100, 1.0, v100
	v_add_f32_e32 v101, 1.0, v101
	v_rcp_f32_e32 v100, v100
	v_rcp_f32_e32 v101, v101
	v_add_f32_e32 v102, 1.0, v102
	v_add_f32_e32 v103, 1.0, v103
	v_rcp_f32_e32 v102, v102
	v_rcp_f32_e32 v103, v103
	v_add_f32_e32 v104, 1.0, v104
	v_add_f32_e32 v105, 1.0, v105
	v_pk_mul_f32 v[94:95], v[94:95], v[98:99]
	v_rcp_f32_e32 v104, v104
	v_rcp_f32_e32 v105, v105
	v_pk_mul_f32 v[86:87], v[94:95], v[86:87]
	v_pk_mul_f32 v[94:95], v[96:97], v[100:101]
	v_cvt_pk_f16_f32 v86, v86, v87
	v_pk_mul_f32 v[88:89], v[94:95], v[88:89]
	s_mov_b64 s[14:15], s[4:5]
	v_cvt_pk_f16_f32 v87, v88, v89
	v_pk_mul_f32 v[88:89], v[90:91], v[102:103]
	s_nop 0
	v_pk_mul_f32 v[82:83], v[88:89], v[82:83]
	s_nop 0
	v_cvt_pk_f16_f32 v88, v82, v83
	v_pk_mul_f32 v[82:83], v[92:93], v[104:105]
	s_nop 0
	v_pk_mul_f32 v[82:83], v[82:83], v[84:85]
	v_mul_f32_e32 v84, 0xbfb8aa3b, v80
	v_cvt_pk_f16_f32 v89, v82, v83
	v_or_b32_e32 v82, 32, v140
	v_mad_i64_i32 v[82:83], s[10:11], v82, s3, v[114:115]
	v_lshl_add_u64 v[82:83], v[82:83], 0, v[116:117]
	global_store_dwordx4 v[82:83], v[86:89], off
	v_mul_f32_e32 v82, 0xbfb8aa3b, v78
	v_mul_f32_e32 v83, 0xbfb8aa3b, v79
	v_exp_f32_e32 v82, v82
	v_exp_f32_e32 v83, v83
	v_mul_f32_e32 v85, 0xbfb8aa3b, v81
	v_exp_f32_e32 v84, v84
	v_exp_f32_e32 v85, v85
	v_mul_f32_e32 v86, 0xbfb8aa3b, v74
	v_mul_f32_e32 v87, 0xbfb8aa3b, v75
	v_exp_f32_e32 v86, v86
	v_exp_f32_e32 v87, v87
	v_mul_f32_e32 v88, 0xbfb8aa3b, v76
	v_mul_f32_e32 v89, 0xbfb8aa3b, v77
	v_add_f32_e32 v82, 1.0, v82
	v_add_f32_e32 v83, 1.0, v83
	v_exp_f32_e32 v88, v88
	v_exp_f32_e32 v89, v89
	v_rcp_f32_e32 v82, v82
	v_rcp_f32_e32 v83, v83
	v_add_f32_e32 v84, 1.0, v84
	v_add_f32_e32 v85, 1.0, v85
	v_rcp_f32_e32 v84, v84
	v_rcp_f32_e32 v85, v85
	v_add_f32_e32 v86, 1.0, v86
	v_add_f32_e32 v87, 1.0, v87
	v_rcp_f32_e32 v86, v86
	v_rcp_f32_e32 v87, v87
	v_add_f32_e32 v88, 1.0, v88
	v_add_f32_e32 v89, 1.0, v89
	v_pk_mul_f32 v[78:79], v[78:79], v[82:83]
	v_rcp_f32_e32 v88, v88
	v_rcp_f32_e32 v89, v89
	v_pk_mul_f32 v[70:71], v[78:79], v[70:71]
	v_pk_mul_f32 v[78:79], v[80:81], v[84:85]
	v_cvt_pk_f16_f32 v70, v70, v71
	v_pk_mul_f32 v[72:73], v[78:79], v[72:73]
	s_nop 0
	v_cvt_pk_f16_f32 v71, v72, v73
	v_pk_mul_f32 v[72:73], v[74:75], v[86:87]
	v_add_u32_e32 v74, 0x80, v140
	v_pk_mul_f32 v[66:67], v[72:73], v[66:67]
	s_nop 0
	v_cvt_pk_f16_f32 v72, v66, v67
	v_pk_mul_f32 v[66:67], v[76:77], v[88:89]
	s_nop 0
	v_pk_mul_f32 v[66:67], v[66:67], v[68:69]
	v_mul_f32_e32 v68, 0xbfb8aa3b, v64
	v_cvt_pk_f16_f32 v73, v66, v67
	v_or_b32_e32 v66, 48, v140
	v_mad_i64_i32 v[66:67], s[10:11], v66, s3, v[114:115]
	v_lshl_add_u64 v[66:67], v[66:67], 0, v[116:117]
	global_store_dwordx4 v[66:67], v[70:73], off
	v_mul_f32_e32 v66, 0xbfb8aa3b, v62
	v_mul_f32_e32 v67, 0xbfb8aa3b, v63
	v_exp_f32_e32 v66, v66
	v_exp_f32_e32 v67, v67
	v_mul_f32_e32 v69, 0xbfb8aa3b, v65
	v_exp_f32_e32 v68, v68
	v_exp_f32_e32 v69, v69
	v_mul_f32_e32 v70, 0xbfb8aa3b, v58
	v_mul_f32_e32 v71, 0xbfb8aa3b, v59
	v_exp_f32_e32 v70, v70
	v_exp_f32_e32 v71, v71
	v_mul_f32_e32 v72, 0xbfb8aa3b, v60
	v_mul_f32_e32 v73, 0xbfb8aa3b, v61
	v_add_f32_e32 v66, 1.0, v66
	v_add_f32_e32 v67, 1.0, v67
	v_exp_f32_e32 v72, v72
	v_exp_f32_e32 v73, v73
	v_rcp_f32_e32 v66, v66
	v_rcp_f32_e32 v67, v67
	v_add_f32_e32 v68, 1.0, v68
	v_add_f32_e32 v69, 1.0, v69
	v_rcp_f32_e32 v68, v68
	v_rcp_f32_e32 v69, v69
	v_add_f32_e32 v70, 1.0, v70
	v_add_f32_e32 v71, 1.0, v71
	v_rcp_f32_e32 v70, v70
	v_rcp_f32_e32 v71, v71
	v_add_f32_e32 v72, 1.0, v72
	v_add_f32_e32 v73, 1.0, v73
	v_pk_mul_f32 v[62:63], v[62:63], v[66:67]
	v_rcp_f32_e32 v72, v72
	v_rcp_f32_e32 v73, v73
	v_pk_mul_f32 v[54:55], v[62:63], v[54:55]
	v_pk_mul_f32 v[62:63], v[64:65], v[68:69]
	v_cvt_pk_f16_f32 v54, v54, v55
	v_pk_mul_f32 v[56:57], v[62:63], v[56:57]
	s_nop 0
	v_cvt_pk_f16_f32 v55, v56, v57
	v_pk_mul_f32 v[56:57], v[58:59], v[70:71]
	s_nop 0
	v_pk_mul_f32 v[50:51], v[56:57], v[50:51]
	s_nop 0
	v_cvt_pk_f16_f32 v56, v50, v51
	v_pk_mul_f32 v[50:51], v[60:61], v[72:73]
	s_nop 0
	v_pk_mul_f32 v[50:51], v[50:51], v[52:53]
	v_mul_f32_e32 v52, 0xbfb8aa3b, v48
	v_cvt_pk_f16_f32 v57, v50, v51
	v_mad_i64_i32 v[50:51], s[10:11], v74, s3, v[114:115]
	v_lshl_add_u64 v[50:51], v[50:51], 0, v[116:117]
	global_store_dwordx4 v[50:51], v[54:57], off
	v_mul_f32_e32 v50, 0xbfb8aa3b, v46
	v_mul_f32_e32 v51, 0xbfb8aa3b, v47
	v_exp_f32_e32 v50, v50
	v_exp_f32_e32 v51, v51
	v_mul_f32_e32 v53, 0xbfb8aa3b, v49
	v_exp_f32_e32 v52, v52
	v_exp_f32_e32 v53, v53
	v_mul_f32_e32 v54, 0xbfb8aa3b, v42
	v_mul_f32_e32 v55, 0xbfb8aa3b, v43
	v_exp_f32_e32 v54, v54
	v_exp_f32_e32 v55, v55
	v_mul_f32_e32 v56, 0xbfb8aa3b, v44
	v_mul_f32_e32 v57, 0xbfb8aa3b, v45
	v_add_f32_e32 v50, 1.0, v50
	v_add_f32_e32 v51, 1.0, v51
	v_exp_f32_e32 v56, v56
	v_exp_f32_e32 v57, v57
	v_rcp_f32_e32 v50, v50
	v_rcp_f32_e32 v51, v51
	v_add_f32_e32 v52, 1.0, v52
	v_add_f32_e32 v53, 1.0, v53
	v_rcp_f32_e32 v52, v52
	v_rcp_f32_e32 v53, v53
	v_add_f32_e32 v54, 1.0, v54
	v_add_f32_e32 v55, 1.0, v55
	v_rcp_f32_e32 v54, v54
	v_rcp_f32_e32 v55, v55
	v_add_f32_e32 v56, 1.0, v56
	v_add_f32_e32 v57, 1.0, v57
	v_pk_mul_f32 v[46:47], v[46:47], v[50:51]
	v_rcp_f32_e32 v56, v56
	v_rcp_f32_e32 v57, v57
	v_pk_mul_f32 v[38:39], v[46:47], v[38:39]
	v_pk_mul_f32 v[46:47], v[48:49], v[52:53]
	v_cvt_pk_f16_f32 v38, v38, v39
	v_pk_mul_f32 v[40:41], v[46:47], v[40:41]
	s_nop 0
	v_cvt_pk_f16_f32 v39, v40, v41
	v_pk_mul_f32 v[40:41], v[42:43], v[54:55]
	s_nop 0
	v_pk_mul_f32 v[34:35], v[40:41], v[34:35]
	s_nop 0
	v_cvt_pk_f16_f32 v40, v34, v35
	v_pk_mul_f32 v[34:35], v[44:45], v[56:57]
	s_nop 0
	v_pk_mul_f32 v[34:35], v[34:35], v[36:37]
	v_mul_f32_e32 v36, 0xbfb8aa3b, v30
	v_cvt_pk_f16_f32 v41, v34, v35
	v_add_u32_e32 v34, 0x90, v140
	v_mad_i64_i32 v[34:35], s[10:11], v34, s3, v[114:115]
	v_lshl_add_u64 v[34:35], v[34:35], 0, v[116:117]
	global_store_dwordx4 v[34:35], v[38:41], off
	v_mul_f32_e32 v34, 0xbfb8aa3b, v28
	v_mul_f32_e32 v35, 0xbfb8aa3b, v29
	v_exp_f32_e32 v34, v34
	v_exp_f32_e32 v35, v35
	v_mul_f32_e32 v37, 0xbfb8aa3b, v31
	v_exp_f32_e32 v36, v36
	v_exp_f32_e32 v37, v37
	v_mul_f32_e32 v38, 0xbfb8aa3b, v24
	v_mul_f32_e32 v39, 0xbfb8aa3b, v25
	v_exp_f32_e32 v38, v38
	v_exp_f32_e32 v39, v39
	v_mul_f32_e32 v40, 0xbfb8aa3b, v26
	v_mul_f32_e32 v41, 0xbfb8aa3b, v27
	v_add_f32_e32 v34, 1.0, v34
	v_add_f32_e32 v35, 1.0, v35
	v_exp_f32_e32 v40, v40
	v_exp_f32_e32 v41, v41
	v_rcp_f32_e32 v34, v34
	v_rcp_f32_e32 v35, v35
	v_add_f32_e32 v36, 1.0, v36
	v_add_f32_e32 v37, 1.0, v37
	v_rcp_f32_e32 v36, v36
	v_rcp_f32_e32 v37, v37
	v_add_f32_e32 v38, 1.0, v38
	v_add_f32_e32 v39, 1.0, v39
	v_rcp_f32_e32 v38, v38
	v_rcp_f32_e32 v39, v39
	v_add_f32_e32 v40, 1.0, v40
	v_add_f32_e32 v41, 1.0, v41
	v_pk_mul_f32 v[28:29], v[28:29], v[34:35]
	v_rcp_f32_e32 v40, v40
	v_rcp_f32_e32 v41, v41
	v_pk_mul_f32 v[20:21], v[28:29], v[20:21]
	v_pk_mul_f32 v[28:29], v[30:31], v[36:37]
	v_cvt_pk_f16_f32 v20, v20, v21
	v_pk_mul_f32 v[22:23], v[28:29], v[22:23]
	s_nop 0
	v_cvt_pk_f16_f32 v21, v22, v23
	v_pk_mul_f32 v[22:23], v[24:25], v[38:39]
	s_nop 0
	v_pk_mul_f32 v[16:17], v[22:23], v[16:17]
	s_nop 0
	v_cvt_pk_f16_f32 v22, v16, v17
	v_pk_mul_f32 v[16:17], v[26:27], v[40:41]
	s_nop 0
	v_pk_mul_f32 v[16:17], v[16:17], v[18:19]
	v_mul_f32_e32 v18, 0xbfb8aa3b, v14
	v_cvt_pk_f16_f32 v23, v16, v17
	v_add_u32_e32 v16, 0xa0, v140
	v_mad_i64_i32 v[16:17], s[10:11], v16, s3, v[114:115]
	v_lshl_add_u64 v[16:17], v[16:17], 0, v[116:117]
	global_store_dwordx4 v[16:17], v[20:23], off
	v_mul_f32_e32 v16, 0xbfb8aa3b, v12
	v_mul_f32_e32 v17, 0xbfb8aa3b, v13
	v_exp_f32_e32 v16, v16
	v_exp_f32_e32 v17, v17
	v_mul_f32_e32 v19, 0xbfb8aa3b, v15
	v_exp_f32_e32 v18, v18
	v_exp_f32_e32 v19, v19
	v_mul_f32_e32 v20, 0xbfb8aa3b, v8
	v_mul_f32_e32 v21, 0xbfb8aa3b, v9
	v_exp_f32_e32 v20, v20
	v_exp_f32_e32 v21, v21
	v_mul_f32_e32 v22, 0xbfb8aa3b, v10
	v_mul_f32_e32 v23, 0xbfb8aa3b, v11
	v_add_f32_e32 v16, 1.0, v16
	v_add_f32_e32 v17, 1.0, v17
	v_exp_f32_e32 v22, v22
	v_exp_f32_e32 v23, v23
	v_rcp_f32_e32 v16, v16
	v_rcp_f32_e32 v17, v17
	v_add_f32_e32 v18, 1.0, v18
	v_add_f32_e32 v19, 1.0, v19
	v_rcp_f32_e32 v18, v18
	v_rcp_f32_e32 v19, v19
	v_add_f32_e32 v20, 1.0, v20
	v_add_f32_e32 v21, 1.0, v21
	v_rcp_f32_e32 v20, v20
	v_rcp_f32_e32 v21, v21
	v_add_f32_e32 v22, 1.0, v22
	v_add_f32_e32 v23, 1.0, v23
	v_pk_mul_f32 v[12:13], v[12:13], v[16:17]
	v_rcp_f32_e32 v22, v22
	v_rcp_f32_e32 v23, v23
	v_pk_mul_f32 v[4:5], v[12:13], v[4:5]
	v_pk_mul_f32 v[12:13], v[14:15], v[18:19]
	v_cvt_pk_f16_f32 v4, v4, v5
	v_pk_mul_f32 v[6:7], v[12:13], v[6:7]
	s_nop 0
	v_cvt_pk_f16_f32 v5, v6, v7
	v_pk_mul_f32 v[6:7], v[8:9], v[20:21]
	s_nop 0
	v_pk_mul_f32 v[0:1], v[6:7], v[0:1]
	s_nop 0
	v_cvt_pk_f16_f32 v6, v0, v1
	v_pk_mul_f32 v[0:1], v[10:11], v[22:23]
	s_nop 0
	v_pk_mul_f32 v[0:1], v[0:1], v[2:3]
	s_nop 0
	v_cvt_pk_f16_f32 v7, v0, v1
	v_add_u32_e32 v0, 0xb0, v140
	v_mad_i64_i32 v[0:1], s[10:11], v0, s3, v[114:115]
	v_lshl_add_u64 v[0:1], v[0:1], 0, v[116:117]
	global_store_dwordx4 v[0:1], v[4:7], off
	s_cmp_lg_u32 s34, 1
	s_cbranch_scc1 .Lups_skip
	s_and_b32 s0, s91, 63
	s_cmp_gt_u32 s0, 5
	s_cbranch_scc1 .Lups_skip
	s_cmp_gt_u32 s91, 196
	s_cbranch_scc1 .Lups_skip
	s_waitcnt vmcnt(0)
	s_barrier
	v_readlane_b32 s0, v251, 36
	s_cmp_lg_u32 s0, 0
	s_cbranch_scc1 .Lups_skip
	buffer_wbl2 sc1
	s_waitcnt vmcnt(0)
	v_readlane_b32 s2, v255, 45
	v_readlane_b32 s3, v254, 25
	s_lshl_b32 s2, s2, 1
	s_cmp_eq_u32 s3, 0
	s_cselect_b32 s3, 1, 0
	s_add_i32 s2, s2, s3
	s_lshl_b32 s2, s2, 2
	s_add_i32 s2, s2, 14016
	v_readlane_b32 s0, v251, 32
	v_readlane_b32 s1, v251, 33
	s_add_u32 s0, s0, s2
	s_addc_u32 s1, s1, 0
	s_mov_b64 s[2:3], exec
	s_mov_b64 exec, 1
	global_atomic_add v33, v248, s[0:1]
	s_mov_b64 exec, s[2:3]

.LBB0_1365:
	s_add_i32 s46, s14, 2
	s_add_u32 s12, s10, 0x100
	s_addc_u32 s13, s11, 0
	s_add_i32 s47, 0, 0x10000
	v_add_u32_e32 v134, s47, v230
	ds_read_b128 v[106:109], v134
	ds_read_b128 v[114:117], v134 offset:2048
	ds_read_b128 v[110:113], v134 offset:1024
	ds_read_b128 v[134:137], v134 offset:3072
	s_cmp_eq_u32 s43, s14
	s_cselect_b32 s14, s8, s44
	s_cselect_b32 s17, s7, s13
	s_cselect_b32 s16, s6, s12
	s_cselect_b32 s15, s9, s45
	v_lshl_add_u64 v[178:179], s[10:11], 0, v[184:185]
	s_add_i32 m0, s24, 0xc000
	ds_read_b128 v[138:141], v232
	ds_read_b128 v[154:157], v232 offset:2048
	ds_read_b128 v[162:165], v232 offset:4096
	ds_read_b128 v[170:173], v232 offset:6144
	ds_read_b128 v[150:153], v232 offset:1024
	ds_read_b128 v[158:161], v232 offset:3072
	ds_read_b128 v[166:169], v232 offset:5120
	ds_read_b128 v[174:177], v232 offset:7168
	global_load_lds_dwordx4 v[178:179], off
	v_lshl_add_u64 v[178:179], s[10:11], 0, v[186:187]
	s_add_i32 m0, s24, 0xe000
	s_nop 0
	global_load_lds_dwordx4 v[178:179], off
	s_waitcnt lgkmcnt(8)
	s_barrier
	s_waitcnt lgkmcnt(6)
	s_setprio 1
	v_mfma_f32_16x16x32_f16 v[146:149], v[106:109], v[138:141], v[146:149]
	v_mfma_f32_16x16x32_f16 v[142:145], v[114:117], v[138:141], v[142:145]
	v_mfma_f32_16x16x32_f16 v[130:133], v[106:109], v[154:157], v[130:133]
	v_mfma_f32_16x16x32_f16 v[122:125], v[114:117], v[154:157], v[122:125]
	s_waitcnt lgkmcnt(4)
	v_mfma_f32_16x16x32_f16 v[94:97], v[106:109], v[162:165], v[94:97]
	v_mfma_f32_16x16x32_f16 v[90:93], v[114:117], v[162:165], v[90:93]
	v_mfma_f32_16x16x32_f16 v[78:81], v[106:109], v[170:173], v[78:81]
	v_mfma_f32_16x16x32_f16 v[74:77], v[114:117], v[170:173], v[74:77]
	s_waitcnt lgkmcnt(2)
	v_mfma_f32_16x16x32_f16 v[146:149], v[110:113], v[150:153], v[146:149]
	v_mfma_f32_16x16x32_f16 v[142:145], v[134:137], v[150:153], v[142:145]
	v_mfma_f32_16x16x32_f16 v[130:133], v[110:113], v[158:161], v[130:133]
	v_mfma_f32_16x16x32_f16 v[122:125], v[134:137], v[158:161], v[122:125]
	s_waitcnt lgkmcnt(0)
	v_mfma_f32_16x16x32_f16 v[94:97], v[110:113], v[166:169], v[94:97]
	v_mfma_f32_16x16x32_f16 v[90:93], v[134:137], v[166:169], v[90:93]
	v_mfma_f32_16x16x32_f16 v[78:81], v[110:113], v[174:177], v[78:81]
	v_mfma_f32_16x16x32_f16 v[74:77], v[134:137], v[174:177], v[74:77]
	s_setprio 0
	s_barrier
	s_add_i32 s48, 0, 0x14000
	s_add_i32 s10, s47, s23
	v_add_u32_e32 v196, s48, v230
	v_lshl_add_u64 v[200:201], s[14:15], 0, v[32:33]
	s_mov_b32 m0, s10
	ds_read_b128 v[178:181], v196
	ds_read_b128 v[192:195], v196 offset:2048
	ds_read_b128 v[188:191], v196 offset:1024
	ds_read_b128 v[196:199], v196 offset:3072
	global_load_lds_dwordx4 v[200:201], off
	v_lshl_add_u64 v[202:203], s[14:15], 0, v[182:183]
	s_add_i32 m0, s10, 0x2000
	s_nop 0
	global_load_lds_dwordx4 v[202:203], off
	s_barrier
	s_waitcnt lgkmcnt(2)
	s_setprio 1
	v_mfma_f32_16x16x32_f16 v[126:129], v[178:181], v[138:141], v[126:129]
	v_mfma_f32_16x16x32_f16 v[118:121], v[192:195], v[138:141], v[118:121]
	v_mfma_f32_16x16x32_f16 v[102:105], v[178:181], v[154:157], v[102:105]
	v_mfma_f32_16x16x32_f16 v[98:101], v[192:195], v[154:157], v[98:101]
	v_mfma_f32_16x16x32_f16 v[86:89], v[178:181], v[162:165], v[86:89]
	v_mfma_f32_16x16x32_f16 v[82:85], v[192:195], v[162:165], v[82:85]
	v_mfma_f32_16x16x32_f16 v[70:73], v[178:181], v[170:173], v[70:73]
	v_mfma_f32_16x16x32_f16 v[66:69], v[192:195], v[170:173], v[66:69]
	s_waitcnt lgkmcnt(0)
	v_mfma_f32_16x16x32_f16 v[126:129], v[188:191], v[150:153], v[126:129]
	v_mfma_f32_16x16x32_f16 v[118:121], v[196:199], v[150:153], v[118:121]
	v_mfma_f32_16x16x32_f16 v[102:105], v[188:191], v[158:161], v[102:105]
	v_mfma_f32_16x16x32_f16 v[98:101], v[196:199], v[158:161], v[98:101]
	v_mfma_f32_16x16x32_f16 v[86:89], v[188:191], v[166:169], v[86:89]
	v_mfma_f32_16x16x32_f16 v[82:85], v[196:199], v[166:169], v[82:85]
	v_mfma_f32_16x16x32_f16 v[70:73], v[188:191], v[174:177], v[70:73]
	v_mfma_f32_16x16x32_f16 v[66:69], v[196:199], v[174:177], v[66:69]
	s_setprio 0
	s_mov_b32 m0, s24
	v_lshl_add_u64 v[204:205], s[16:17], 0, v[32:33]
	s_barrier
	ds_read_b128 v[138:141], v232 offset:16384
	ds_read_b128 v[154:157], v232 offset:18432
	ds_read_b128 v[162:165], v232 offset:20480
	ds_read_b128 v[170:173], v232 offset:22528
	ds_read_b128 v[150:153], v232 offset:17408
	ds_read_b128 v[158:161], v232 offset:19456
	ds_read_b128 v[166:169], v232 offset:21504
	ds_read_b128 v[174:177], v232 offset:23552
	global_load_lds_dwordx4 v[204:205], off
	v_lshl_add_u64 v[206:207], s[16:17], 0, v[182:183]
	s_mov_b32 m0, s25
	s_nop 0
	global_load_lds_dwordx4 v[206:207], off
	s_barrier
	s_waitcnt lgkmcnt(6)
	s_setprio 1
	v_mfma_f32_16x16x32_f16 v[62:65], v[106:109], v[138:141], v[62:65]
	v_mfma_f32_16x16x32_f16 v[58:61], v[114:117], v[138:141], v[58:61]
	v_mfma_f32_16x16x32_f16 v[46:49], v[106:109], v[154:157], v[46:49]
	v_mfma_f32_16x16x32_f16 v[42:45], v[114:117], v[154:157], v[42:45]
	s_waitcnt lgkmcnt(4)
	v_mfma_f32_16x16x32_f16 v[28:31], v[106:109], v[162:165], v[28:31]
	v_mfma_f32_16x16x32_f16 v[24:27], v[114:117], v[162:165], v[24:27]
	v_mfma_f32_16x16x32_f16 v[12:15], v[106:109], v[170:173], v[12:15]
	v_mfma_f32_16x16x32_f16 v[8:11], v[114:117], v[170:173], v[8:11]
	s_waitcnt lgkmcnt(2)
	v_mfma_f32_16x16x32_f16 v[62:65], v[110:113], v[150:153], v[62:65]
	v_mfma_f32_16x16x32_f16 v[58:61], v[134:137], v[150:153], v[58:61]
	v_mfma_f32_16x16x32_f16 v[46:49], v[110:113], v[158:161], v[46:49]
	v_mfma_f32_16x16x32_f16 v[42:45], v[134:137], v[158:161], v[42:45]
	s_waitcnt lgkmcnt(0)
	v_mfma_f32_16x16x32_f16 v[28:31], v[110:113], v[166:169], v[28:31]
	v_mfma_f32_16x16x32_f16 v[24:27], v[134:137], v[166:169], v[24:27]
	v_mfma_f32_16x16x32_f16 v[12:15], v[110:113], v[174:177], v[12:15]
	v_mfma_f32_16x16x32_f16 v[8:11], v[134:137], v[174:177], v[8:11]
	s_setprio 0
	s_barrier
	s_add_u32 s10, s14, 0xb0000
	s_addc_u32 s11, s15, 0
	s_add_i32 s47, s48, s23
	v_lshl_add_u64 v[106:107], s[10:11], 0, v[32:33]
	s_mov_b32 m0, s47
	s_nop 0
	global_load_lds_dwordx4 v[106:107], off
	v_lshl_add_u64 v[106:107], s[10:11], 0, v[182:183]
	s_add_i32 m0, s47, 0x2000
	s_nop 0
	global_load_lds_dwordx4 v[106:107], off
	s_waitcnt vmcnt(6)
	s_barrier
	s_setprio 1
	v_mfma_f32_16x16x32_f16 v[54:57], v[178:181], v[138:141], v[54:57]
	v_mfma_f32_16x16x32_f16 v[50:53], v[192:195], v[138:141], v[50:53]
	v_mfma_f32_16x16x32_f16 v[38:41], v[178:181], v[154:157], v[38:41]
	v_mfma_f32_16x16x32_f16 v[34:37], v[192:195], v[154:157], v[34:37]
	v_mfma_f32_16x16x32_f16 v[20:23], v[178:181], v[162:165], v[20:23]
	v_mfma_f32_16x16x32_f16 v[16:19], v[192:195], v[162:165], v[16:19]
	v_mfma_f32_16x16x32_f16 v[4:7], v[178:181], v[170:173], v[4:7]
	v_mfma_f32_16x16x32_f16 v[0:3], v[192:195], v[170:173], v[0:3]
	v_mfma_f32_16x16x32_f16 v[54:57], v[188:191], v[150:153], v[54:57]
	v_mfma_f32_16x16x32_f16 v[50:53], v[196:199], v[150:153], v[50:53]
	v_mfma_f32_16x16x32_f16 v[38:41], v[188:191], v[158:161], v[38:41]
	v_mfma_f32_16x16x32_f16 v[34:37], v[196:199], v[158:161], v[34:37]
	v_mfma_f32_16x16x32_f16 v[20:23], v[188:191], v[166:169], v[20:23]
	v_mfma_f32_16x16x32_f16 v[16:19], v[196:199], v[166:169], v[16:19]
	v_mfma_f32_16x16x32_f16 v[4:7], v[188:191], v[174:177], v[4:7]
	v_mfma_f32_16x16x32_f16 v[0:3], v[196:199], v[174:177], v[0:3]
	s_setprio 0
	s_add_i32 s47, 0, 0x18000
	v_add_u32_e32 v134, s47, v230
	s_barrier
	ds_read_b128 v[106:109], v134
	ds_read_b128 v[114:117], v134 offset:2048
	ds_read_b128 v[110:113], v134 offset:1024
	ds_read_b128 v[134:137], v134 offset:3072
	s_add_u32 s10, s16, 0xb0000
	s_addc_u32 s11, s17, 0
	s_mov_b32 m0, s26
	v_lshl_add_u64 v[178:179], s[10:11], 0, v[32:33]
	ds_read_b128 v[138:141], v232 offset:32768
	ds_read_b128 v[154:157], v232 offset:34816
	ds_read_b128 v[162:165], v232 offset:36864
	ds_read_b128 v[170:173], v232 offset:38912
	ds_read_b128 v[150:153], v232 offset:33792
	ds_read_b128 v[158:161], v232 offset:35840
	ds_read_b128 v[166:169], v232 offset:37888
	ds_read_b128 v[174:177], v232 offset:39936
	global_load_lds_dwordx4 v[178:179], off
	v_lshl_add_u64 v[178:179], s[10:11], 0, v[182:183]
	s_mov_b32 m0, s27
	s_nop 0
	global_load_lds_dwordx4 v[178:179], off
	s_waitcnt lgkmcnt(8)
	s_barrier
	s_waitcnt lgkmcnt(6)
	s_setprio 1
	v_mfma_f32_16x16x32_f16 v[146:149], v[106:109], v[138:141], v[146:149]
	v_mfma_f32_16x16x32_f16 v[142:145], v[114:117], v[138:141], v[142:145]
	v_mfma_f32_16x16x32_f16 v[130:133], v[106:109], v[154:157], v[130:133]
	v_mfma_f32_16x16x32_f16 v[122:125], v[114:117], v[154:157], v[122:125]
	s_waitcnt lgkmcnt(4)
	v_mfma_f32_16x16x32_f16 v[94:97], v[106:109], v[162:165], v[94:97]
	v_mfma_f32_16x16x32_f16 v[90:93], v[114:117], v[162:165], v[90:93]
	v_mfma_f32_16x16x32_f16 v[78:81], v[106:109], v[170:173], v[78:81]
	v_mfma_f32_16x16x32_f16 v[74:77], v[114:117], v[170:173], v[74:77]
	s_waitcnt lgkmcnt(2)
	v_mfma_f32_16x16x32_f16 v[146:149], v[110:113], v[150:153], v[146:149]
	v_mfma_f32_16x16x32_f16 v[142:145], v[134:137], v[150:153], v[142:145]
	v_mfma_f32_16x16x32_f16 v[130:133], v[110:113], v[158:161], v[130:133]
	v_mfma_f32_16x16x32_f16 v[122:125], v[134:137], v[158:161], v[122:125]
	s_waitcnt lgkmcnt(0)
	v_mfma_f32_16x16x32_f16 v[94:97], v[110:113], v[166:169], v[94:97]
	v_mfma_f32_16x16x32_f16 v[90:93], v[134:137], v[166:169], v[90:93]
	v_mfma_f32_16x16x32_f16 v[78:81], v[110:113], v[174:177], v[78:81]
	v_mfma_f32_16x16x32_f16 v[74:77], v[134:137], v[174:177], v[74:77]
	s_setprio 0
	s_barrier
	s_add_i32 s16, 0, 0x1c000
	s_add_i32 s10, s47, s23
	v_add_u32_e32 v196, s16, v230
	v_lshl_add_u64 v[200:201], v[200:201], 0, s[84:85]
	s_mov_b32 m0, s10
	ds_read_b128 v[178:181], v196
	ds_read_b128 v[192:195], v196 offset:2048
	ds_read_b128 v[188:191], v196 offset:1024
	ds_read_b128 v[196:199], v196 offset:3072
	global_load_lds_dwordx4 v[200:201], off
	v_lshl_add_u64 v[200:201], v[202:203], 0, s[84:85]
	s_add_i32 m0, s10, 0x2000
	s_nop 0
	global_load_lds_dwordx4 v[200:201], off
	s_barrier
	s_waitcnt lgkmcnt(2)
	s_setprio 1
	v_mfma_f32_16x16x32_f16 v[126:129], v[178:181], v[138:141], v[126:129]
	v_mfma_f32_16x16x32_f16 v[118:121], v[192:195], v[138:141], v[118:121]
	v_mfma_f32_16x16x32_f16 v[102:105], v[178:181], v[154:157], v[102:105]
	v_mfma_f32_16x16x32_f16 v[98:101], v[192:195], v[154:157], v[98:101]
	v_mfma_f32_16x16x32_f16 v[86:89], v[178:181], v[162:165], v[86:89]
	v_mfma_f32_16x16x32_f16 v[82:85], v[192:195], v[162:165], v[82:85]
	v_mfma_f32_16x16x32_f16 v[70:73], v[178:181], v[170:173], v[70:73]
	v_mfma_f32_16x16x32_f16 v[66:69], v[192:195], v[170:173], v[66:69]
	s_waitcnt lgkmcnt(0)
	v_mfma_f32_16x16x32_f16 v[126:129], v[188:191], v[150:153], v[126:129]
	v_mfma_f32_16x16x32_f16 v[118:121], v[196:199], v[150:153], v[118:121]
	v_mfma_f32_16x16x32_f16 v[102:105], v[188:191], v[158:161], v[102:105]
	v_mfma_f32_16x16x32_f16 v[98:101], v[196:199], v[158:161], v[98:101]
	v_mfma_f32_16x16x32_f16 v[86:89], v[188:191], v[166:169], v[86:89]
	v_mfma_f32_16x16x32_f16 v[82:85], v[196:199], v[166:169], v[82:85]
	v_mfma_f32_16x16x32_f16 v[70:73], v[188:191], v[174:177], v[70:73]
	v_mfma_f32_16x16x32_f16 v[66:69], v[196:199], v[174:177], v[66:69]
	s_setprio 0
	s_mov_b32 m0, s29
	v_lshl_add_u64 v[200:201], v[204:205], 0, s[84:85]
	s_barrier
	ds_read_b128 v[138:141], v232 offset:49152
	ds_read_b128 v[154:157], v232 offset:51200
	ds_read_b128 v[162:165], v232 offset:53248
	ds_read_b128 v[170:173], v232 offset:55296
	ds_read_b128 v[150:153], v232 offset:50176
	ds_read_b128 v[158:161], v232 offset:52224
	ds_read_b128 v[166:169], v232 offset:54272
	ds_read_b128 v[174:177], v232 offset:56320
	global_load_lds_dwordx4 v[200:201], off
	v_lshl_add_u64 v[200:201], v[206:207], 0, s[84:85]
	s_mov_b32 m0, s30
	s_nop 0
	global_load_lds_dwordx4 v[200:201], off
	s_barrier
	s_waitcnt lgkmcnt(6)
	s_setprio 1
	v_mfma_f32_16x16x32_f16 v[62:65], v[106:109], v[138:141], v[62:65]
	v_mfma_f32_16x16x32_f16 v[58:61], v[114:117], v[138:141], v[58:61]
	v_mfma_f32_16x16x32_f16 v[46:49], v[106:109], v[154:157], v[46:49]
	v_mfma_f32_16x16x32_f16 v[42:45], v[114:117], v[154:157], v[42:45]
	s_waitcnt lgkmcnt(4)
	v_mfma_f32_16x16x32_f16 v[28:31], v[106:109], v[162:165], v[28:31]
	v_mfma_f32_16x16x32_f16 v[24:27], v[114:117], v[162:165], v[24:27]
	v_mfma_f32_16x16x32_f16 v[12:15], v[106:109], v[170:173], v[12:15]
	v_mfma_f32_16x16x32_f16 v[8:11], v[114:117], v[170:173], v[8:11]
	s_waitcnt lgkmcnt(2)
	v_mfma_f32_16x16x32_f16 v[62:65], v[110:113], v[150:153], v[62:65]
	v_mfma_f32_16x16x32_f16 v[58:61], v[134:137], v[150:153], v[58:61]
	v_mfma_f32_16x16x32_f16 v[46:49], v[110:113], v[158:161], v[46:49]
	v_mfma_f32_16x16x32_f16 v[42:45], v[134:137], v[158:161], v[42:45]
	s_waitcnt lgkmcnt(0)
	v_mfma_f32_16x16x32_f16 v[28:31], v[110:113], v[166:169], v[28:31]
	v_mfma_f32_16x16x32_f16 v[24:27], v[134:137], v[166:169], v[24:27]
	v_mfma_f32_16x16x32_f16 v[12:15], v[110:113], v[174:177], v[12:15]
	v_mfma_f32_16x16x32_f16 v[8:11], v[134:137], v[174:177], v[8:11]
	s_setprio 0
	s_barrier
	s_add_u32 s10, s14, 0xb0080
	s_addc_u32 s11, s15, 0
	s_add_i32 s14, s16, s23
	v_lshl_add_u64 v[106:107], s[10:11], 0, v[32:33]
	s_mov_b32 m0, s14
	s_nop 0
	global_load_lds_dwordx4 v[106:107], off
	v_lshl_add_u64 v[106:107], s[10:11], 0, v[182:183]
	s_add_i32 m0, s14, 0x2000
	s_nop 0
	global_load_lds_dwordx4 v[106:107], off
	s_waitcnt vmcnt(6)
	s_barrier
	s_setprio 1
	v_mfma_f32_16x16x32_f16 v[54:57], v[178:181], v[138:141], v[54:57]
	v_mfma_f32_16x16x32_f16 v[50:53], v[192:195], v[138:141], v[50:53]
	v_mfma_f32_16x16x32_f16 v[38:41], v[178:181], v[154:157], v[38:41]
	v_mfma_f32_16x16x32_f16 v[34:37], v[192:195], v[154:157], v[34:37]
	v_mfma_f32_16x16x32_f16 v[20:23], v[178:181], v[162:165], v[20:23]
	v_mfma_f32_16x16x32_f16 v[16:19], v[192:195], v[162:165], v[16:19]
	v_mfma_f32_16x16x32_f16 v[4:7], v[178:181], v[170:173], v[4:7]
	v_mfma_f32_16x16x32_f16 v[0:3], v[192:195], v[170:173], v[0:3]
	v_mfma_f32_16x16x32_f16 v[54:57], v[188:191], v[150:153], v[54:57]
	v_mfma_f32_16x16x32_f16 v[50:53], v[196:199], v[150:153], v[50:53]
	v_mfma_f32_16x16x32_f16 v[38:41], v[188:191], v[158:161], v[38:41]
	v_mfma_f32_16x16x32_f16 v[34:37], v[196:199], v[158:161], v[34:37]
	v_mfma_f32_16x16x32_f16 v[20:23], v[188:191], v[166:169], v[20:23]
	v_mfma_f32_16x16x32_f16 v[16:19], v[196:199], v[166:169], v[16:19]
	v_mfma_f32_16x16x32_f16 v[4:7], v[188:191], v[174:177], v[4:7]
	v_mfma_f32_16x16x32_f16 v[0:3], v[196:199], v[174:177], v[0:3]
	s_setprio 0
	s_add_u32 s44, s44, 0x100
	s_addc_u32 s45, s45, 0
	s_cmp_ge_u32 s46, s42
	s_mov_b64 s[10:11], s[12:13]
	s_mov_b32 s14, s46
	s_barrier
	s_cbranch_scc0 .LBB0_1365
	s_cmp_eq_u32 s40, 0
	s_cselect_b32 s6, 0x9000, 0
	v_lshl_or_b32 v106, s41, 8, v231
	s_add_u32 s6, s31, s6
	s_addc_u32 s7, s34, 0
	v_ashrrev_i32_e32 v107, 31, v106
	v_lshl_add_u64 v[116:117], v[106:107], 2, s[6:7]
	global_load_dwordx4 v[108:111], v[116:117], off offset:16
	global_load_dwordx4 v[112:115], v[116:117], off
	s_cmp_eq_u32 s39, 0
	s_waitcnt vmcnt(0)
	v_pk_mul_f32 v[194:195], v[110:111], 0.5 op_sel_hi:[1,0]
	v_pk_mul_f32 v[198:199], v[114:115], 0.5 op_sel_hi:[1,0]
	v_pk_mul_f32 v[202:203], v[112:113], 0.5 op_sel_hi:[1,0]
	v_pk_mul_f32 v[200:201], v[108:109], 0.5 op_sel_hi:[1,0]
	global_load_dwordx4 v[108:111], v[116:117], off offset:528
	global_load_dwordx4 v[112:115], v[116:117], off offset:512
	s_waitcnt vmcnt(0)
	v_pk_mul_f32 v[188:189], v[110:111], 0.5 op_sel_hi:[1,0]
	v_pk_mul_f32 v[196:197], v[112:113], 0.5 op_sel_hi:[1,0]
	v_lshl_add_u32 v112, s40, 8, v229
	v_pk_mul_f32 v[190:191], v[114:115], 0.5 op_sel_hi:[1,0]
	v_pk_mul_f32 v[192:193], v[108:109], 0.5 op_sel_hi:[1,0]
	v_or_b32_e32 v114, 16, v112
	v_or_b32_e32 v110, 32, v112
	v_or_b32_e32 v108, 48, v112
	v_ashrrev_i32_e32 v113, 31, v112
	v_ashrrev_i32_e32 v115, 31, v114
	v_ashrrev_i32_e32 v111, 31, v110
	v_ashrrev_i32_e32 v109, 31, v108
	s_cbranch_scc1 .LBB0_1368
	s_add_i32 s96, s39, -1
	s_lshl_b64 s[6:7], s[96:97], 20
	v_readlane_b32 s8, v252, 11
	v_readlane_b32 s9, v252, 12
	s_add_u32 s6, s8, s6
	s_addc_u32 s7, s9, s7
	v_lshlrev_b64 v[138:139], 2, v[106:107]
	v_lshrrev_b32_e32 v150, 5, v220
	v_mul_u32_u24_e32 v150, 48, v150
	s_nop 0
	v_sub_co_u32_e32 v138, vcc, v138, v150
	s_nop 1
	v_subbrev_co_u32_e32 v139, vcc, 0, v139, vcc
	v_lshl_add_u64 v[138:139], s[6:7], 0, v[138:139]
	s_mov_b64 s[6:7], 0x80000
	v_lshlrev_b64 v[204:205], 12, v[112:113]
	v_lshl_add_u64 v[204:205], v[204:205], 0, v[138:139]
	v_lshl_add_u64 v[212:213], v[204:205], 0, s[6:7]
	v_lshlrev_b64 v[206:207], 12, v[114:115]
	v_lshl_add_u64 v[206:207], v[206:207], 0, v[138:139]
	v_lshl_add_u64 v[214:215], v[206:207], 0, s[6:7]
	v_lshlrev_b64 v[208:209], 12, v[110:111]
	v_lshl_add_u64 v[208:209], v[208:209], 0, v[138:139]
	v_lshl_add_u64 v[216:217], v[208:209], 0, s[6:7]
	v_lshlrev_b64 v[210:211], 12, v[108:109]
	v_lshl_add_u64 v[210:211], v[210:211], 0, v[138:139]
	v_lshl_add_u64 v[218:219], v[210:211], 0, s[6:7]
	s_waitcnt vmcnt(0)
	v_pk_mul_f32 v[152:153], v[146:147], v[202:203]
	v_pk_mul_f32 v[154:155], v[148:149], v[198:199]
	v_pk_mul_f32 v[156:157], v[142:143], v[200:201]
	v_pk_mul_f32 v[158:159], v[144:145], v[194:195]
	s_nop 1
	v_permlane32_swap_b32_e32 v152, v156
	v_permlane32_swap_b32_e32 v153, v157
	v_permlane32_swap_b32_e32 v154, v158
	v_permlane32_swap_b32_e32 v155, v159
	s_nop 0
	global_store_dwordx4 v[204:205], v[152:155], off
	global_store_dwordx4 v[204:205], v[156:159], off offset:64
	v_pk_mul_f32 v[160:161], v[126:127], v[196:197]
	v_pk_mul_f32 v[162:163], v[128:129], v[190:191]
	v_pk_mul_f32 v[164:165], v[118:119], v[192:193]
	v_pk_mul_f32 v[166:167], v[120:121], v[188:189]
	s_nop 1
	v_permlane32_swap_b32_e32 v160, v164
	v_permlane32_swap_b32_e32 v161, v165
	v_permlane32_swap_b32_e32 v162, v166
	v_permlane32_swap_b32_e32 v163, v167
	s_nop 0
	global_store_dwordx4 v[204:205], v[160:163], off offset:512
	global_store_dwordx4 v[204:205], v[164:167], off offset:576
	v_pk_mul_f32 v[168:169], v[130:131], v[202:203]
	v_pk_mul_f32 v[170:171], v[132:133], v[198:199]
	v_pk_mul_f32 v[172:173], v[122:123], v[200:201]
	v_pk_mul_f32 v[174:175], v[124:125], v[194:195]
	s_nop 1
	v_permlane32_swap_b32_e32 v168, v172
	v_permlane32_swap_b32_e32 v169, v173
	v_permlane32_swap_b32_e32 v170, v174
	v_permlane32_swap_b32_e32 v171, v175
	s_nop 0
	global_store_dwordx4 v[206:207], v[168:171], off
	global_store_dwordx4 v[206:207], v[172:175], off offset:64
	v_pk_mul_f32 v[176:177], v[102:103], v[196:197]
	v_pk_mul_f32 v[178:179], v[104:105], v[190:191]
	v_pk_mul_f32 v[180:181], v[98:99], v[192:193]
	v_pk_mul_f32 v[182:183], v[100:101], v[188:189]
	s_nop 1
	v_permlane32_swap_b32_e32 v176, v180
	v_permlane32_swap_b32_e32 v177, v181
	v_permlane32_swap_b32_e32 v178, v182
	v_permlane32_swap_b32_e32 v179, v183
	s_nop 0
	global_store_dwordx4 v[206:207], v[176:179], off offset:512
	global_store_dwordx4 v[206:207], v[180:183], off offset:576
	v_pk_mul_f32 v[152:153], v[94:95], v[202:203]
	v_pk_mul_f32 v[154:155], v[96:97], v[198:199]
	v_pk_mul_f32 v[156:157], v[90:91], v[200:201]
	v_pk_mul_f32 v[158:159], v[92:93], v[194:195]
	s_nop 1
	v_permlane32_swap_b32_e32 v152, v156
	v_permlane32_swap_b32_e32 v153, v157
	v_permlane32_swap_b32_e32 v154, v158
	v_permlane32_swap_b32_e32 v155, v159
	s_nop 0
	global_store_dwordx4 v[208:209], v[152:155], off
	global_store_dwordx4 v[208:209], v[156:159], off offset:64
	v_pk_mul_f32 v[160:161], v[86:87], v[196:197]
	v_pk_mul_f32 v[162:163], v[88:89], v[190:191]
	v_pk_mul_f32 v[164:165], v[82:83], v[192:193]
	v_pk_mul_f32 v[166:167], v[84:85], v[188:189]
	s_nop 1
	v_permlane32_swap_b32_e32 v160, v164
	v_permlane32_swap_b32_e32 v161, v165
	v_permlane32_swap_b32_e32 v162, v166
	v_permlane32_swap_b32_e32 v163, v167
	s_nop 0
	global_store_dwordx4 v[208:209], v[160:163], off offset:512
	global_store_dwordx4 v[208:209], v[164:167], off offset:576
	v_pk_mul_f32 v[168:169], v[78:79], v[202:203]
	v_pk_mul_f32 v[170:171], v[80:81], v[198:199]
	v_pk_mul_f32 v[172:173], v[74:75], v[200:201]
	v_pk_mul_f32 v[174:175], v[76:77], v[194:195]
	s_nop 1
	v_permlane32_swap_b32_e32 v168, v172
	v_permlane32_swap_b32_e32 v169, v173
	v_permlane32_swap_b32_e32 v170, v174
	v_permlane32_swap_b32_e32 v171, v175
	s_nop 0
	global_store_dwordx4 v[210:211], v[168:171], off
	global_store_dwordx4 v[210:211], v[172:175], off offset:64
	v_pk_mul_f32 v[176:177], v[70:71], v[196:197]
	v_pk_mul_f32 v[178:179], v[72:73], v[190:191]
	v_pk_mul_f32 v[180:181], v[66:67], v[192:193]
	v_pk_mul_f32 v[182:183], v[68:69], v[188:189]
	s_nop 1
	v_permlane32_swap_b32_e32 v176, v180
	v_permlane32_swap_b32_e32 v177, v181
	v_permlane32_swap_b32_e32 v178, v182
	v_permlane32_swap_b32_e32 v179, v183
	s_nop 0
	global_store_dwordx4 v[210:211], v[176:179], off offset:512
	global_store_dwordx4 v[210:211], v[180:183], off offset:576
	v_pk_mul_f32 v[152:153], v[62:63], v[202:203]
	v_pk_mul_f32 v[154:155], v[64:65], v[198:199]
	v_pk_mul_f32 v[156:157], v[58:59], v[200:201]
	v_pk_mul_f32 v[158:159], v[60:61], v[194:195]
	s_nop 1
	v_permlane32_swap_b32_e32 v152, v156
	v_permlane32_swap_b32_e32 v153, v157
	v_permlane32_swap_b32_e32 v154, v158
	v_permlane32_swap_b32_e32 v155, v159
	s_nop 0
	global_store_dwordx4 v[212:213], v[152:155], off
	global_store_dwordx4 v[212:213], v[156:159], off offset:64
	v_pk_mul_f32 v[160:161], v[54:55], v[196:197]
	v_pk_mul_f32 v[162:163], v[56:57], v[190:191]
	v_pk_mul_f32 v[164:165], v[50:51], v[192:193]
	v_pk_mul_f32 v[166:167], v[52:53], v[188:189]
	s_nop 1
	v_permlane32_swap_b32_e32 v160, v164
	v_permlane32_swap_b32_e32 v161, v165
	v_permlane32_swap_b32_e32 v162, v166
	v_permlane32_swap_b32_e32 v163, v167
	s_nop 0
	global_store_dwordx4 v[212:213], v[160:163], off offset:512
	global_store_dwordx4 v[212:213], v[164:167], off offset:576
	v_pk_mul_f32 v[168:169], v[46:47], v[202:203]
	v_pk_mul_f32 v[170:171], v[48:49], v[198:199]
	v_pk_mul_f32 v[172:173], v[42:43], v[200:201]
	v_pk_mul_f32 v[174:175], v[44:45], v[194:195]
	s_nop 1
	v_permlane32_swap_b32_e32 v168, v172
	v_permlane32_swap_b32_e32 v169, v173
	v_permlane32_swap_b32_e32 v170, v174
	v_permlane32_swap_b32_e32 v171, v175
	s_nop 0
	global_store_dwordx4 v[214:215], v[168:171], off
	global_store_dwordx4 v[214:215], v[172:175], off offset:64
	v_pk_mul_f32 v[176:177], v[38:39], v[196:197]
	v_pk_mul_f32 v[178:179], v[40:41], v[190:191]
	v_pk_mul_f32 v[180:181], v[34:35], v[192:193]
	v_pk_mul_f32 v[182:183], v[36:37], v[188:189]
	s_nop 1
	v_permlane32_swap_b32_e32 v176, v180
	v_permlane32_swap_b32_e32 v177, v181
	v_permlane32_swap_b32_e32 v178, v182
	v_permlane32_swap_b32_e32 v179, v183
	s_nop 0
	global_store_dwordx4 v[214:215], v[176:179], off offset:512
	global_store_dwordx4 v[214:215], v[180:183], off offset:576
	v_pk_mul_f32 v[152:153], v[28:29], v[202:203]
	v_pk_mul_f32 v[154:155], v[30:31], v[198:199]
	v_pk_mul_f32 v[156:157], v[24:25], v[200:201]
	v_pk_mul_f32 v[158:159], v[26:27], v[194:195]
	s_nop 1
	v_permlane32_swap_b32_e32 v152, v156
	v_permlane32_swap_b32_e32 v153, v157
	v_permlane32_swap_b32_e32 v154, v158
	v_permlane32_swap_b32_e32 v155, v159
	s_nop 0
	global_store_dwordx4 v[216:217], v[152:155], off
	global_store_dwordx4 v[216:217], v[156:159], off offset:64
	v_pk_mul_f32 v[160:161], v[20:21], v[196:197]
	v_pk_mul_f32 v[162:163], v[22:23], v[190:191]
	v_pk_mul_f32 v[164:165], v[16:17], v[192:193]
	v_pk_mul_f32 v[166:167], v[18:19], v[188:189]
	s_nop 1
	v_permlane32_swap_b32_e32 v160, v164
	v_permlane32_swap_b32_e32 v161, v165
	v_permlane32_swap_b32_e32 v162, v166
	v_permlane32_swap_b32_e32 v163, v167
	s_nop 0
	global_store_dwordx4 v[216:217], v[160:163], off offset:512
	global_store_dwordx4 v[216:217], v[164:167], off offset:576
	v_pk_mul_f32 v[168:169], v[12:13], v[202:203]
	v_pk_mul_f32 v[170:171], v[14:15], v[198:199]
	v_pk_mul_f32 v[172:173], v[8:9], v[200:201]
	v_pk_mul_f32 v[174:175], v[10:11], v[194:195]
	s_nop 1
	v_permlane32_swap_b32_e32 v168, v172
	v_permlane32_swap_b32_e32 v169, v173
	v_permlane32_swap_b32_e32 v170, v174
	v_permlane32_swap_b32_e32 v171, v175
	s_nop 0
	global_store_dwordx4 v[218:219], v[168:171], off
	global_store_dwordx4 v[218:219], v[172:175], off offset:64
	v_pk_mul_f32 v[176:177], v[4:5], v[196:197]
	v_pk_mul_f32 v[178:179], v[6:7], v[190:191]
	v_pk_mul_f32 v[180:181], v[0:1], v[192:193]
	v_pk_mul_f32 v[182:183], v[2:3], v[188:189]
	s_nop 1
	v_permlane32_swap_b32_e32 v176, v180
	v_permlane32_swap_b32_e32 v177, v181
	v_permlane32_swap_b32_e32 v178, v182
	v_permlane32_swap_b32_e32 v179, v183
	s_nop 0
	global_store_dwordx4 v[218:219], v[176:179], off offset:512
	global_store_dwordx4 v[218:219], v[180:183], off offset:576
	s_cbranch_execnz .LBB0_1352
	s_branch .LBB0_1351
